# all remaining packed f32 VALU ops split into scalar pairs (bit-identical)
# baseline (speedup 1.0000x reference)
.LBB0_24:
	v_lshl_add_u64 v[12:13], v[6:7], 0, s[10:11]
	v_add_co_u32_e32 v80, vcc, s12, v12
	global_load_dword v78, v[12:13], off
	s_nop 0
	v_addc_co_u32_e32 v81, vcc, 0, v13, vcc
	v_add_co_u32_e32 v82, vcc, s37, v12
	v_mov_b32_e32 v74, s68
	s_nop 0
	v_addc_co_u32_e32 v83, vcc, 0, v13, vcc
	v_add_co_u32_e32 v84, vcc, s40, v12
	ds_read_b128 v[14:17], v74
	ds_read_b128 v[18:21], v74 offset:16
	v_addc_co_u32_e32 v85, vcc, 0, v13, vcc
	v_add_co_u32_e32 v86, vcc, s41, v12
	ds_read_b128 v[22:25], v74 offset:4096
	ds_read_b128 v[26:29], v74 offset:4112
	ds_read_b128 v[30:33], v74 offset:8192
	ds_read_b128 v[34:37], v74 offset:8208
	ds_read_b128 v[38:41], v74 offset:12288
	ds_read_b128 v[42:45], v74 offset:12304
	v_addc_co_u32_e32 v87, vcc, 0, v13, vcc
	v_add_co_u32_e32 v88, vcc, s42, v12
	ds_read_b128 v[46:49], v74 offset:32
	ds_read_b128 v[50:53], v74 offset:48
	ds_read_b128 v[54:57], v74 offset:4128
	ds_read_b128 v[58:61], v74 offset:4144
	ds_read_b128 v[62:65], v74 offset:8224
	ds_read_b128 v[66:69], v74 offset:8240
	ds_read_b128 v[70:73], v74 offset:12320
	ds_read_b128 v[74:77], v74 offset:12336
	v_addc_co_u32_e32 v89, vcc, 0, v13, vcc
	v_add_co_u32_e32 v90, vcc, s43, v12
	s_waitcnt lgkmcnt(14)
	v_mov_b32_e32 v108, v14
	v_addc_co_u32_e32 v91, vcc, 0, v13, vcc
	v_add_co_u32_e32 v92, vcc, s44, v12
	s_waitcnt lgkmcnt(13)
	v_mov_b32_e32 v109, v22
	v_addc_co_u32_e32 v93, vcc, 0, v13, vcc
	v_add_co_u32_e32 v94, vcc, s45, v12
	v_mov_b32_e32 v22, v15
	s_nop 0
	v_addc_co_u32_e32 v95, vcc, 0, v13, vcc
	v_add_co_u32_e32 v96, vcc, s46, v12
	v_mov_b32_e32 v14, v16
	s_nop 0
	v_addc_co_u32_e32 v97, vcc, 0, v13, vcc
	v_add_co_u32_e32 v98, vcc, s47, v12
	v_mov_b32_e32 v15, v24
	s_nop 0
	v_addc_co_u32_e32 v99, vcc, 0, v13, vcc
	v_add_co_u32_e32 v100, vcc, s48, v12
	v_mov_b32_e32 v24, v17
	s_nop 0
	v_addc_co_u32_e32 v101, vcc, 0, v13, vcc
	v_add_co_u32_e32 v102, vcc, s49, v12
	s_waitcnt lgkmcnt(11)
	v_mov_b32_e32 v16, v30
	v_addc_co_u32_e32 v103, vcc, 0, v13, vcc
	v_add_co_u32_e32 v104, vcc, s50, v12
	s_waitcnt lgkmcnt(9)
	v_mov_b32_e32 v17, v38
	v_addc_co_u32_e32 v105, vcc, 0, v13, vcc
	v_add_co_u32_e32 v106, vcc, s51, v12
	v_mov_b32_e32 v38, v31
	s_nop 0
	v_addc_co_u32_e32 v107, vcc, 0, v13, vcc
	v_add_co_u32_e32 v12, vcc, s64, v12
	v_mov_b32_e32 v30, v32
	s_nop 0
	v_addc_co_u32_e32 v13, vcc, 0, v13, vcc
	global_load_dword v80, v[80:81], off
	s_nop 0
	global_load_dword v82, v[82:83], off
	s_nop 0
	global_load_dword v84, v[84:85], off
	s_nop 0
	global_load_dword v86, v[86:87], off
	s_nop 0
	global_load_dword v88, v[88:89], off
	s_nop 0
	global_load_dword v90, v[90:91], off
	s_nop 0
	global_load_dword v92, v[92:93], off
	s_nop 0
	global_load_dword v94, v[94:95], off
	s_nop 0
	global_load_dword v96, v[96:97], off
	s_nop 0
	global_load_dword v98, v[98:99], off
	s_nop 0
	global_load_dword v100, v[100:101], off
	s_nop 0
	global_load_dword v102, v[102:103], off
	s_nop 0
	global_load_dword v104, v[104:105], off
	s_nop 0
	global_load_dword v106, v[106:107], off
	s_nop 0
	global_load_dword v12, v[12:13], off
	v_mov_b32_e32 v31, v40
	v_mov_b32_e32 v40, v33
	v_mov_b32_e32 v32, v18
	v_mov_b32_e32 v33, v26
	v_mov_b32_e32 v26, v19
	v_mov_b32_e32 v18, v20
	s_waitcnt vmcnt(15)
	v_fma_f32 v8, v78, v108, v8
	v_fma_f32 v9, v78, v109, v9
	v_fma_f32 v10, v78, v16, v10
	v_fma_f32 v11, v78, v17, v11
	v_mov_b32_e32 v19, v28
	v_mov_b32_e32 v28, v21
	v_mov_b32_e32 v20, v34
	s_waitcnt lgkmcnt(8)
	v_mov_b32_e32 v21, v42
	v_mov_b32_e32 v42, v35
	v_mov_b32_e32 v34, v36
	v_mov_b32_e32 v35, v44
	v_mov_b32_e32 v44, v37
	s_waitcnt lgkmcnt(7)
	v_mov_b32_e32 v36, v46
	s_waitcnt lgkmcnt(5)
	v_mov_b32_e32 v37, v54
	v_mov_b32_e32 v54, v47
	v_mov_b32_e32 v46, v48
	v_mov_b32_e32 v47, v56
	v_mov_b32_e32 v56, v49
	s_waitcnt lgkmcnt(3)
	v_mov_b32_e32 v48, v62
	s_waitcnt lgkmcnt(1)
	v_mov_b32_e32 v49, v70
	v_mov_b32_e32 v70, v63
	v_mov_b32_e32 v62, v64
	v_mov_b32_e32 v63, v72
	v_mov_b32_e32 v72, v65
	v_mov_b32_e32 v64, v50
	v_mov_b32_e32 v65, v58
	v_mov_b32_e32 v58, v51
	v_mov_b32_e32 v50, v52
	v_mov_b32_e32 v51, v60
	v_mov_b32_e32 v60, v53
	v_mov_b32_e32 v52, v66
	s_waitcnt lgkmcnt(0)
	v_mov_b32_e32 v53, v74
	v_mov_b32_e32 v74, v67
	s_add_u32 s10, s10, 0x30000
	v_mov_b32_e32 v66, v68
	v_mov_b32_e32 v67, v76
	s_addc_u32 s11, s11, 0
	s_add_i32 s68, s68, 64
	v_mov_b32_e32 v76, v69
	s_cmp_eq_u32 s10, 0x180000
	s_waitcnt vmcnt(14)
	v_fma_f32 v8, v80, v22, v8
	v_fma_f32 v9, v80, v23, v9
	v_fma_f32 v10, v80, v38, v10
	v_fma_f32 v11, v80, v39, v11
	s_waitcnt vmcnt(13)
	v_fma_f32 v8, v82, v14, v8
	v_fma_f32 v9, v82, v15, v9
	v_fma_f32 v10, v82, v30, v10
	v_fma_f32 v11, v82, v31, v11
	s_waitcnt vmcnt(12)
	v_fma_f32 v8, v84, v24, v8
	v_fma_f32 v9, v84, v25, v9
	v_fma_f32 v10, v84, v40, v10
	v_fma_f32 v11, v84, v41, v11
	s_waitcnt vmcnt(11)
	v_fma_f32 v8, v86, v32, v8
	v_fma_f32 v9, v86, v33, v9
	v_fma_f32 v10, v86, v20, v10
	v_fma_f32 v11, v86, v21, v11
	s_waitcnt vmcnt(10)
	v_fma_f32 v8, v88, v26, v8
	v_fma_f32 v9, v88, v27, v9
	v_fma_f32 v10, v88, v42, v10
	v_fma_f32 v11, v88, v43, v11
	s_waitcnt vmcnt(9)
	v_fma_f32 v8, v90, v18, v8
	v_fma_f32 v9, v90, v19, v9
	v_fma_f32 v10, v90, v34, v10
	v_fma_f32 v11, v90, v35, v11
	s_waitcnt vmcnt(8)
	v_fma_f32 v8, v92, v28, v8
	v_fma_f32 v9, v92, v29, v9
	v_fma_f32 v10, v92, v44, v10
	v_fma_f32 v11, v92, v45, v11
	s_waitcnt vmcnt(7)
	v_fma_f32 v8, v94, v36, v8
	v_fma_f32 v9, v94, v37, v9
	v_fma_f32 v10, v94, v48, v10
	v_fma_f32 v11, v94, v49, v11
	s_waitcnt vmcnt(6)
	v_fma_f32 v8, v96, v54, v8
	v_fma_f32 v9, v96, v55, v9
	v_fma_f32 v10, v96, v70, v10
	v_fma_f32 v11, v96, v71, v11
	s_waitcnt vmcnt(5)
	v_fma_f32 v8, v98, v46, v8
	v_fma_f32 v9, v98, v47, v9
	v_fma_f32 v10, v98, v62, v10
	v_fma_f32 v11, v98, v63, v11
	s_waitcnt vmcnt(4)
	v_fma_f32 v8, v100, v56, v8
	v_fma_f32 v9, v100, v57, v9
	v_fma_f32 v10, v100, v72, v10
	v_fma_f32 v11, v100, v73, v11
	s_waitcnt vmcnt(3)
	v_fma_f32 v8, v102, v64, v8
	v_fma_f32 v9, v102, v65, v9
	v_fma_f32 v10, v102, v52, v10
	v_fma_f32 v11, v102, v53, v11
	s_waitcnt vmcnt(2)
	v_fma_f32 v8, v104, v58, v8
	v_fma_f32 v9, v104, v59, v9
	v_fma_f32 v10, v104, v74, v10
	v_fma_f32 v11, v104, v75, v11
	s_waitcnt vmcnt(1)
	v_fma_f32 v8, v106, v50, v8
	v_fma_f32 v9, v106, v51, v9
	v_fma_f32 v10, v106, v66, v10
	v_fma_f32 v11, v106, v67, v11
	s_waitcnt vmcnt(0)
	v_fma_f32 v8, v12, v60, v8
	v_fma_f32 v9, v12, v61, v9
	v_fma_f32 v10, v12, v76, v10
	v_fma_f32 v11, v12, v77, v11
	s_cbranch_scc0 .LBB0_24
	v_lshl_add_u32 v6, v5, 2, s3
	v_cmp_gt_i32_e32 vcc, s65, v4
	ds_write2st64_b32 v6, v8, v9 offset0:64 offset1:65
	ds_write2st64_b32 v6, v10, v11 offset0:66 offset1:67
	s_waitcnt lgkmcnt(0)
	s_barrier
	s_and_saveexec_b64 s[10:11], vcc
	s_cbranch_execz .LBB0_27
	s_mul_i32 s9, s0, 0xc00
	s_add_i32 s9, s9, s8
	v_or_b32_e32 v6, s9, v5
	v_ashrrev_i32_e32 v7, 31, v6
	v_lshl_add_u64 v[6:7], v[6:7], 2, s[82:83]
	global_load_dword v16, v[6:7], off
	v_and_b32_e32 v6, 0x3fffffc0, v4
	v_lshrrev_b32_e32 v7, 6, v4
	v_lshlrev_b32_e32 v6, 2, v6
	v_lshl_add_u32 v7, s0, 2, v7
	v_add3_u32 v2, 0, v6, v2
	v_mul_lo_u32 v14, v7, s66
	ds_read2st64_b32 v[6:7], v2 offset0:64 offset1:68
	ds_read2st64_b32 v[8:9], v2 offset0:72 offset1:76
	ds_read2st64_b32 v[10:11], v2 offset0:80 offset1:84
	ds_read2st64_b32 v[12:13], v2 offset0:88 offset1:92
	v_add_u32_e32 v2, s8, v14
	v_or_b32_e32 v14, v2, v5
	v_ashrrev_i32_e32 v15, 31, v14
	s_waitcnt vmcnt(0) lgkmcnt(3)
	v_add_f32_e32 v2, v16, v6
	v_add_f32_e32 v2, v2, v7
	s_waitcnt lgkmcnt(2)
	v_add_f32_e32 v2, v2, v8
	v_add_f32_e32 v2, v2, v9
	s_waitcnt lgkmcnt(1)
	v_add_f32_e32 v2, v2, v10
	v_add_f32_e32 v2, v2, v11
	s_waitcnt lgkmcnt(0)
	v_add_f32_e32 v2, v2, v12
	v_add_f32_e32 v2, v2, v13
	v_lshl_add_u64 v[6:7], v[14:15], 2, s[34:35]
	global_store_dword v[6:7], v2, off

.LBB0_40:
	global_load_dwordx4 v[48:51], v[36:37], off offset:-2048 nt
	global_load_dwordx4 v[14:17], v[36:37], off offset:-1024 nt
	s_waitcnt lgkmcnt(0)
	global_load_dwordx4 v[6:9], v[36:37], off nt
	global_load_dwordx4 v[2:5], v[36:37], off offset:1024 nt
	s_add_i32 s36, s82, s27
	s_cmp_lt_i32 s36, 0x8000
	s_cselect_b32 s38, s36, s27
	s_ashr_i32 s37, s27, 31
	s_lshr_b32 s37, s37, 19
	s_add_i32 s37, s27, s37
	s_ashr_i32 s37, s37, 13
	s_mul_i32 s40, s37, 0xc00
	s_ashr_i32 s39, s38, 31
	s_ashr_i32 s41, s40, 31
	s_lshl_b64 s[38:39], s[38:39], 12
	s_lshl_b64 s[40:41], s[40:41], 2
	s_add_u32 s40, s34, s40
	s_addc_u32 s41, s35, s41
	v_lshl_add_u64 v[64:65], v[30:31], 2, s[40:41]
	v_add_co_u32_e32 v10, vcc, s3, v64
	v_lshl_add_u64 v[66:67], s[12:13], 0, v[38:39]
	s_nop 0
	v_addc_co_u32_e32 v11, vcc, 0, v65, vcc
	global_load_dwordx4 v[52:55], v[10:11], off
	global_load_dwordx4 v[56:59], v[34:35], off
	global_load_dwordx4 v[60:63], v[64:65], off
	s_cmpk_gt_i32 s36, 0x7fff
	s_waitcnt vmcnt(6)
	v_mov_b32_e32 v12, v49
	s_waitcnt vmcnt(5)
	v_mov_b32_e32 v13, v15
	v_mov_b32_e32 v10, v48
	v_mov_b32_e32 v11, v14
	s_waitcnt vmcnt(4)
	v_mov_b32_e32 v24, v7
	s_waitcnt vmcnt(3)
	v_mov_b32_e32 v25, v3
	v_mul_f32_e32 v12, v12, v12
	v_mul_f32_e32 v13, v13, v13
	v_mov_b32_e32 v18, v50
	v_mov_b32_e32 v19, v16
	v_mov_b32_e32 v22, v6
	v_mov_b32_e32 v23, v2
	v_mul_f32_e32 v24, v24, v24
	v_mul_f32_e32 v25, v25, v25
	v_fma_f32 v10, v10, v10, v12
	v_fma_f32 v11, v11, v11, v13
	v_mov_b32_e32 v20, v51
	v_mov_b32_e32 v21, v17
	v_mov_b32_e32 v26, v8
	v_mov_b32_e32 v27, v4
	v_fma_f32 v12, v22, v22, v24
	v_fma_f32 v13, v23, v23, v25
	v_fma_f32 v10, v18, v18, v10
	v_fma_f32 v11, v19, v19, v11
	v_mov_b32_e32 v28, v9
	v_mov_b32_e32 v29, v5
	v_fma_f32 v12, v26, v26, v12
	v_fma_f32 v13, v27, v27, v13
	v_fma_f32 v10, v20, v20, v10
	v_fma_f32 v11, v21, v21, v11
	v_fma_f32 v12, v28, v28, v12
	v_fma_f32 v13, v29, v29, v13
	v_add_f32_e32 v10, v10, v11
	v_add_f32_e32 v10, v10, v12
	v_add_f32_e32 v10, v10, v13
	ds_bpermute_b32 v11, v40, v10
	s_waitcnt vmcnt(2)
	v_add_f32_e32 v52, 1.0, v52
	v_add_f32_e32 v53, 1.0, v53
	v_add_f32_e32 v54, 1.0, v54
	v_add_f32_e32 v55, 1.0, v55
	s_waitcnt lgkmcnt(0)
	v_add_f32_e32 v10, v10, v11
	ds_bpermute_b32 v11, v41, v10
	s_waitcnt lgkmcnt(0)
	v_add_f32_e32 v10, v10, v11
	ds_bpermute_b32 v11, v42, v10
	s_waitcnt lgkmcnt(0)
	v_add_f32_e32 v10, v10, v11
	ds_bpermute_b32 v11, v43, v10
	s_waitcnt lgkmcnt(0)
	v_add_f32_e32 v12, v10, v11
	ds_bpermute_b32 v13, v44, v12
	v_lshl_add_u64 v[10:11], v[32:33], 0, s[38:39]
	s_waitcnt lgkmcnt(0)
	v_add_f32_e32 v47, v12, v13
	ds_bpermute_b32 v68, v45, v47
	global_load_dwordx4 v[26:29], v[10:11], off nt
	global_load_dwordx4 v[22:25], v[10:11], off offset:1024 nt
	global_load_dwordx4 v[18:21], v[10:11], off offset:2048 nt
	s_nop 0
	global_load_dwordx4 v[10:13], v[10:11], off offset:3072 nt
	s_waitcnt lgkmcnt(0)
	v_add_f32_e32 v47, v47, v68
	v_fmamk_f32 v47, v47, 0x3a800000, v46
	v_mul_f32_e32 v68, 0x4b800000, v47
	v_cmp_gt_f32_e32 vcc, s1, v47
	s_nop 1
	v_cndmask_b32_e32 v47, v47, v68, vcc
	v_rsq_f32_e32 v47, v47
	v_lshl_add_u64 v[68:69], v[64:65], 0, s[28:29]
	v_mul_f32_e32 v70, 0x45800000, v47
	v_cndmask_b32_e32 v70, v47, v70, vcc
	v_mul_f32_e32 v48, v48, v70
	v_mul_f32_e32 v49, v49, v70
	v_mul_f32_e32 v50, v50, v70
	v_mul_f32_e32 v51, v51, v70
	s_waitcnt vmcnt(5)
	v_mul_f32_e32 v48, v56, v48
	v_mul_f32_e32 v49, v57, v49
	v_mul_f32_e32 v50, v58, v50
	v_mul_f32_e32 v51, v59, v51
	s_waitcnt vmcnt(4)
	v_fma_f32 v48, v48, v52, v60
	v_fma_f32 v49, v49, v53, v61
	v_fma_f32 v50, v50, v54, v62
	v_fma_f32 v51, v51, v55, v63
	v_cvt_pk_bf16_f32 v48, v48, v49
	v_cvt_pk_bf16_f32 v49, v50, v51
	global_store_dwordx2 v[66:67], v[48:49], off nt
	global_load_dwordx4 v[48:51], v[34:35], off offset:1024
	s_nop 0
	global_load_dwordx4 v[52:55], v[68:69], off offset:1024
	global_load_dwordx4 v[56:59], v[64:65], off offset:1024
	v_mul_f32_e32 v14, v14, v70
	v_mul_f32_e32 v15, v15, v70
	v_mul_f32_e32 v16, v16, v70
	v_mul_f32_e32 v17, v17, v70
	v_mul_f32_e32 v6, v6, v70
	v_mul_f32_e32 v7, v7, v70
	v_mul_f32_e32 v8, v8, v70
	v_mul_f32_e32 v9, v9, v70
	v_mul_f32_e32 v2, v2, v70
	v_mul_f32_e32 v3, v3, v70
	v_mul_f32_e32 v4, v4, v70
	v_mul_f32_e32 v5, v5, v70
	s_waitcnt vmcnt(2)
	v_mul_f32_e32 v14, v14, v48
	v_mul_f32_e32 v15, v15, v49
	s_waitcnt vmcnt(1)
	v_add_f32_e32 v48, 1.0, v52
	v_add_f32_e32 v49, 1.0, v53
	v_mul_f32_e32 v16, v16, v50
	v_mul_f32_e32 v17, v17, v51
	v_add_f32_e32 v50, 1.0, v54
	v_add_f32_e32 v51, 1.0, v55
	s_waitcnt vmcnt(0)
	v_fma_f32 v14, v14, v48, v56
	v_fma_f32 v15, v15, v49, v57
	v_fma_f32 v16, v16, v50, v58
	v_fma_f32 v17, v17, v51, v59
	v_cvt_pk_bf16_f32 v14, v14, v15
	v_cvt_pk_bf16_f32 v15, v16, v17
	global_store_dwordx2 v[66:67], v[14:15], off offset:512 nt
	global_load_dwordx4 v[14:17], v[34:35], off offset:2048
	s_nop 0
	global_load_dwordx4 v[48:51], v[68:69], off offset:2048
	global_load_dwordx4 v[52:55], v[64:65], off offset:2048
	s_waitcnt vmcnt(2)
	v_mul_f32_e32 v6, v6, v14
	v_mul_f32_e32 v7, v7, v15
	s_waitcnt vmcnt(1)
	v_add_f32_e32 v14, 1.0, v48
	v_add_f32_e32 v15, 1.0, v49
	v_mul_f32_e32 v8, v8, v16
	v_mul_f32_e32 v9, v9, v17
	v_add_f32_e32 v16, 1.0, v50
	v_add_f32_e32 v17, 1.0, v51
	s_waitcnt vmcnt(0)
	v_fma_f32 v6, v6, v14, v52
	v_fma_f32 v7, v7, v15, v53
	v_fma_f32 v8, v8, v16, v54
	v_fma_f32 v9, v9, v17, v55
	v_cvt_pk_bf16_f32 v6, v6, v7
	v_cvt_pk_bf16_f32 v7, v8, v9
	global_store_dwordx2 v[66:67], v[6:7], off offset:1024 nt
	global_load_dwordx4 v[14:17], v[34:35], off offset:3072
	global_load_dwordx4 v[48:51], v[68:69], off offset:3072
	global_load_dwordx4 v[52:55], v[64:65], off offset:3072
	v_mul_f32_e32 v6, v27, v27
	v_mul_f32_e32 v7, v23, v23
	v_mul_f32_e32 v8, v19, v19
	v_fmac_f32_e32 v6, v26, v26
	v_fmac_f32_e32 v7, v22, v22
	v_mul_f32_e32 v9, v11, v11
	v_fmac_f32_e32 v8, v18, v18
	v_fmac_f32_e32 v6, v28, v28
	v_fmac_f32_e32 v7, v24, v24
	v_fmac_f32_e32 v9, v10, v10
	v_fmac_f32_e32 v8, v20, v20
	v_fmac_f32_e32 v6, v29, v29
	v_fmac_f32_e32 v7, v25, v25
	v_fmac_f32_e32 v9, v12, v12
	v_fmac_f32_e32 v8, v21, v21
	v_add_f32_e32 v6, v6, v7
	v_fmac_f32_e32 v9, v13, v13
	v_add_f32_e32 v6, v6, v8
	v_add_f32_e32 v6, v6, v9
	ds_bpermute_b32 v7, v40, v6
	s_waitcnt lgkmcnt(0)
	v_add_f32_e32 v6, v6, v7
	ds_bpermute_b32 v7, v41, v6
	s_waitcnt lgkmcnt(0)
	v_add_f32_e32 v6, v6, v7
	ds_bpermute_b32 v7, v42, v6
	s_waitcnt lgkmcnt(0)
	v_add_f32_e32 v6, v6, v7
	ds_bpermute_b32 v7, v43, v6
	s_waitcnt lgkmcnt(0)
	v_add_f32_e32 v6, v6, v7
	ds_bpermute_b32 v7, v44, v6
	s_waitcnt lgkmcnt(0)
	v_add_f32_e32 v6, v6, v7
	ds_bpermute_b32 v7, v45, v6
	s_waitcnt vmcnt(2)
	v_mul_f32_e32 v2, v2, v14
	v_mul_f32_e32 v3, v3, v15
	s_waitcnt vmcnt(1)
	v_add_f32_e32 v8, 1.0, v48
	v_add_f32_e32 v9, 1.0, v49
	v_mul_f32_e32 v4, v4, v16
	v_mul_f32_e32 v5, v5, v17
	v_add_f32_e32 v14, 1.0, v50
	v_add_f32_e32 v15, 1.0, v51
	s_waitcnt vmcnt(0)
	v_fma_f32 v2, v2, v8, v52
	v_fma_f32 v3, v3, v9, v53
	v_fma_f32 v4, v4, v14, v54
	v_fma_f32 v5, v5, v15, v55
	v_cvt_pk_bf16_f32 v2, v2, v3
	v_cvt_pk_bf16_f32 v3, v4, v5
	global_store_dwordx2 v[66:67], v[2:3], off offset:1536 nt
	s_cbranch_scc1 .LBB0_39
	s_ashr_i32 s37, s36, 31
	s_lshr_b32 s37, s37, 19
	s_add_i32 s36, s36, s37
	s_ashr_i32 s36, s36, 13
	s_mulk_i32 s36, 0xc00
	s_ashr_i32 s37, s36, 31
	s_lshl_b64 s[36:37], s[36:37], 2
	s_add_u32 s36, s34, s36
	s_addc_u32 s37, s35, s37
	v_lshl_add_u64 v[52:53], v[30:31], 2, s[36:37]
	v_add_co_u32_e32 v8, vcc, s3, v52
	global_load_dwordx4 v[2:5], v[34:35], off
	s_nop 0
	v_addc_co_u32_e32 v9, vcc, 0, v53, vcc
	global_load_dwordx4 v[14:17], v[8:9], off
	global_load_dwordx4 v[48:51], v[52:53], off
	s_waitcnt lgkmcnt(0)
	v_add_f32_e32 v6, v6, v7
	v_fmamk_f32 v6, v6, 0x3a800000, v46
	v_mul_f32_e32 v7, 0x4b800000, v6
	v_cmp_gt_f32_e32 vcc, s1, v6
	v_lshl_add_u64 v[54:55], s[8:9], 0, v[38:39]
	v_lshl_add_u64 v[58:59], v[52:53], 0, s[28:29]
	v_cndmask_b32_e32 v6, v6, v7, vcc
	v_rsq_f32_e32 v6, v6
	s_nop 0
	v_mul_f32_e32 v7, 0x45800000, v6
	v_cndmask_b32_e32 v56, v6, v7, vcc
	v_mul_f32_e32 v6, v26, v56
	v_mul_f32_e32 v7, v27, v56
	v_mul_f32_e32 v8, v28, v56
	v_mul_f32_e32 v9, v29, v56
	v_mul_f32_e32 v22, v22, v56
	v_mul_f32_e32 v23, v23, v56
	v_mul_f32_e32 v24, v24, v56
	v_mul_f32_e32 v25, v25, v56
	v_mul_f32_e32 v18, v18, v56
	v_mul_f32_e32 v19, v19, v56
	v_mul_f32_e32 v20, v20, v56
	v_mul_f32_e32 v21, v21, v56
	v_mul_f32_e32 v10, v10, v56
	v_mul_f32_e32 v11, v11, v56
	v_mul_f32_e32 v12, v12, v56
	v_mul_f32_e32 v13, v13, v56
	s_waitcnt vmcnt(2)
	v_mul_f32_e32 v2, v6, v2
	v_mul_f32_e32 v3, v7, v3
	v_mul_f32_e32 v4, v8, v4
	v_mul_f32_e32 v5, v9, v5
	s_waitcnt vmcnt(1)
	v_add_f32_e32 v6, 1.0, v14
	v_add_f32_e32 v7, 1.0, v15
	v_add_f32_e32 v8, 1.0, v16
	v_add_f32_e32 v9, 1.0, v17
	s_waitcnt vmcnt(0)
	v_fma_f32 v2, v2, v6, v48
	v_fma_f32 v3, v3, v7, v49
	v_fma_f32 v4, v4, v8, v50
	v_fma_f32 v5, v5, v9, v51
	v_cvt_pk_bf16_f32 v2, v2, v3
	v_cvt_pk_bf16_f32 v3, v4, v5
	global_store_dwordx2 v[54:55], v[2:3], off nt
	global_load_dwordx4 v[2:5], v[34:35], off offset:1024
	s_nop 0
	global_load_dwordx4 v[6:9], v[58:59], off offset:1024
	global_load_dwordx4 v[14:17], v[52:53], off offset:1024
	s_waitcnt vmcnt(2)
	v_mul_f32_e32 v2, v22, v2
	v_mul_f32_e32 v3, v23, v3
	s_waitcnt vmcnt(1)
	v_add_f32_e32 v6, 1.0, v6
	v_add_f32_e32 v7, 1.0, v7
	v_mul_f32_e32 v4, v24, v4
	v_mul_f32_e32 v5, v25, v5
	v_add_f32_e32 v8, 1.0, v8
	v_add_f32_e32 v9, 1.0, v9
	s_waitcnt vmcnt(0)
	v_fma_f32 v2, v2, v6, v14
	v_fma_f32 v3, v3, v7, v15
	v_fma_f32 v4, v4, v8, v16
	v_fma_f32 v5, v5, v9, v17
	v_cvt_pk_bf16_f32 v2, v2, v3
	v_cvt_pk_bf16_f32 v3, v4, v5
	global_store_dwordx2 v[54:55], v[2:3], off offset:512 nt
	global_load_dwordx4 v[2:5], v[34:35], off offset:2048
	s_nop 0
	global_load_dwordx4 v[6:9], v[58:59], off offset:2048
	global_load_dwordx4 v[14:17], v[52:53], off offset:2048
	s_waitcnt vmcnt(2)
	v_mul_f32_e32 v2, v18, v2
	v_mul_f32_e32 v3, v19, v3
	s_waitcnt vmcnt(1)
	v_add_f32_e32 v6, 1.0, v6
	v_add_f32_e32 v7, 1.0, v7
	v_mul_f32_e32 v4, v20, v4
	v_mul_f32_e32 v5, v21, v5
	v_add_f32_e32 v8, 1.0, v8
	v_add_f32_e32 v9, 1.0, v9
	s_waitcnt vmcnt(0)
	v_fma_f32 v2, v2, v6, v14
	v_fma_f32 v3, v3, v7, v15
	v_fma_f32 v4, v4, v8, v16
	v_fma_f32 v5, v5, v9, v17
	v_cvt_pk_bf16_f32 v2, v2, v3
	v_cvt_pk_bf16_f32 v3, v4, v5
	global_store_dwordx2 v[54:55], v[2:3], off offset:1024 nt
	global_load_dwordx4 v[2:5], v[34:35], off offset:3072
	s_nop 0
	global_load_dwordx4 v[6:9], v[58:59], off offset:3072
	global_load_dwordx4 v[14:17], v[52:53], off offset:3072
	s_waitcnt vmcnt(2)
	v_mul_f32_e32 v2, v10, v2
	v_mul_f32_e32 v3, v11, v3
	s_waitcnt vmcnt(1)
	v_add_f32_e32 v6, 1.0, v6
	v_add_f32_e32 v7, 1.0, v7
	v_mul_f32_e32 v4, v12, v4
	v_mul_f32_e32 v5, v13, v5
	v_add_f32_e32 v8, 1.0, v8
	v_add_f32_e32 v9, 1.0, v9
	s_waitcnt vmcnt(0)
	v_fma_f32 v2, v2, v6, v14
	v_fma_f32 v3, v3, v7, v15
	v_fma_f32 v4, v4, v8, v16
	v_fma_f32 v5, v5, v9, v17
	v_cvt_pk_bf16_f32 v2, v2, v3
	v_cvt_pk_bf16_f32 v3, v4, v5
	global_store_dwordx2 v[54:55], v[2:3], off offset:1536 nt
	s_branch .LBB0_39

.LBB0_227:
	s_add_u32 s0, s16, s6
	s_addc_u32 s1, s17, s7
	global_load_dwordx4 v[4:7], v3, s[0:1]
	global_load_dwordx4 v[8:11], v3, s[0:1] offset:16
	s_add_u32 s0, s18, s6
	s_addc_u32 s1, s19, s7
	global_load_dwordx4 v[12:15], v3, s[0:1]
	global_load_dwordx4 v[16:19], v3, s[0:1] offset:16
	s_add_u32 s0, s20, s6
	s_addc_u32 s1, s21, s7
	global_load_dwordx4 v[20:23], v3, s[0:1]
	global_load_dwordx4 v[24:27], v3, s[0:1] offset:16
	s_add_u32 s0, s22, s6
	s_addc_u32 s1, s23, s7
	global_load_dwordx4 v[28:31], v3, s[0:1]
	global_load_dwordx4 v[32:35], v3, s[0:1] offset:16
	s_add_u32 s6, s6, 32
	s_addc_u32 s7, s7, 0
	s_cmpk_eq_i32 s6, 0x100
	s_waitcnt vmcnt(7)
	v_mov_b32_e32 v36, v4
	v_mov_b32_e32 v4, v6
	s_waitcnt vmcnt(6)
	v_mov_b32_e32 v6, v8
	v_mov_b32_e32 v8, v10
	s_waitcnt vmcnt(5)
	v_mov_b32_e32 v10, v12
	v_mov_b32_e32 v12, v14
	s_waitcnt vmcnt(3)
	v_mov_b32_e32 v37, v20
	v_mov_b32_e32 v20, v5
	v_mov_b32_e32 v5, v22
	v_mov_b32_e32 v22, v7
	s_waitcnt vmcnt(2)
	v_mov_b32_e32 v7, v24
	v_mov_b32_e32 v24, v9
	v_mov_b32_e32 v9, v26
	v_mov_b32_e32 v26, v11
	s_waitcnt vmcnt(1)
	v_mov_b32_e32 v11, v28
	v_mov_b32_e32 v28, v13
	v_fma_f32 v0, v36, v10, v0
	v_fma_f32 v1, v37, v11, v1
	v_mov_b32_e32 v13, v30
	v_fma_f32 v0, v20, v28, v0
	v_fma_f32 v1, v21, v29, v1
	v_mov_b32_e32 v30, v15
	v_fma_f32 v0, v4, v12, v0
	v_fma_f32 v1, v5, v13, v1
	v_mov_b32_e32 v14, v16
	s_waitcnt vmcnt(0)
	v_mov_b32_e32 v15, v32
	v_fma_f32 v0, v22, v30, v0
	v_fma_f32 v1, v23, v31, v1
	v_mov_b32_e32 v32, v17
	v_fma_f32 v0, v6, v14, v0
	v_fma_f32 v1, v7, v15, v1
	v_mov_b32_e32 v16, v18
	v_mov_b32_e32 v17, v34
	v_fma_f32 v0, v24, v32, v0
	v_fma_f32 v1, v25, v33, v1
	v_mov_b32_e32 v34, v19
	v_fma_f32 v0, v8, v16, v0
	v_fma_f32 v1, v9, v17, v1
	s_nop 0
	v_fma_f32 v0, v26, v34, v0
	v_fma_f32 v1, v27, v35, v1
	s_cbranch_scc0 .LBB0_227
	v_readlane_b32 s15, v255, 0
	v_readlane_b32 s0, v255, 1
	s_lshr_b32 s1, s15, 7
	s_bfe_u32 s16, s15, 0x10006
	v_add_u32_e32 v3, s0, v2
	s_lshl_b32 s0, s1, 14
	s_add_i32 s4, s0, 0
	s_add_u32 s42, s34, 0x20000
	s_addc_u32 s43, s35, 0
	s_lshl_b32 s5, s1, 5
	s_lshl_b32 s0, s16, 6
	v_and_b32_e32 v9, 63, v2
	v_writelane_b32 v255, s1, 30
	s_cmpk_lt_u32 s15, 0x80
	v_writelane_b32 v255, s0, 31
	s_cselect_b64 s[48:49], -1, 0
	s_add_i32 s0, 0, 0x1bc00
	v_lshlrev_b32_e32 v96, 3, v9
	v_lshlrev_b32_e32 v5, 1, v2
	v_lshrrev_b32_e32 v4, 1, v2
	v_add_u32_e32 v12, s0, v96
	v_readlane_b32 s0, v255, 2
	v_and_b32_e32 v6, 8, v5
	v_and_b32_e32 v4, 4, v4
	v_and_b32_e32 v11, 19, v2
	s_lshl_b32 s12, s0, 9
	s_add_i32 s0, 0, 0x11c00
	s_add_i32 s13, 0, 0x1c040
	v_or3_b32 v11, v6, v11, v4
	v_and_b32_e32 v6, 15, v2
	s_cmpk_gt_u32 s15, 0xff
	v_lshrrev_b32_e32 v7, 2, v2
	v_and_b32_e32 v8, 31, v2
	v_bfe_u32 v10, v2, 5, 1
	v_lshlrev_b32_e32 v4, 3, v6
	v_lshlrev_b32_e32 v6, 4, v6
	s_cselect_b64 s[50:51], -1, 0
	s_cmpk_lt_u32 s15, 0x100
	v_lshlrev_b32_e32 v2, 3, v2
	v_cmp_gt_u32_e64 s[18:19], 2, v9
	v_mul_f32_e32 v0, 0x3fb8aa3b, v0
	v_mul_f32_e32 v1, 0x3fb8aa3b, v1
	v_ashrrev_i32_e32 v140, 4, v3
	v_add_u32_e32 v13, s0, v6
	s_cselect_b64 s[28:29], -1, 0
	s_movk_i32 s0, 0x110
	v_and_b32_e32 v2, 24, v2
	v_writelane_b32 v255, s18, 32
	v_exp_f32_e32 v0, v0
	v_exp_f32_e32 v1, v1
	v_and_or_b32 v189, v5, 32, v2
	v_mul_lo_u32 v5, v140, s0
	s_and_b64 s[0:1], s[28:29], exec
	v_writelane_b32 v255, s19, 33
	v_cmp_gt_u32_e64 s[18:19], 4, v9
	s_cselect_b32 s0, 0, 32
	s_and_b32 s1, 64, s15
	v_writelane_b32 v255, s18, 34
	s_cmp_eq_u32 s16, 0
	s_cselect_b64 s[52:53], -1, 0
	v_writelane_b32 v255, s19, 35
	v_cmp_gt_u32_e64 s[18:19], 8, v9
	s_cmp_lg_u32 s1, 0
	v_sub_f32_e32 v0, v0, v1
	v_writelane_b32 v255, s18, 36
	v_add_u32_e32 v187, 0, v6
	v_cvt_f32_ubyte0_e32 v14, v11
	s_cselect_b64 s[66:67], -1, 0
	v_writelane_b32 v255, s19, 37
	v_cmp_gt_u32_e64 s[18:19], 16, v9
	s_add_u32 s27, s62, 0x10000000
	v_add_f32_e32 v147, 0x3e4ccccd, v0
	v_lshlrev_b32_e32 v0, 3, v10
	v_cvt_pk_bf16_f32 v14, v14, v14
	v_cmp_gt_u32_e64 s[10:11], 32, v9
	v_writelane_b32 v255, s18, 38
	s_addc_u32 s76, s63, 0
	s_add_i32 s77, s13, s0
	s_lshl_b32 s0, s89, 2
	v_add_u32_e32 v146, v187, v5
	v_mov_b32_e32 v97, 0
	v_cndmask_b32_e64 v100, 0, v14, s[10:11]
	v_mul_u32_u24_e32 v14, 0x110, v11
	v_or_b32_e32 v11, 32, v11
	v_and_or_b32 v7, v7, 3, v0
	s_movk_i32 s14, 0x140
	v_writelane_b32 v255, s19, 39
	s_add_i32 s77, s77, s0
	v_mad_u64_u32 v[148:149], s[0:1], v140, 48, v[146:147]
	v_lshlrev_b32_e32 v1, 2, v8
	v_lshlrev_b32_e32 v6, 4, v10
	v_cvt_f32_ubyte0_e32 v11, v11
	v_lshlrev_b32_e32 v2, 9, v10
	v_mad_u32_u24 v192, v7, s14, 0
	v_mov_b32_e32 v7, v97
	v_writelane_b32 v255, s16, 40
	s_lshl_b32 s0, s16, 9
	v_cmp_eq_u32_e64 s[22:23], 0, v3
	v_or_b32_e32 v186, s5, v8
	v_cmp_gt_i32_e64 s[8:9], 4, v3
	v_lshl_add_u32 v188, v3, 2, s13
	v_lshl_or_b32 v3, s16, 7, v6
	v_cvt_pk_bf16_f32 v11, v11, v11
	v_mul_lo_u32 v190, v140, s14
	v_add3_u32 v191, s4, v1, v2
	v_lshlrev_b32_e32 v2, 2, v10
	v_lshl_add_u64 v[144:145], s[24:25], 0, v[6:7]
	s_add_i32 s78, s0, 0
	v_sub_u32_e32 v1, v0, v8
	v_readlane_b32 s0, v255, 24
	s_mov_b32 s24, 1.0
	s_mov_b32 s41, 0
	v_ashrrev_i32_e32 v141, 31, v140
	v_cmp_eq_u32_e64 s[6:7], 0, v9
	v_mov_b32_e32 v101, v97
	v_mov_b32_e32 v102, v97
	v_mov_b32_e32 v103, v97
	v_cndmask_b32_e64 v104, 0, v11, s[10:11]
	v_mov_b32_e32 v105, v97
	v_mov_b32_e32 v106, v97
	v_mov_b32_e32 v107, v97
	v_lshl_add_u64 v[142:143], s[68:69], 0, v[96:97]
	v_add3_u32 v193, 0, v14, v3
	v_subrev_u32_e32 v149, 64, v186
	v_subrev_u32_e32 v194, s5, v1
	s_add_i32 s79, s0, -1
	s_add_i32 s72, 0, 0x1c000
	v_lshlrev_b32_e32 v150, 1, v0
	v_lshlrev_b32_e32 v152, 1, v4
	s_mov_b32 s80, 0xf800000
	v_mov_b32_e32 v195, 0x260
	v_add_u32_e32 v196, s12, v12
	v_add_u32_e32 v197, v13, v190
	s_mov_b32 s25, 0xc3200000
	v_lshlrev_b32_e32 v154, 1, v2
	v_mov_b32_e32 v198, 0x3727c5ac
	v_mbcnt_hi_u32_b32 v254, -1, v139
	v_mov_b32_e32 v199, 0x42800000
	s_mov_b32 s101, s2
	s_mov_b32 s100, 0
	s_and_b32 s101, s101, 7
	s_branch .LBB0_231

.LBB0_238:
	s_waitcnt vmcnt(15)
	v_and_b32_e32 v34, 0xffff0000, v108
	v_lshlrev_b32_e32 v33, 16, v108
	v_mul_f32_e32 v34, v34, v34
	v_and_b32_e32 v36, 0xffff0000, v109
	v_fmac_f32_e32 v34, v33, v33
	v_lshlrev_b32_e32 v33, 16, v109
	v_mul_f32_e32 v36, v36, v36
	v_fmac_f32_e32 v36, v33, v33
	v_add_f32_e32 v33, v34, v36
	v_and_b32_e32 v36, 0xffff0000, v110
	v_lshlrev_b32_e32 v34, 16, v110
	v_mul_f32_e32 v36, v36, v36
	v_fmac_f32_e32 v36, v34, v34
	v_add_f32_e32 v33, v36, v33
	v_and_b32_e32 v36, 0xffff0000, v111
	v_lshlrev_b32_e32 v34, 16, v111
	v_mul_f32_e32 v36, v36, v36
	v_fmac_f32_e32 v36, v34, v34
	v_add_f32_e32 v33, v36, v33
	s_waitcnt vmcnt(14)
	v_and_b32_e32 v36, 0xffff0000, v112
	v_lshlrev_b32_e32 v34, 16, v112
	v_mul_f32_e32 v36, v36, v36
	v_fmac_f32_e32 v36, v34, v34
	v_add_f32_e32 v33, v36, v33
	v_and_b32_e32 v36, 0xffff0000, v113
	v_lshlrev_b32_e32 v34, 16, v113
	v_mul_f32_e32 v36, v36, v36
	v_fmac_f32_e32 v36, v34, v34
	v_add_f32_e32 v33, v36, v33
	v_and_b32_e32 v36, 0xffff0000, v114
	v_lshlrev_b32_e32 v34, 16, v114
	v_mul_f32_e32 v36, v36, v36
	v_fmac_f32_e32 v36, v34, v34
	v_add_f32_e32 v33, v36, v33
	v_and_b32_e32 v36, 0xffff0000, v115
	v_lshlrev_b32_e32 v34, 16, v115
	v_mul_f32_e32 v36, v36, v36
	v_fmac_f32_e32 v36, v34, v34
	v_add_f32_e32 v33, v36, v33
	s_waitcnt vmcnt(13)
	v_and_b32_e32 v36, 0xffff0000, v116
	v_lshlrev_b32_e32 v34, 16, v116
	v_mul_f32_e32 v36, v36, v36
	v_fmac_f32_e32 v36, v34, v34
	v_add_f32_e32 v33, v36, v33
	v_and_b32_e32 v36, 0xffff0000, v117
	v_lshlrev_b32_e32 v34, 16, v117
	v_mul_f32_e32 v36, v36, v36
	v_fmac_f32_e32 v36, v34, v34
	v_add_f32_e32 v33, v36, v33
	v_and_b32_e32 v36, 0xffff0000, v118
	v_lshlrev_b32_e32 v34, 16, v118
	v_mul_f32_e32 v36, v36, v36
	v_fmac_f32_e32 v36, v34, v34
	v_add_f32_e32 v33, v36, v33
	v_and_b32_e32 v36, 0xffff0000, v119
	v_lshlrev_b32_e32 v34, 16, v119
	v_mul_f32_e32 v36, v36, v36
	v_fmac_f32_e32 v36, v34, v34
	v_add_f32_e32 v33, v36, v33
	s_waitcnt vmcnt(12)
	v_and_b32_e32 v36, 0xffff0000, v120
	v_lshlrev_b32_e32 v34, 16, v120
	v_mul_f32_e32 v36, v36, v36
	v_fmac_f32_e32 v36, v34, v34
	v_add_f32_e32 v33, v36, v33
	v_and_b32_e32 v36, 0xffff0000, v121
	v_lshlrev_b32_e32 v34, 16, v121
	v_mul_f32_e32 v36, v36, v36
	v_fmac_f32_e32 v36, v34, v34
	v_add_f32_e32 v33, v36, v33
	v_and_b32_e32 v36, 0xffff0000, v122
	v_lshlrev_b32_e32 v34, 16, v122
	v_mul_f32_e32 v36, v36, v36
	v_fmac_f32_e32 v36, v34, v34
	v_add_f32_e32 v33, v36, v33
	v_and_b32_e32 v36, 0xffff0000, v123
	v_lshlrev_b32_e32 v34, 16, v123
	v_mul_f32_e32 v36, v36, v36
	v_fmac_f32_e32 v36, v34, v34
	v_add_f32_e32 v33, v36, v33
	v_and_b32_e32 v36, 64, v254
	v_xor_b32_e32 v34, 32, v254
	v_add_u32_e32 v37, 64, v36
	v_cmp_lt_i32_e32 vcc, v34, v37
	s_nop 1
	v_cndmask_b32_e32 v34, v254, v34, vcc
	v_lshlrev_b32_e32 v151, 2, v34
	ds_bpermute_b32 v34, v151, v33
	s_and_b64 vcc, exec, s[20:21]
	s_cbranch_vccnz .LBB0_240
	v_add_u32_e32 v37, -1, v254
	v_cmp_lt_i32_e32 vcc, v37, v36
	v_max_f32_e32 v39, v35, v35
	v_add_u32_e32 v40, -2, v254
	v_cndmask_b32_e32 v37, v37, v254, vcc
	v_lshlrev_b32_e32 v37, 2, v37
	ds_bpermute_b32 v38, v37, v35
	v_cmp_lt_i32_e32 vcc, v40, v36
	v_readlane_b32 s14, v255, 32
	v_readlane_b32 s15, v255, 33
	v_max_f32_e32 v32, v32, v32
	s_waitcnt lgkmcnt(0)
	v_max_f32_e32 v38, v38, v38
	v_max_f32_e32 v38, v39, v38
	v_cndmask_b32_e64 v35, v38, v35, s[6:7]
	v_cndmask_b32_e32 v38, v40, v254, vcc
	v_lshlrev_b32_e32 v38, 2, v38
	ds_bpermute_b32 v38, v38, v35
	v_add_u32_e32 v39, -4, v254
	v_max_f32_e32 v40, v35, v35
	v_cmp_lt_i32_e32 vcc, v39, v36
	s_mov_b32 s12, 0x3f8020c5
	s_waitcnt lgkmcnt(0)
	v_max_f32_e32 v38, v38, v38
	v_max_f32_e32 v38, v40, v38
	v_cndmask_b32_e64 v35, v38, v35, s[14:15]
	v_cndmask_b32_e32 v38, v39, v254, vcc
	v_lshlrev_b32_e32 v38, 2, v38
	ds_bpermute_b32 v38, v38, v35
	v_max_f32_e32 v39, v35, v35
	v_readlane_b32 s14, v255, 34
	v_readlane_b32 s15, v255, 35
	s_waitcnt lgkmcnt(0)
	v_max_f32_e32 v38, v38, v38
	v_max_f32_e32 v38, v39, v38
	v_cndmask_b32_e64 v35, v38, v35, s[14:15]
	v_add_u32_e32 v38, -8, v254
	v_cmp_lt_i32_e32 vcc, v38, v36
	v_max_f32_e32 v39, v35, v35
	v_readlane_b32 s14, v255, 36
	v_cndmask_b32_e32 v38, v38, v254, vcc
	v_lshlrev_b32_e32 v38, 2, v38
	ds_bpermute_b32 v38, v38, v35
	v_readlane_b32 s15, v255, 37
	s_waitcnt lgkmcnt(0)
	v_max_f32_e32 v38, v38, v38
	v_max_f32_e32 v38, v39, v38
	v_cndmask_b32_e64 v35, v38, v35, s[14:15]
	v_add_u32_e32 v38, -16, v254
	v_cmp_lt_i32_e32 vcc, v38, v36
	v_max_f32_e32 v39, v35, v35
	v_readlane_b32 s14, v255, 38
	v_cndmask_b32_e32 v38, v38, v254, vcc
	v_lshlrev_b32_e32 v38, 2, v38
	ds_bpermute_b32 v38, v38, v35
	v_readlane_b32 s15, v255, 39
	s_waitcnt lgkmcnt(0)
	v_max_f32_e32 v38, v38, v38
	v_max_f32_e32 v38, v39, v38
	v_cndmask_b32_e64 v35, v38, v35, s[14:15]
	v_subrev_u32_e32 v38, 32, v254
	v_cmp_lt_i32_e32 vcc, v38, v36
	s_nop 1
	v_cndmask_b32_e32 v36, v38, v254, vcc
	v_lshlrev_b32_e32 v36, 2, v36
	ds_bpermute_b32 v36, v36, v35
	v_max_f32_e32 v38, v35, v35
	s_waitcnt lgkmcnt(0)
	v_max_f32_e32 v36, v36, v36
	v_max_f32_e32 v36, v38, v36
	v_cndmask_b32_e64 v35, v36, v35, s[10:11]
	ds_bpermute_b32 v36, v37, v35
	s_waitcnt lgkmcnt(0)
	v_cndmask_b32_e64 v36, v36, 0, s[6:7]
	v_max_f32_e32 v36, v36, v36
	v_max_f32_e32 v32, v36, v32
	v_mul_f32_e32 v36, 0x4f800000, v32
	v_cmp_gt_f32_e32 vcc, s80, v32
	s_nop 1
	v_cndmask_b32_e32 v32, v32, v36, vcc
	v_sqrt_f32_e32 v36, v32
	s_nop 0
	v_add_u32_e32 v37, -1, v36
	v_fma_f32 v39, -v37, v36, v32
	v_add_u32_e32 v38, 1, v36
	v_cmp_ge_f32_e64 s[20:21], 0, v39
	s_nop 1
	v_cndmask_b32_e64 v37, v36, v37, s[20:21]
	v_fma_f32 v36, -v38, v36, v32
	v_cmp_lt_f32_e64 s[20:21], 0, v36
	s_nop 1
	v_cndmask_b32_e64 v36, v37, v38, s[20:21]
	v_mul_f32_e32 v38, 0x4f800000, v35
	v_cmp_gt_f32_e64 s[20:21], s80, v35
	v_mul_f32_e32 v37, 0x37800000, v36
	v_cndmask_b32_e32 v36, v36, v37, vcc
	v_cndmask_b32_e64 v35, v35, v38, s[20:21]
	v_sqrt_f32_e32 v38, v35
	v_cmp_class_f32_e32 vcc, v32, v195
	s_nop 1
	v_cndmask_b32_e32 v36, v36, v32, vcc
	v_add_u32_e32 v32, -1, v38
	v_fma_f32 v37, -v32, v38, v35
	v_cmp_ge_f32_e32 vcc, 0, v37
	v_add_u32_e32 v37, 1, v38
	s_nop 0
	v_cndmask_b32_e32 v32, v38, v32, vcc
	v_fma_f32 v38, -v37, v38, v35
	v_cmp_lt_f32_e32 vcc, 0, v38
	s_nop 1
	v_cndmask_b32_e32 v32, v32, v37, vcc
	v_mul_f32_e32 v37, 0x37800000, v32
	v_cndmask_b32_e64 v32, v32, v37, s[20:21]
	v_cmp_class_f32_e32 vcc, v35, v195
	s_nop 1
	v_cndmask_b32_e32 v37, v32, v35, vcc
	v_mul_f32_e32 v36, s12, v36
	v_mul_f32_e32 v37, s12, v37
	ds_write_b64 v196, v[36:37]

.LBB0_311:
	v_lshl_add_u64 v[0:1], s[10:11], 0, v[18:19]
	global_load_dwordx2 v[2:3], v[0:1], off nt
	global_load_dwordx2 v[4:5], v[0:1], off offset:512 nt
	global_load_dwordx2 v[6:7], v[0:1], off offset:1024 nt
	s_nop 0
	global_load_dwordx2 v[0:1], v[0:1], off offset:1536 nt
	s_add_i32 s7, s82, s5
	s_cmp_lt_i32 s7, 0x8000
	s_cselect_b32 s46, s7, s5
	s_ashr_i32 s27, s5, 31
	s_lshr_b32 s27, s27, 19
	s_add_i32 s27, s5, s27
	s_ashr_i32 s47, s46, 31
	s_ashr_i32 s27, s27, 13
	s_lshl_b64 s[48:49], s[46:47], 13
	s_lshl_b64 s[50:51], s[46:47], 12
	s_mul_i32 s46, s27, 0xc00
	s_ashr_i32 s47, s46, 31
	s_lshl_b64 s[46:47], s[46:47], 2
	s_add_u32 s46, s34, s46
	s_addc_u32 s47, s35, s47
	v_lshl_add_u64 v[30:31], v[16:17], 2, s[46:47]
	v_add_co_u32_e32 v10, vcc, s0, v30
	v_lshl_add_u64 v[8:9], s[18:19], 0, v[22:23]
	s_nop 0
	v_addc_co_u32_e32 v11, vcc, 0, v31, vcc
	s_waitcnt lgkmcnt(0)
	global_load_dwordx4 v[56:59], v[10:11], off
	global_load_dwordx4 v[40:43], v[26:27], off
	global_load_dwordx4 v[44:47], v[8:9], off nt
	global_load_dwordx4 v[60:63], v[8:9], off offset:1024 nt
	v_lshl_add_u64 v[88:89], s[36:37], 0, v[22:23]
	global_load_dwordx4 v[64:67], v[8:9], off offset:3072 nt
	global_load_dwordx4 v[68:71], v[8:9], off offset:2048 nt
	s_cmpk_gt_i32 s7, 0x7fff
	s_waitcnt vmcnt(9)
	v_and_b32_e32 v73, 0xffff0000, v2
	s_waitcnt vmcnt(8)
	v_and_b32_e32 v77, 0xffff0000, v4
	v_lshlrev_b32_e32 v72, 16, v2
	v_lshlrev_b32_e32 v74, 16, v3
	v_and_b32_e32 v75, 0xffff0000, v3
	v_lshlrev_b32_e32 v76, 16, v4
	s_waitcnt vmcnt(7)
	v_and_b32_e32 v81, 0xffff0000, v6
	s_waitcnt vmcnt(6)
	v_and_b32_e32 v85, 0xffff0000, v0
	v_mov_b32_e32 v2, v73
	v_mov_b32_e32 v3, v77
	v_lshlrev_b32_e32 v78, 16, v5
	v_lshlrev_b32_e32 v80, 16, v6
	v_lshlrev_b32_e32 v84, 16, v0
	v_lshlrev_b32_e32 v86, 16, v1
	v_and_b32_e32 v87, 0xffff0000, v1
	v_mov_b32_e32 v0, v72
	v_mov_b32_e32 v1, v76
	v_mov_b32_e32 v12, v81
	v_mov_b32_e32 v13, v85
	v_mul_f32_e32 v2, v2, v2
	v_mul_f32_e32 v3, v3, v3
	v_and_b32_e32 v79, 0xffff0000, v5
	v_lshlrev_b32_e32 v82, 16, v7
	v_mov_b32_e32 v4, v74
	v_mov_b32_e32 v5, v78
	v_mov_b32_e32 v10, v80
	v_mov_b32_e32 v11, v84
	v_mul_f32_e32 v12, v12, v12
	v_mul_f32_e32 v13, v13, v13
	v_fma_f32 v0, v0, v0, v2
	v_fma_f32 v1, v1, v1, v3
	v_and_b32_e32 v83, 0xffff0000, v7
	v_mov_b32_e32 v6, v75
	v_mov_b32_e32 v7, v79
	v_mov_b32_e32 v14, v82
	v_mov_b32_e32 v15, v86
	v_fma_f32 v2, v10, v10, v12
	v_fma_f32 v3, v11, v11, v13
	v_fma_f32 v0, v4, v4, v0
	v_fma_f32 v1, v5, v5, v1
	v_mov_b32_e32 v32, v83
	v_mov_b32_e32 v33, v87
	v_fma_f32 v2, v14, v14, v2
	v_fma_f32 v3, v15, v15, v3
	v_fma_f32 v0, v6, v6, v0
	v_fma_f32 v1, v7, v7, v1
	v_fma_f32 v2, v32, v32, v2
	v_fma_f32 v3, v33, v33, v3
	v_add_f32_e32 v0, v0, v1
	v_add_f32_e32 v0, v0, v2
	v_add_f32_e32 v0, v0, v3
	ds_bpermute_b32 v1, v48, v0
	s_waitcnt vmcnt(5)
	v_mul_f32_e32 v56, v56, v72
	v_mul_f32_e32 v57, v57, v73
	v_mul_f32_e32 v58, v58, v74
	v_mul_f32_e32 v59, v59, v75
	v_lshl_add_u64 v[2:3], v[24:25], 0, s[50:51]
	global_load_dwordx4 v[12:15], v[2:3], off nt
	global_load_dwordx4 v[8:11], v[2:3], off offset:1024 nt
	s_waitcnt lgkmcnt(0)
	v_add_f32_e32 v0, v0, v1
	ds_bpermute_b32 v1, v49, v0
	s_waitcnt lgkmcnt(0)
	v_add_f32_e32 v0, v0, v1
	ds_bpermute_b32 v1, v50, v0
	s_waitcnt lgkmcnt(0)
	v_add_f32_e32 v0, v0, v1
	ds_bpermute_b32 v1, v51, v0
	s_waitcnt lgkmcnt(0)
	v_add_f32_e32 v4, v0, v1
	ds_bpermute_b32 v5, v52, v4
	v_lshl_add_u64 v[0:1], v[20:21], 0, s[48:49]
	s_waitcnt lgkmcnt(0)
	v_add_f32_e32 v55, v4, v5
	ds_bpermute_b32 v90, v53, v55
	global_load_dwordx2 v[38:39], v[0:1], off nt
	global_load_dwordx2 v[36:37], v[0:1], off offset:512 nt
	global_load_dwordx2 v[34:35], v[0:1], off offset:1024 nt
	global_load_dwordx2 v[32:33], v[0:1], off offset:1536 nt
	global_load_dwordx4 v[4:7], v[2:3], off offset:2048 nt
	s_nop 0
	global_load_dwordx4 v[0:3], v[2:3], off offset:3072 nt
	s_waitcnt lgkmcnt(0)
	v_add_f32_e32 v55, v55, v90
	v_fmamk_f32 v55, v55, 0x3a800000, v54
	v_mul_f32_e32 v90, 0x4b800000, v55
	v_cmp_gt_f32_e32 vcc, s1, v55
	s_nop 1
	v_cndmask_b32_e32 v55, v55, v90, vcc
	v_rsq_f32_e32 v55, v55
	v_lshl_add_u64 v[90:91], v[30:31], 0, s[40:41]
	v_mul_f32_e32 v72, 0x45800000, v55
	v_cndmask_b32_e32 v72, v55, v72, vcc
	v_mul_f32_e32 v56, v72, v56
	v_mul_f32_e32 v57, v72, v57
	v_mul_f32_e32 v58, v72, v58
	v_mul_f32_e32 v59, v72, v59
	s_waitcnt vmcnt(11)
	v_fma_f32 v40, v40, v56, v44
	v_fma_f32 v41, v41, v57, v45
	v_fma_f32 v42, v42, v58, v46
	v_fma_f32 v43, v43, v59, v47
	global_store_dwordx4 v[88:89], v[40:43], off nt
	global_load_dwordx4 v[44:47], v[90:91], off offset:1024
	global_load_dwordx4 v[56:59], v[26:27], off offset:1024
	v_add_co_u32_e32 v74, vcc, s4, v30
	s_waitcnt vmcnt(1)
	v_mul_f32_e32 v44, v44, v76
	v_mul_f32_e32 v45, v45, v77
	v_mul_f32_e32 v46, v46, v78
	v_mul_f32_e32 v47, v47, v79
	v_mul_f32_e32 v44, v72, v44
	v_mul_f32_e32 v45, v72, v45
	v_mul_f32_e32 v46, v72, v46
	v_mul_f32_e32 v47, v72, v47
	s_waitcnt vmcnt(0)
	v_fma_f32 v44, v56, v44, v60
	v_fma_f32 v45, v57, v45, v61
	v_fma_f32 v46, v58, v46, v62
	v_fma_f32 v47, v59, v47, v63
	global_store_dwordx4 v[88:89], v[44:47], off offset:1024 nt
	global_load_dwordx4 v[56:59], v[90:91], off offset:2048
	global_load_dwordx4 v[60:63], v[26:27], off offset:2048
	v_addc_co_u32_e32 v75, vcc, 0, v31, vcc
	v_mov_b32_e32 v78, v41
	v_mov_b32_e32 v79, v45
	v_mov_b32_e32 v76, v40
	v_mov_b32_e32 v77, v44
	v_mul_f32_e32 v78, v78, v78
	v_mul_f32_e32 v79, v79, v79
	s_waitcnt vmcnt(1)
	v_mul_f32_e32 v56, v56, v80
	v_mul_f32_e32 v57, v57, v81
	v_mul_f32_e32 v58, v58, v82
	v_mul_f32_e32 v59, v59, v83
	v_mul_f32_e32 v56, v72, v56
	v_mul_f32_e32 v57, v72, v57
	v_mul_f32_e32 v58, v72, v58
	v_mul_f32_e32 v59, v72, v59
	s_waitcnt vmcnt(0)
	v_fma_f32 v56, v60, v56, v68
	v_fma_f32 v57, v61, v57, v69
	v_fma_f32 v58, v62, v58, v70
	v_fma_f32 v59, v63, v59, v71
	global_store_dwordx4 v[88:89], v[56:59], off offset:2048 nt
	global_load_dwordx4 v[60:63], v[90:91], off offset:3072
	global_load_dwordx4 v[68:71], v[26:27], off offset:3072
	v_mov_b32_e32 v80, v42
	v_mov_b32_e32 v81, v46
	v_fma_f32 v76, v76, v76, v78
	v_fma_f32 v77, v77, v77, v79
	v_mov_b32_e32 v82, v43
	v_mov_b32_e32 v83, v47
	v_fma_f32 v76, v80, v80, v76
	v_fma_f32 v77, v81, v81, v77
	v_mov_b32_e32 v78, v57
	v_fma_f32 v76, v82, v82, v76
	v_fma_f32 v77, v83, v83, v77
	v_mov_b32_e32 v80, v58
	v_add_f32_e32 v55, v76, v77
	v_mov_b32_e32 v76, v56
	v_mov_b32_e32 v82, v59
	s_waitcnt vmcnt(1)
	v_mul_f32_e32 v60, v60, v84
	v_mul_f32_e32 v61, v61, v85
	v_mul_f32_e32 v62, v62, v86
	v_mul_f32_e32 v63, v63, v87
	v_mul_f32_e32 v60, v72, v60
	v_mul_f32_e32 v61, v72, v61
	v_mul_f32_e32 v62, v72, v62
	v_mul_f32_e32 v63, v72, v63
	s_waitcnt vmcnt(0)
	v_fma_f32 v60, v68, v60, v64
	v_fma_f32 v61, v69, v61, v65
	v_fma_f32 v62, v70, v62, v66
	v_fma_f32 v63, v71, v63, v67
	global_store_dwordx4 v[88:89], v[60:63], off offset:3072 nt
	global_load_dwordx4 v[64:67], v[28:29], off
	global_load_dwordx4 v[68:71], v[74:75], off
	s_nop 0
	global_load_dwordx4 v[72:75], v[74:75], off offset:-4096
	v_mov_b32_e32 v79, v61
	v_mov_b32_e32 v77, v60
	v_mul_f32_e32 v78, v78, v78
	v_mul_f32_e32 v79, v79, v79
	v_mov_b32_e32 v81, v62
	v_fma_f32 v76, v76, v76, v78
	v_fma_f32 v77, v77, v77, v79
	v_mov_b32_e32 v83, v63
	v_fma_f32 v76, v80, v80, v76
	v_fma_f32 v77, v81, v81, v77
	v_lshl_add_u64 v[78:79], v[30:31], 0, s[44:45]
	v_fma_f32 v76, v82, v82, v76
	v_fma_f32 v77, v83, v83, v77
	v_lshl_add_u64 v[30:31], v[30:31], 0, s[42:43]
	v_add_f32_e32 v55, v55, v76
	v_add_f32_e32 v55, v55, v77
	ds_bpermute_b32 v76, v48, v55
	s_waitcnt lgkmcnt(0)
	v_add_f32_e32 v55, v55, v76
	ds_bpermute_b32 v76, v49, v55
	s_waitcnt lgkmcnt(0)
	v_add_f32_e32 v55, v55, v76
	ds_bpermute_b32 v76, v50, v55
	s_waitcnt lgkmcnt(0)
	v_add_f32_e32 v55, v55, v76
	ds_bpermute_b32 v76, v51, v55
	s_waitcnt lgkmcnt(0)
	v_add_f32_e32 v55, v55, v76
	ds_bpermute_b32 v76, v52, v55
	s_waitcnt lgkmcnt(0)
	v_add_f32_e32 v55, v55, v76
	ds_bpermute_b32 v76, v53, v55
	s_waitcnt lgkmcnt(0)
	v_add_f32_e32 v55, v55, v76
	v_fmamk_f32 v55, v55, 0x3a800000, v54
	v_mul_f32_e32 v76, 0x4b800000, v55
	v_cmp_gt_f32_e32 vcc, s1, v55
	s_nop 1
	v_cndmask_b32_e32 v55, v55, v76, vcc
	v_rsq_f32_e32 v55, v55
	v_lshl_add_u64 v[76:77], s[38:39], 0, v[18:19]
	v_mul_f32_e32 v80, 0x45800000, v55
	v_cndmask_b32_e32 v80, v55, v80, vcc
	v_mul_f32_e32 v40, v40, v80
	v_mul_f32_e32 v41, v41, v80
	v_mul_f32_e32 v42, v42, v80
	v_mul_f32_e32 v43, v43, v80
	v_mul_f32_e32 v44, v44, v80
	v_mul_f32_e32 v45, v45, v80
	v_mul_f32_e32 v46, v46, v80
	v_mul_f32_e32 v47, v47, v80
	v_mul_f32_e32 v56, v56, v80
	v_mul_f32_e32 v57, v57, v80
	v_mul_f32_e32 v58, v58, v80
	v_mul_f32_e32 v59, v59, v80
	s_waitcnt vmcnt(2)
	v_mul_f32_e32 v40, v64, v40
	v_mul_f32_e32 v41, v65, v41
	s_waitcnt vmcnt(1)
	v_add_f32_e32 v64, 1.0, v68
	v_add_f32_e32 v65, 1.0, v69
	v_mul_f32_e32 v42, v66, v42
	v_mul_f32_e32 v43, v67, v43
	v_add_f32_e32 v66, 1.0, v70
	v_add_f32_e32 v67, 1.0, v71
	s_waitcnt vmcnt(0)
	v_fma_f32 v40, v64, v40, v72
	v_fma_f32 v41, v65, v41, v73
	v_fma_f32 v42, v66, v42, v74
	v_fma_f32 v43, v67, v43, v75
	v_cvt_pk_bf16_f32 v40, v40, v41
	v_cvt_pk_bf16_f32 v41, v42, v43
	global_store_dwordx2 v[76:77], v[40:41], off nt
	global_load_dwordx4 v[40:43], v[28:29], off offset:1024
	s_nop 0
	global_load_dwordx4 v[64:67], v[78:79], off offset:1024
	global_load_dwordx4 v[68:71], v[30:31], off offset:1024
	s_waitcnt vmcnt(2)
	v_mul_f32_e32 v40, v40, v44
	v_mul_f32_e32 v41, v41, v45
	s_waitcnt vmcnt(1)
	v_add_f32_e32 v44, 1.0, v64
	v_add_f32_e32 v45, 1.0, v65
	v_mul_f32_e32 v42, v46, v42
	v_mul_f32_e32 v43, v47, v43
	v_add_f32_e32 v46, 1.0, v66
	v_add_f32_e32 v47, 1.0, v67
	s_waitcnt vmcnt(0)
	v_fma_f32 v40, v40, v44, v68
	v_fma_f32 v41, v41, v45, v69
	v_fma_f32 v42, v42, v46, v70
	v_fma_f32 v43, v43, v47, v71
	v_cvt_pk_bf16_f32 v40, v40, v41
	v_cvt_pk_bf16_f32 v41, v42, v43
	global_store_dwordx2 v[76:77], v[40:41], off offset:512 nt
	global_load_dwordx4 v[40:43], v[28:29], off offset:2048
	s_nop 0
	global_load_dwordx4 v[44:47], v[78:79], off offset:2048
	global_load_dwordx4 v[64:67], v[30:31], off offset:2048
	s_waitcnt vmcnt(2)
	v_mul_f32_e32 v40, v56, v40
	v_mul_f32_e32 v41, v57, v41
	s_waitcnt vmcnt(1)
	v_add_f32_e32 v44, 1.0, v44
	v_add_f32_e32 v45, 1.0, v45
	v_mul_f32_e32 v42, v58, v42
	v_mul_f32_e32 v43, v59, v43
	v_add_f32_e32 v46, 1.0, v46
	v_add_f32_e32 v47, 1.0, v47
	s_waitcnt vmcnt(0)
	v_fma_f32 v40, v40, v44, v64
	v_fma_f32 v41, v41, v45, v65
	v_fma_f32 v42, v42, v46, v66
	v_fma_f32 v43, v43, v47, v67
	v_cvt_pk_bf16_f32 v40, v40, v41
	v_cvt_pk_bf16_f32 v41, v42, v43
	global_store_dwordx2 v[76:77], v[40:41], off offset:1024 nt
	global_load_dwordx4 v[64:67], v[28:29], off offset:3072
	global_load_dwordx4 v[68:71], v[78:79], off offset:3072
	global_load_dwordx4 v[72:75], v[30:31], off offset:3072
	v_lshlrev_b32_e32 v44, 16, v38
	v_and_b32_e32 v45, 0xffff0000, v38
	v_lshlrev_b32_e32 v42, 16, v36
	v_and_b32_e32 v43, 0xffff0000, v36
	v_lshlrev_b32_e32 v46, 16, v39
	v_and_b32_e32 v47, 0xffff0000, v39
	v_lshlrev_b32_e32 v40, 16, v37
	v_and_b32_e32 v41, 0xffff0000, v37
	v_lshlrev_b32_e32 v38, 16, v34
	v_and_b32_e32 v39, 0xffff0000, v34
	v_mul_f32_e32 v30, v44, v44
	v_mul_f32_e32 v31, v45, v45
	v_mul_f32_e32 v58, v42, v42
	v_mul_f32_e32 v59, v43, v43
	v_lshlrev_b32_e32 v36, 16, v35
	v_and_b32_e32 v37, 0xffff0000, v35
	v_lshlrev_b32_e32 v34, 16, v32
	v_and_b32_e32 v35, 0xffff0000, v32
	v_mul_f32_e32 v56, v46, v46
	v_mul_f32_e32 v57, v47, v47
	v_mul_f32_e32 v78, v40, v40
	v_mul_f32_e32 v79, v41, v41
	v_mul_f32_e32 v82, v38, v38
	v_mul_f32_e32 v83, v39, v39
	v_add_f32_e32 v55, v58, v59
	v_add_f32_e32 v30, v30, v31
	v_lshlrev_b32_e32 v32, 16, v33
	v_and_b32_e32 v33, 0xffff0000, v33
	v_mul_f32_e32 v84, v36, v36
	v_mul_f32_e32 v85, v37, v37
	v_mul_f32_e32 v86, v34, v34
	v_mul_f32_e32 v87, v35, v35
	v_add_f32_e32 v31, v82, v83
	v_add_f32_e32 v55, v78, v55
	v_add_f32_e32 v30, v56, v30
	v_mul_f32_e32 v88, v32, v32
	v_mul_f32_e32 v89, v33, v33
	v_add_f32_e32 v58, v86, v87
	v_add_f32_e32 v31, v84, v31
	v_add_f32_e32 v55, v79, v55
	v_add_f32_e32 v30, v57, v30
	v_add_f32_e32 v56, v88, v58
	v_add_f32_e32 v31, v85, v31
	v_add_f32_e32 v30, v30, v55
	v_add_f32_e32 v56, v89, v56
	v_add_f32_e32 v30, v30, v31
	v_add_f32_e32 v30, v30, v56
	ds_bpermute_b32 v31, v48, v30
	v_mul_f32_e32 v58, v62, v80
	v_mul_f32_e32 v59, v63, v80
	s_waitcnt lgkmcnt(0)
	v_add_f32_e32 v30, v30, v31
	ds_bpermute_b32 v31, v49, v30
	s_waitcnt lgkmcnt(0)
	v_add_f32_e32 v30, v30, v31
	ds_bpermute_b32 v31, v50, v30
	s_waitcnt lgkmcnt(0)
	v_add_f32_e32 v30, v30, v31
	ds_bpermute_b32 v31, v51, v30
	s_waitcnt lgkmcnt(0)
	v_add_f32_e32 v30, v30, v31
	ds_bpermute_b32 v31, v52, v30
	s_waitcnt lgkmcnt(0)
	v_add_f32_e32 v55, v30, v31
	ds_bpermute_b32 v56, v53, v55
	v_mul_f32_e32 v30, v60, v80
	v_mul_f32_e32 v31, v61, v80
	s_waitcnt vmcnt(2)
	v_mul_f32_e32 v58, v58, v66
	v_mul_f32_e32 v59, v59, v67
	v_mul_f32_e32 v30, v30, v64
	v_mul_f32_e32 v31, v31, v65
	s_waitcnt vmcnt(1)
	v_add_f32_e32 v60, 1.0, v68
	v_add_f32_e32 v61, 1.0, v69
	v_add_f32_e32 v62, 1.0, v70
	v_add_f32_e32 v63, 1.0, v71
	s_waitcnt vmcnt(0)
	v_fma_f32 v30, v30, v60, v72
	v_fma_f32 v31, v31, v61, v73
	v_fma_f32 v58, v58, v62, v74
	v_fma_f32 v59, v59, v63, v75
	v_cvt_pk_bf16_f32 v30, v30, v31
	v_cvt_pk_bf16_f32 v31, v58, v59
	global_store_dwordx2 v[76:77], v[30:31], off offset:1536 nt
	s_cbranch_scc1 .LBB0_310
	s_ashr_i32 s27, s7, 31
	s_lshr_b32 s27, s27, 19
	s_add_i32 s7, s7, s27
	s_ashr_i32 s7, s7, 13
	s_mul_i32 s46, s7, 0xc00
	s_ashr_i32 s47, s46, 31
	s_lshl_b64 s[46:47], s[46:47], 2
	s_add_u32 s46, s34, s46
	s_addc_u32 s47, s35, s47
	v_lshl_add_u64 v[30:31], v[16:17], 2, s[46:47]
	v_add_co_u32_e32 v58, vcc, s0, v30
	s_waitcnt lgkmcnt(0)
	v_add_f32_e32 v55, v55, v56
	v_addc_co_u32_e32 v59, vcc, 0, v31, vcc
	global_load_dwordx4 v[58:61], v[58:59], off
	s_nop 0
	global_load_dwordx4 v[62:65], v[26:27], off
	v_fmamk_f32 v55, v55, 0x3a800000, v54
	v_mul_f32_e32 v56, 0x4b800000, v55
	v_cmp_gt_f32_e32 vcc, s1, v55
	v_lshl_add_u64 v[66:67], s[24:25], 0, v[22:23]
	v_lshl_add_u64 v[70:71], v[30:31], 0, s[40:41]
	v_cndmask_b32_e32 v55, v55, v56, vcc
	v_rsq_f32_e32 v55, v55
	s_waitcnt vmcnt(1)
	v_mul_f32_e32 v44, v58, v44
	v_mul_f32_e32 v45, v59, v45
	v_mul_f32_e32 v56, 0x45800000, v55
	v_cndmask_b32_e32 v68, v55, v56, vcc
	v_mul_f32_e32 v46, v60, v46
	v_mul_f32_e32 v47, v61, v47
	v_mul_f32_e32 v44, v68, v44
	v_mul_f32_e32 v45, v68, v45
	v_mul_f32_e32 v46, v68, v46
	v_mul_f32_e32 v47, v68, v47
	s_waitcnt vmcnt(0)
	v_fma_f32 v12, v62, v44, v12
	v_fma_f32 v13, v63, v45, v13
	v_fma_f32 v14, v64, v46, v14
	v_fma_f32 v15, v65, v47, v15
	global_store_dwordx4 v[66:67], v[12:15], off nt
	global_load_dwordx4 v[44:47], v[70:71], off offset:1024
	global_load_dwordx4 v[56:59], v[26:27], off offset:1024
	s_waitcnt vmcnt(1)
	v_mul_f32_e32 v42, v44, v42
	v_mul_f32_e32 v43, v45, v43
	v_mul_f32_e32 v40, v46, v40
	v_mul_f32_e32 v41, v47, v41
	v_mul_f32_e32 v42, v68, v42
	v_mul_f32_e32 v43, v68, v43
	v_mul_f32_e32 v40, v68, v40
	v_mul_f32_e32 v41, v68, v41
	s_waitcnt vmcnt(0)
	v_fma_f32 v8, v56, v42, v8
	v_fma_f32 v9, v57, v43, v9
	v_fma_f32 v10, v58, v40, v10
	v_fma_f32 v11, v59, v41, v11
	global_store_dwordx4 v[66:67], v[8:11], off offset:1024 nt
	global_load_dwordx4 v[40:43], v[70:71], off offset:2048
	global_load_dwordx4 v[44:47], v[26:27], off offset:2048
	v_mov_b32_e32 v56, v14
	v_mov_b32_e32 v57, v10
	v_mov_b32_e32 v58, v15
	v_mov_b32_e32 v59, v11
	s_waitcnt vmcnt(1)
	v_mul_f32_e32 v38, v40, v38
	v_mul_f32_e32 v39, v41, v39
	v_mul_f32_e32 v36, v42, v36
	v_mul_f32_e32 v37, v43, v37
	v_mul_f32_e32 v38, v68, v38
	v_mul_f32_e32 v39, v68, v39
	v_mul_f32_e32 v36, v68, v36
	v_mul_f32_e32 v37, v68, v37
	s_waitcnt vmcnt(0)
	v_fma_f32 v4, v44, v38, v4
	v_fma_f32 v5, v45, v39, v5
	v_fma_f32 v6, v46, v36, v6
	v_fma_f32 v7, v47, v37, v7
	global_store_dwordx4 v[66:67], v[4:7], off offset:2048 nt
	global_load_dwordx4 v[36:39], v[70:71], off offset:3072
	global_load_dwordx4 v[40:43], v[26:27], off offset:3072
	v_add_co_u32_e32 v44, vcc, s4, v30
	v_mov_b32_e32 v46, v13
	s_nop 0
	v_addc_co_u32_e32 v45, vcc, 0, v31, vcc
	v_mov_b32_e32 v47, v9
	v_mul_f32_e32 v46, v46, v46
	v_mul_f32_e32 v47, v47, v47
	s_waitcnt vmcnt(1)
	v_mul_f32_e32 v34, v36, v34
	v_mul_f32_e32 v35, v37, v35
	v_mul_f32_e32 v32, v38, v32
	v_mul_f32_e32 v33, v39, v33
	v_mul_f32_e32 v34, v68, v34
	v_mul_f32_e32 v35, v68, v35
	v_mul_f32_e32 v32, v68, v32
	v_mul_f32_e32 v33, v68, v33
	s_waitcnt vmcnt(0)
	v_fma_f32 v0, v40, v34, v0
	v_fma_f32 v1, v41, v35, v1
	v_fma_f32 v2, v42, v32, v2
	v_fma_f32 v3, v43, v33, v3
	global_store_dwordx4 v[66:67], v[0:3], off offset:3072 nt
	global_load_dwordx4 v[32:35], v[28:29], off
	global_load_dwordx4 v[36:39], v[44:45], off
	global_load_dwordx4 v[40:43], v[44:45], off offset:-4096
	v_mov_b32_e32 v44, v12
	v_mov_b32_e32 v45, v8
	v_fma_f32 v44, v44, v44, v46
	v_fma_f32 v45, v45, v45, v47
	v_mov_b32_e32 v46, v5
	v_fma_f32 v44, v56, v56, v44
	v_fma_f32 v45, v57, v57, v45
	v_mov_b32_e32 v47, v1
	v_fma_f32 v44, v58, v58, v44
	v_fma_f32 v45, v59, v59, v45
	v_mul_f32_e32 v46, v46, v46
	v_mul_f32_e32 v47, v47, v47
	v_add_f32_e32 v55, v44, v45
	v_mov_b32_e32 v44, v4
	v_mov_b32_e32 v45, v0
	v_mov_b32_e32 v56, v6
	v_mov_b32_e32 v57, v2
	v_fma_f32 v44, v44, v44, v46
	v_fma_f32 v45, v45, v45, v47
	v_mov_b32_e32 v58, v7
	v_mov_b32_e32 v59, v3
	v_fma_f32 v44, v56, v56, v44
	v_fma_f32 v45, v57, v57, v45
	v_lshl_add_u64 v[46:47], v[30:31], 0, s[44:45]
	v_fma_f32 v44, v58, v58, v44
	v_fma_f32 v45, v59, v59, v45
	s_nop 0
	v_add_f32_e32 v44, v55, v44
	v_add_f32_e32 v44, v44, v45
	ds_bpermute_b32 v45, v48, v44
	s_waitcnt lgkmcnt(0)
	v_add_f32_e32 v44, v44, v45
	ds_bpermute_b32 v45, v49, v44
	s_waitcnt lgkmcnt(0)
	v_add_f32_e32 v44, v44, v45
	ds_bpermute_b32 v45, v50, v44
	s_waitcnt lgkmcnt(0)
	v_add_f32_e32 v44, v44, v45
	ds_bpermute_b32 v45, v51, v44
	s_waitcnt lgkmcnt(0)
	v_add_f32_e32 v44, v44, v45
	ds_bpermute_b32 v45, v52, v44
	s_waitcnt lgkmcnt(0)
	v_add_f32_e32 v44, v44, v45
	ds_bpermute_b32 v45, v53, v44
	s_waitcnt lgkmcnt(0)
	v_add_f32_e32 v44, v44, v45
	v_fmamk_f32 v44, v44, 0x3a800000, v54
	v_mul_f32_e32 v45, 0x4b800000, v44
	v_cmp_gt_f32_e32 vcc, s1, v44
	s_nop 1
	v_cndmask_b32_e32 v44, v44, v45, vcc
	v_rsq_f32_e32 v55, v44
	v_lshl_add_u64 v[44:45], s[14:15], 0, v[18:19]
	v_mul_f32_e32 v56, 0x45800000, v55
	v_cndmask_b32_e32 v56, v55, v56, vcc
	v_mul_f32_e32 v12, v12, v56
	v_mul_f32_e32 v13, v13, v56
	v_mul_f32_e32 v14, v14, v56
	v_mul_f32_e32 v15, v15, v56
	v_mul_f32_e32 v8, v8, v56
	v_mul_f32_e32 v9, v9, v56
	v_mul_f32_e32 v10, v10, v56
	v_mul_f32_e32 v11, v11, v56
	v_mul_f32_e32 v4, v4, v56
	v_mul_f32_e32 v5, v5, v56
	v_mul_f32_e32 v6, v6, v56
	v_mul_f32_e32 v7, v7, v56
	v_mul_f32_e32 v0, v0, v56
	v_mul_f32_e32 v1, v1, v56
	s_waitcnt vmcnt(2)
	v_mul_f32_e32 v12, v32, v12
	v_mul_f32_e32 v13, v33, v13
	s_waitcnt vmcnt(1)
	v_add_f32_e32 v32, 1.0, v36
	v_add_f32_e32 v33, 1.0, v37
	v_mul_f32_e32 v14, v34, v14
	v_mul_f32_e32 v15, v35, v15
	v_add_f32_e32 v34, 1.0, v38
	v_add_f32_e32 v35, 1.0, v39
	s_waitcnt vmcnt(0)
	v_fma_f32 v12, v32, v12, v40
	v_fma_f32 v13, v33, v13, v41
	v_fma_f32 v14, v34, v14, v42
	v_fma_f32 v15, v35, v15, v43
	v_cvt_pk_bf16_f32 v12, v12, v13
	v_cvt_pk_bf16_f32 v13, v14, v15
	global_store_dwordx2 v[44:45], v[12:13], off nt
	global_load_dwordx4 v[12:15], v[28:29], off offset:1024
	s_nop 0
	global_load_dwordx4 v[32:35], v[46:47], off offset:1024
	v_lshl_add_u64 v[40:41], v[30:31], 0, s[42:43]
	global_load_dwordx4 v[36:39], v[40:41], off offset:1024
	v_mul_f32_e32 v2, v2, v56
	v_mul_f32_e32 v3, v3, v56
	s_waitcnt vmcnt(2)
	v_mul_f32_e32 v8, v12, v8
	v_mul_f32_e32 v9, v13, v9
	s_waitcnt vmcnt(1)
	v_add_f32_e32 v12, 1.0, v32
	v_add_f32_e32 v13, 1.0, v33
	v_mul_f32_e32 v10, v10, v14
	v_mul_f32_e32 v11, v11, v15
	v_add_f32_e32 v14, 1.0, v34
	v_add_f32_e32 v15, 1.0, v35
	s_waitcnt vmcnt(0)
	v_fma_f32 v8, v8, v12, v36
	v_fma_f32 v9, v9, v13, v37
	v_fma_f32 v10, v10, v14, v38
	v_fma_f32 v11, v11, v15, v39
	v_cvt_pk_bf16_f32 v8, v8, v9
	v_cvt_pk_bf16_f32 v9, v10, v11
	global_store_dwordx2 v[44:45], v[8:9], off offset:512 nt
	global_load_dwordx4 v[8:11], v[28:29], off offset:2048
	s_nop 0
	global_load_dwordx4 v[12:15], v[46:47], off offset:2048
	global_load_dwordx4 v[30:33], v[40:41], off offset:2048
	s_waitcnt vmcnt(2)
	v_mul_f32_e32 v4, v4, v8
	v_mul_f32_e32 v5, v5, v9
	s_waitcnt vmcnt(1)
	v_add_f32_e32 v8, 1.0, v12
	v_add_f32_e32 v9, 1.0, v13
	v_mul_f32_e32 v6, v6, v10
	v_mul_f32_e32 v7, v7, v11
	v_add_f32_e32 v10, 1.0, v14
	v_add_f32_e32 v11, 1.0, v15
	s_waitcnt vmcnt(0)
	v_fma_f32 v4, v4, v8, v30
	v_fma_f32 v5, v5, v9, v31
	v_fma_f32 v6, v6, v10, v32
	v_fma_f32 v7, v7, v11, v33
	v_cvt_pk_bf16_f32 v4, v4, v5
	v_cvt_pk_bf16_f32 v5, v6, v7
	global_store_dwordx2 v[44:45], v[4:5], off offset:1024 nt
	global_load_dwordx4 v[4:7], v[28:29], off offset:3072
	s_nop 0
	global_load_dwordx4 v[8:11], v[46:47], off offset:3072
	global_load_dwordx4 v[12:15], v[40:41], off offset:3072
	s_waitcnt vmcnt(2)
	v_mul_f32_e32 v0, v0, v4
	v_mul_f32_e32 v1, v1, v5
	s_waitcnt vmcnt(1)
	v_add_f32_e32 v4, 1.0, v8
	v_add_f32_e32 v5, 1.0, v9
	v_mul_f32_e32 v2, v2, v6
	v_mul_f32_e32 v3, v3, v7
	v_add_f32_e32 v6, 1.0, v10
	v_add_f32_e32 v7, 1.0, v11
	s_waitcnt vmcnt(0)
	v_fma_f32 v0, v0, v4, v12
	v_fma_f32 v1, v1, v5, v13
	v_fma_f32 v2, v2, v6, v14
	v_fma_f32 v3, v3, v7, v15
	v_cvt_pk_bf16_f32 v0, v0, v1
	v_cvt_pk_bf16_f32 v1, v2, v3
	global_store_dwordx2 v[44:45], v[0:1], off offset:1536 nt
	s_branch .LBB0_310

.LBB0_350:
	s_bfe_u32 s4, s36, 0x20007
	s_waitcnt vmcnt(7)
	ds_write_b128 v46, v[0:3]
	s_waitcnt vmcnt(6)
	ds_write_b128 v46, v[4:7] offset:33792
	s_waitcnt vmcnt(5)
	ds_write_b128 v46, v[16:19] offset:8448
	s_waitcnt vmcnt(4)
	ds_write_b128 v46, v[8:11] offset:42240
	s_waitcnt vmcnt(3)
	ds_write_b128 v46, v[24:27] offset:16896
	s_waitcnt vmcnt(2)
	ds_write_b128 v46, v[12:15] offset:50688
	s_waitcnt vmcnt(1)
	ds_write_b128 v46, v[28:31] offset:25344
	s_waitcnt vmcnt(0)
	ds_write_b128 v46, v[20:23] offset:59136
	v_cvt_f32_ubyte0_e32 v26, s4
	v_sub_f32_e32 v26, 0xc0a00000, v26
	v_cmp_gt_f32_e32 vcc, s0, v26
	s_and_b64 s[4:5], vcc, exec
	s_cselect_b32 s6, 0xffffffc0, 0
	s_add_i32 s10, s36, s33
	v_cndmask_b32_e32 v27, 0, v50, vcc
	s_cmpk_lt_i32 s10, 0x800
	v_add_f32_e32 v26, v26, v27
	s_cselect_b64 s[4:5], -1, 0
	v_exp_f32_e32 v26, v26
	s_and_b64 vcc, s[4:5], exec
	s_waitcnt lgkmcnt(0)
	s_barrier
	ds_read_b128 v[0:3], v47
	ds_read_b128 v[4:7], v47 offset:64
	ds_read_b128 v[8:11], v48 offset:33792
	ds_read_b128 v[12:15], v48 offset:33856
	ds_read_b128 v[16:19], v49 offset:33792
	ds_read_b128 v[20:23], v49 offset:33856
	ds_read_b128 v[52:55], v47 offset:128
	ds_read_b128 v[56:59], v47 offset:192
	ds_read_b128 v[60:63], v48 offset:33920
	ds_read_b128 v[64:67], v48 offset:33984
	ds_read_b128 v[68:71], v49 offset:33920
	ds_read_b128 v[72:75], v49 offset:33984
	ds_read_b128 v[76:79], v47 offset:256
	ds_read_b128 v[80:83], v47 offset:320
	ds_read_b128 v[84:87], v48 offset:34048
	ds_read_b128 v[88:91], v48 offset:34112
	ds_read_b128 v[92:95], v49 offset:34048
	ds_read_b128 v[96:99], v49 offset:34112
	ds_read_b128 v[100:103], v47 offset:384
	ds_read_b128 v[104:107], v47 offset:448
	ds_read_b128 v[108:111], v48 offset:34176
	ds_read_b128 v[112:115], v48 offset:34240
	ds_read_b128 v[116:119], v49 offset:34176
	ds_read_b128 v[120:123], v49 offset:34240
	s_cselect_b32 s5, s10, s36
	s_waitcnt lgkmcnt(14)
	v_mfma_f32_16x16x32_bf16 v[8:11], v[8:11], v[0:3], 0
	s_ashr_i32 s4, s5, 9
	s_ashr_i32 s37, s36, 31
	s_lshl_b32 s11, s5, 6
	v_mfma_f32_16x16x32_bf16 v[0:3], v[16:19], v[0:3], 0
	s_lshl_b32 s12, s5, 2
	s_ashr_i32 s5, s4, 31
	v_ldexp_f32 v26, v26, s6
	s_lshl_b64 s[6:7], s[36:37], 13
	s_mov_b32 s36, s10
	s_and_b32 s10, s11, 0x1fc0
	s_lshl_b64 s[4:5], s[4:5], 13
	s_or_b32 s4, s4, s10
	v_mov_b64_e32 v[24:25], s[62:63]
	v_mfma_f32_16x16x32_bf16 v[128:131], v[20:23], v[4:7], v[0:3]
	s_and_b32 s24, s12, 0x600
	v_sub_f32_e32 v16, 1.0, v26
	v_log_f32_e32 v134, v16
	v_lshl_add_u64 v[0:1], s[4:5], 0, v[32:33]
	v_mad_u64_u32 v[2:3], s[4:5], v0, s1, v[24:25]
	v_mad_i32_i24 v3, v1, s1, v3
	v_lshl_add_u64 v[0:1], v[2:3], 0, s[24:25]
	v_mfma_f32_16x16x32_bf16 v[124:127], v[12:15], v[4:7], v[8:11]
	v_mul_f32_e32 v135, v134, v39
	v_mul_f32_e32 v136, v134, v40
	v_mul_f32_e32 v137, v134, v41
	v_lshl_add_u64 v[8:9], v[0:1], 0, v[34:35]
	v_add_co_u32_e64 v10, s[4:5], s27, v8
	global_load_dwordx4 v[0:3], v[8:9], off
	global_load_dwordx4 v[4:7], v[8:9], off offset:2048
	v_addc_co_u32_e64 v11, s[4:5], 0, v9, s[4:5]
	v_add_co_u32_e64 v12, s[4:5], s38, v8
	v_mfma_f32_16x16x32_bf16 v[60:63], v[60:63], v[52:55], v[124:127]
	s_nop 0
	v_addc_co_u32_e64 v13, s[4:5], 0, v9, s[4:5]
	v_add_co_u32_e64 v20, s[4:5], s39, v8
	s_waitcnt lgkmcnt(13)
	v_mfma_f32_16x16x32_bf16 v[52:55], v[68:71], v[52:55], v[128:131]
	v_addc_co_u32_e64 v21, s[4:5], 0, v9, s[4:5]
	global_load_dwordx4 v[16:19], v[10:11], off
	s_nop 0
	global_load_dwordx4 v[8:11], v[10:11], off offset:2048
	s_nop 0
	global_load_dwordx4 v[24:27], v[12:13], off
	s_nop 0
	global_load_dwordx4 v[12:15], v[12:13], off offset:2048
	s_nop 0
	global_load_dwordx4 v[28:31], v[20:21], off
	s_nop 0
	global_load_dwordx4 v[20:23], v[20:21], off offset:2048
	v_mfma_f32_16x16x32_bf16 v[60:63], v[64:67], v[56:59], v[60:63]
	v_mul_f32_e32 v138, v134, v42
	v_lshl_add_u64 v[132:133], v[36:37], 0, s[6:7]
	v_mul_f32_e32 v139, v134, v38
	s_waitcnt lgkmcnt(12)
	v_mfma_f32_16x16x32_bf16 v[52:55], v[72:75], v[56:59], v[52:55]
	v_mul_f32_e32 v140, v134, v43
	v_mul_f32_e32 v141, v134, v44
	v_mul_f32_e32 v142, v134, v45
	s_waitcnt lgkmcnt(9)
	v_mfma_f32_16x16x32_bf16 v[56:59], v[84:87], v[76:79], v[60:63]
	v_cmp_gt_f32_e64 s[4:5], s0, v135
	v_cmp_gt_f32_e64 s[6:7], s0, v136
	v_cmp_gt_f32_e64 s[10:11], s0, v137
	s_waitcnt lgkmcnt(7)
	v_mfma_f32_16x16x32_bf16 v[52:55], v[92:95], v[76:79], v[52:55]
	v_cmp_gt_f32_e64 s[12:13], s0, v138
	v_cndmask_b32_e64 v135, 0, v50, s[4:5]
	v_cndmask_b32_e64 v136, 0, v50, s[6:7]
	v_mfma_f32_16x16x32_bf16 v[56:59], v[88:91], v[80:83], v[56:59]
	v_cndmask_b32_e64 v137, 0, v50, s[10:11]
	v_cndmask_b32_e64 v138, 0, v50, s[12:13]
	v_cmp_gt_f32_e64 s[14:15], s0, v139
	s_waitcnt lgkmcnt(6)
	v_mfma_f32_16x16x32_bf16 v[52:55], v[96:99], v[80:83], v[52:55]
	v_cmp_gt_f32_e64 s[16:17], s0, v140
	v_cmp_gt_f32_e64 s[18:19], s0, v141
	v_cmp_gt_f32_e64 s[20:21], s0, v142
	s_waitcnt lgkmcnt(3)
	v_mfma_f32_16x16x32_bf16 v[56:59], v[108:111], v[100:103], v[56:59]
	v_cndmask_b32_e64 v139, 0, v50, s[14:15]
	v_cndmask_b32_e64 v140, 0, v50, s[16:17]
	v_cndmask_b32_e64 v124, 0, v50, s[18:19]
	s_waitcnt lgkmcnt(1)
	v_mfma_f32_16x16x32_bf16 v[52:55], v[116:119], v[100:103], v[52:55]
	v_cndmask_b32_e64 v125, 0, v50, s[20:21]
	v_fmac_f32_e32 v135, v134, v39
	v_fmac_f32_e32 v136, v134, v40
	v_fmac_f32_e32 v137, v134, v41
	v_fmac_f32_e32 v138, v134, v42
	v_fmac_f32_e32 v139, v134, v38
	v_fmac_f32_e32 v140, v134, v43
	v_fmac_f32_e32 v124, v134, v44
	v_fmac_f32_e32 v125, v134, v45
	v_exp_f32_e32 v60, v135
	v_exp_f32_e32 v61, v136
	v_exp_f32_e32 v62, v137
	v_exp_f32_e32 v63, v138
	v_exp_f32_e32 v72, v139
	v_exp_f32_e32 v73, v140
	v_exp_f32_e32 v74, v124
	v_exp_f32_e32 v75, v125
	v_mfma_f32_16x16x32_bf16 v[56:59], v[112:115], v[104:107], v[56:59]
	v_cndmask_b32_e64 v68, 0, v51, s[4:5]
	v_cndmask_b32_e64 v69, 0, v51, s[6:7]
	v_cndmask_b32_e64 v64, 0, v51, s[10:11]
	s_waitcnt lgkmcnt(0)
	v_mfma_f32_16x16x32_bf16 v[52:55], v[120:123], v[104:107], v[52:55]
	v_cndmask_b32_e64 v65, 0, v51, s[12:13]
	v_cndmask_b32_e64 v66, 0, v51, s[14:15]
	v_cndmask_b32_e64 v67, 0, v51, s[16:17]
	v_cndmask_b32_e64 v70, 0, v51, s[18:19]
	v_cndmask_b32_e64 v71, 0, v51, s[20:21]
	v_ldexp_f32 v60, v60, v68
	v_ldexp_f32 v61, v61, v69
	v_ldexp_f32 v62, v62, v64
	v_ldexp_f32 v63, v63, v65
	v_ldexp_f32 v64, v72, v66
	v_ldexp_f32 v65, v73, v67
	v_ldexp_f32 v66, v74, v70
	v_ldexp_f32 v67, v75, v71
	v_mul_f32_e32 v56, v60, v56
	v_mul_f32_e32 v57, v61, v57
	v_mul_f32_e32 v58, v62, v58
	v_mul_f32_e32 v59, v63, v59
	v_mul_f32_e32 v52, v64, v52
	v_mul_f32_e32 v53, v65, v53
	v_mul_f32_e32 v54, v66, v54
	v_mul_f32_e32 v55, v67, v55
	v_cvt_pk_bf16_f32 v56, v56, v57
	v_cvt_pk_bf16_f32 v57, v58, v59
	v_cvt_pk_bf16_f32 v52, v52, v53
	v_cvt_pk_bf16_f32 v53, v54, v55
	global_store_dwordx2 v[132:133], v[56:57], off
	global_store_dwordx2 v[132:133], v[52:53], off offset:32
	s_barrier
	s_cbranch_vccnz .LBB0_350

.LBB0_377:
	s_and_b32 s4, s0, 0xffffe000
	s_and_b32 s5, s21, 0xfff
	s_or_b32 s4, s4, s5
	s_mul_hi_i32 s5, s4, 0x3000
	s_mulk_i32 s4, 0x3000
	s_add_u32 s4, s62, s4
	s_addc_u32 s5, s63, s5
	v_lshl_add_u64 v[6:7], v[0:1], 1, s[4:5]
	v_lshl_add_u64 v[8:9], v[6:7], 0, s[14:15]
	v_lshl_add_u64 v[4:5], v[6:7], 0, s[16:17]
	v_add_co_u32_e32 v6, vcc, s19, v6
	global_load_dwordx4 v[16:19], v[8:9], off offset:1024 nt
	global_load_dwordx4 v[20:23], v[4:5], off offset:1024 nt
	global_load_dwordx4 v[24:27], v[8:9], off offset:2048 nt
	global_load_dwordx4 v[28:31], v[4:5], off offset:2048 nt
	global_load_dwordx4 v[32:35], v[8:9], off offset:3072 nt
	global_load_dwordx4 v[36:39], v[4:5], off offset:3072 nt
	v_addc_co_u32_e32 v7, vcc, 0, v7, vcc
	global_load_dwordx4 v[40:43], v[6:7], off offset:-4096 nt
	global_load_dwordx4 v[44:47], v[6:7], off nt
	s_add_i32 s21, s21, s82
	s_add_i32 s0, s0, s1
	s_cmpk_lt_i32 s21, 0x4000
	s_waitcnt vmcnt(7)
	v_lshlrev_b32_e32 v48, 16, v19
	v_and_b32_e32 v49, 0xffff0000, v19
	v_lshlrev_b32_e32 v50, 16, v18
	v_and_b32_e32 v51, 0xffff0000, v18
	s_waitcnt vmcnt(6)
	v_lshlrev_b32_e32 v18, 16, v22
	v_and_b32_e32 v19, 0xffff0000, v22
	v_lshlrev_b32_e32 v8, 16, v17
	v_and_b32_e32 v9, 0xffff0000, v17
	v_lshlrev_b32_e32 v52, 16, v21
	v_and_b32_e32 v53, 0xffff0000, v21
	v_lshlrev_b32_e32 v54, 16, v16
	v_and_b32_e32 v55, 0xffff0000, v16
	v_lshlrev_b32_e32 v16, 16, v20
	v_and_b32_e32 v17, 0xffff0000, v20
	v_lshlrev_b32_e32 v20, 16, v23
	v_and_b32_e32 v21, 0xffff0000, v23
	s_waitcnt vmcnt(5)
	v_lshlrev_b32_e32 v22, 16, v27
	v_and_b32_e32 v23, 0xffff0000, v27
	v_lshlrev_b32_e32 v56, 16, v26
	v_and_b32_e32 v57, 0xffff0000, v26
	s_waitcnt vmcnt(4)
	v_lshlrev_b32_e32 v26, 16, v30
	v_and_b32_e32 v27, 0xffff0000, v30
	v_lshlrev_b32_e32 v58, 16, v25
	v_and_b32_e32 v59, 0xffff0000, v25
	v_lshlrev_b32_e32 v60, 16, v29
	v_and_b32_e32 v61, 0xffff0000, v29
	v_lshlrev_b32_e32 v62, 16, v24
	v_and_b32_e32 v63, 0xffff0000, v24
	v_lshlrev_b32_e32 v24, 16, v28
	v_and_b32_e32 v25, 0xffff0000, v28
	v_lshlrev_b32_e32 v28, 16, v31
	v_and_b32_e32 v29, 0xffff0000, v31
	s_waitcnt vmcnt(3)
	v_lshlrev_b32_e32 v30, 16, v35
	v_and_b32_e32 v31, 0xffff0000, v35
	v_lshlrev_b32_e32 v64, 16, v34
	v_and_b32_e32 v65, 0xffff0000, v34
	s_waitcnt vmcnt(2)
	v_lshlrev_b32_e32 v34, 16, v38
	v_and_b32_e32 v35, 0xffff0000, v38
	v_lshlrev_b32_e32 v68, 16, v37
	v_and_b32_e32 v69, 0xffff0000, v37
	v_lshlrev_b32_e32 v66, 16, v33
	v_and_b32_e32 v67, 0xffff0000, v33
	v_lshlrev_b32_e32 v70, 16, v32
	v_and_b32_e32 v71, 0xffff0000, v32
	v_lshlrev_b32_e32 v32, 16, v36
	v_and_b32_e32 v33, 0xffff0000, v36
	v_lshlrev_b32_e32 v36, 16, v39
	v_and_b32_e32 v37, 0xffff0000, v39
	s_waitcnt vmcnt(1)
	v_lshlrev_b32_e32 v38, 16, v43
	v_and_b32_e32 v39, 0xffff0000, v43
	v_lshlrev_b32_e32 v72, 16, v42
	v_and_b32_e32 v73, 0xffff0000, v42
	s_waitcnt vmcnt(0)
	v_lshlrev_b32_e32 v42, 16, v46
	v_and_b32_e32 v43, 0xffff0000, v46
	v_lshlrev_b32_e32 v74, 16, v41
	v_and_b32_e32 v75, 0xffff0000, v41
	v_lshlrev_b32_e32 v76, 16, v45
	v_and_b32_e32 v77, 0xffff0000, v45
	v_lshlrev_b32_e32 v78, 16, v40
	v_and_b32_e32 v79, 0xffff0000, v40
	v_lshlrev_b32_e32 v40, 16, v44
	v_and_b32_e32 v41, 0xffff0000, v44
	v_lshlrev_b32_e32 v44, 16, v47
	v_and_b32_e32 v45, 0xffff0000, v47
	v_mul_f32_e32 v102, 0xbfb8aa3b, v18
	v_mul_f32_e32 v103, 0xbfb8aa3b, v19
	v_mul_f32_e32 v104, 0xbfb8aa3b, v52
	v_mul_f32_e32 v105, 0xbfb8aa3b, v53
	v_mul_f32_e32 v108, 0xbfb8aa3b, v20
	v_mul_f32_e32 v109, 0xbfb8aa3b, v21
	v_mul_f32_e32 v110, 0xbfb8aa3b, v26
	v_mul_f32_e32 v111, 0xbfb8aa3b, v27
	v_mul_f32_e32 v112, 0xbfb8aa3b, v60
	v_mul_f32_e32 v113, 0xbfb8aa3b, v61
	v_mul_f32_e32 v116, 0xbfb8aa3b, v28
	v_mul_f32_e32 v117, 0xbfb8aa3b, v29
	v_mul_f32_e32 v118, 0xbfb8aa3b, v34
	v_mul_f32_e32 v119, 0xbfb8aa3b, v35
	v_mul_f32_e32 v120, 0xbfb8aa3b, v68
	v_mul_f32_e32 v121, 0xbfb8aa3b, v69
	v_mul_f32_e32 v124, 0xbfb8aa3b, v36
	v_mul_f32_e32 v125, 0xbfb8aa3b, v37
	v_mul_f32_e32 v126, 0xbfb8aa3b, v42
	v_mul_f32_e32 v127, 0xbfb8aa3b, v43
	v_mul_f32_e32 v128, 0xbfb8aa3b, v76
	v_mul_f32_e32 v129, 0xbfb8aa3b, v77
	v_mul_f32_e32 v132, 0xbfb8aa3b, v44
	v_mul_f32_e32 v133, 0xbfb8aa3b, v45
	v_exp_f32_e32 v102, v102
	v_exp_f32_e32 v103, v103
	v_exp_f32_e32 v104, v104
	v_exp_f32_e32 v105, v105
	v_exp_f32_e32 v108, v108
	v_exp_f32_e32 v109, v109
	v_exp_f32_e32 v110, v110
	v_exp_f32_e32 v111, v111
	v_exp_f32_e32 v112, v112
	v_exp_f32_e32 v113, v113
	v_exp_f32_e32 v116, v116
	v_exp_f32_e32 v117, v117
	v_exp_f32_e32 v118, v118
	v_exp_f32_e32 v119, v119
	v_exp_f32_e32 v120, v120
	v_exp_f32_e32 v121, v121
	v_mov_b32_e32 v80, v49
	v_mov_b32_e32 v81, v51
	v_mul_f32_e32 v106, 0xbfb8aa3b, v16
	v_mul_f32_e32 v107, 0xbfb8aa3b, v17
	v_mov_b32_e32 v86, v23
	v_mov_b32_e32 v87, v57
	v_mov_b32_e32 v92, v31
	v_mov_b32_e32 v93, v65
	v_mov_b32_e32 v98, v39
	v_mov_b32_e32 v99, v73
	v_exp_f32_e32 v124, v124
	v_exp_f32_e32 v125, v125
	v_exp_f32_e32 v126, v126
	v_exp_f32_e32 v127, v127
	v_exp_f32_e32 v128, v128
	v_exp_f32_e32 v129, v129
	v_exp_f32_e32 v132, v132
	v_exp_f32_e32 v133, v133
	v_mov_b32_e32 v46, v48
	v_mov_b32_e32 v47, v50
	v_mov_b32_e32 v84, v22
	v_mov_b32_e32 v85, v56
	v_mov_b32_e32 v90, v30
	v_mov_b32_e32 v91, v64
	v_mov_b32_e32 v96, v38
	v_mov_b32_e32 v97, v72
	v_mul_f32_e32 v80, v80, v80
	v_mul_f32_e32 v81, v81, v81
	v_exp_f32_e32 v106, v106
	v_exp_f32_e32 v107, v107
	v_mul_f32_e32 v86, v86, v86
	v_mul_f32_e32 v87, v87, v87
	v_mul_f32_e32 v92, v92, v92
	v_mul_f32_e32 v93, v93, v93
	v_mul_f32_e32 v98, v98, v98
	v_mul_f32_e32 v99, v99, v99
	v_fma_f32 v46, v46, v46, v80
	v_fma_f32 v47, v47, v47, v81
	v_fma_f32 v80, v84, v84, v86
	v_fma_f32 v81, v85, v85, v87
	v_fma_f32 v84, v90, v90, v92
	v_fma_f32 v85, v91, v91, v93
	v_fma_f32 v86, v96, v96, v98
	v_fma_f32 v87, v97, v97, v99
	v_mov_b32_e32 v90, v47
	v_mov_b32_e32 v92, v85
	v_mov_b32_e32 v93, v81
	v_mov_b32_e32 v85, v80
	v_mov_b32_e32 v91, v87
	v_mov_b32_e32 v47, v86
	v_add_f32_e32 v80, 1.0, v102
	v_add_f32_e32 v81, 1.0, v103
	v_add_f32_e32 v86, 1.0, v104
	v_add_f32_e32 v87, 1.0, v105
	v_add_f32_e32 v98, 1.0, v108
	v_add_f32_e32 v99, 1.0, v109
	v_add_f32_e32 v102, 1.0, v110
	v_add_f32_e32 v103, 1.0, v111
	v_add_f32_e32 v104, 1.0, v112
	v_add_f32_e32 v105, 1.0, v113
	v_add_f32_e32 v108, 1.0, v116
	v_add_f32_e32 v109, 1.0, v117
	v_add_f32_e32 v110, 1.0, v118
	v_add_f32_e32 v111, 1.0, v119
	v_add_f32_e32 v112, 1.0, v120
	v_add_f32_e32 v113, 1.0, v121
	v_add_f32_e32 v116, 1.0, v124
	v_add_f32_e32 v117, 1.0, v125
	v_add_f32_e32 v118, 1.0, v126
	v_add_f32_e32 v119, 1.0, v127
	v_add_f32_e32 v120, 1.0, v128
	v_add_f32_e32 v121, 1.0, v129
	v_add_f32_e32 v124, 1.0, v132
	v_add_f32_e32 v125, 1.0, v133
	v_rcp_f32_e32 v98, v98
	v_rcp_f32_e32 v99, v99
	v_rcp_f32_e32 v104, v104
	v_rcp_f32_e32 v105, v105
	v_rcp_f32_e32 v108, v108
	v_rcp_f32_e32 v109, v109
	v_rcp_f32_e32 v110, v110
	v_rcp_f32_e32 v111, v111
	v_rcp_f32_e32 v112, v112
	v_rcp_f32_e32 v113, v113
	v_add_f32_e32 v96, 1.0, v106
	v_add_f32_e32 v97, 1.0, v107
	v_rcp_f32_e32 v80, v80
	v_rcp_f32_e32 v81, v81
	v_rcp_f32_e32 v86, v86
	v_rcp_f32_e32 v87, v87
	v_rcp_f32_e32 v116, v116
	v_rcp_f32_e32 v117, v117
	v_rcp_f32_e32 v118, v118
	v_rcp_f32_e32 v119, v119
	v_rcp_f32_e32 v120, v120
	v_rcp_f32_e32 v121, v121
	v_rcp_f32_e32 v124, v124
	v_rcp_f32_e32 v125, v125
	v_rcp_f32_e32 v96, v96
	v_rcp_f32_e32 v97, v97
	v_rcp_f32_e32 v102, v102
	v_rcp_f32_e32 v103, v103
	v_mul_f32_e32 v20, v98, v20
	v_mul_f32_e32 v21, v99, v21
	v_mul_f32_e32 v60, v104, v60
	v_mul_f32_e32 v61, v105, v61
	v_mul_f32_e32 v28, v108, v28
	v_mul_f32_e32 v29, v109, v29
	v_mul_f32_e32 v34, v110, v34
	v_mul_f32_e32 v35, v111, v35
	v_mul_f32_e32 v68, v112, v68
	v_mul_f32_e32 v69, v113, v69
	v_mov_b32_e32 v89, v58
	v_mov_b32_e32 v95, v66
	v_mul_f32_e32 v18, v80, v18
	v_mul_f32_e32 v19, v81, v19
	v_mul_f32_e32 v52, v86, v52
	v_mul_f32_e32 v53, v87, v53
	v_mul_f32_e32 v36, v116, v36
	v_mul_f32_e32 v37, v117, v37
	v_mul_f32_e32 v42, v118, v42
	v_mul_f32_e32 v43, v119, v43
	v_mul_f32_e32 v76, v120, v76
	v_mul_f32_e32 v77, v121, v77
	v_mul_f32_e32 v44, v124, v44
	v_mul_f32_e32 v45, v125, v45
	v_mul_f32_e32 v20, v20, v48
	v_mul_f32_e32 v21, v21, v49
	v_mul_f32_e32 v48, v60, v58
	v_mul_f32_e32 v49, v61, v59
	v_mov_b32_e32 v58, v63
	v_mul_f32_e32 v22, v28, v22
	v_mul_f32_e32 v23, v29, v23
	v_mul_f32_e32 v28, v34, v64
	v_mul_f32_e32 v29, v35, v65
	v_mul_f32_e32 v34, v68, v66
	v_mul_f32_e32 v35, v69, v67
	v_mov_b32_e32 v66, v71
	v_mov_b32_e32 v83, v8
	v_mov_b32_e32 v88, v62
	v_mov_b32_e32 v94, v70
	v_mov_b32_e32 v101, v74
	v_mul_f32_e32 v16, v96, v16
	v_mul_f32_e32 v17, v97, v17
	v_mul_f32_e32 v18, v18, v50
	v_mul_f32_e32 v19, v19, v51
	v_mul_f32_e32 v50, v52, v8
	v_mul_f32_e32 v51, v53, v9
	v_mov_b32_e32 v8, v55
	v_mul_f32_e32 v30, v36, v30
	v_mul_f32_e32 v31, v37, v31
	v_mul_f32_e32 v36, v42, v72
	v_mul_f32_e32 v37, v43, v73
	v_mul_f32_e32 v42, v76, v74
	v_mul_f32_e32 v43, v77, v75
	v_mov_b32_e32 v74, v79
	v_mul_f32_e32 v38, v44, v38
	v_mul_f32_e32 v39, v45, v39
	v_mul_f32_e32 v44, v58, v58
	v_mul_f32_e32 v45, v59, v59
	v_mul_f32_e32 v52, v66, v66
	v_mul_f32_e32 v53, v67, v67
	v_mov_b32_e32 v82, v54
	v_mov_b32_e32 v100, v78
	v_mul_f32_e32 v16, v16, v54
	v_mul_f32_e32 v17, v17, v55
	v_mul_f32_e32 v8, v8, v8
	v_mul_f32_e32 v9, v9, v9
	v_mul_f32_e32 v54, v74, v74
	v_mul_f32_e32 v55, v75, v75
	v_fma_f32 v44, v88, v88, v44
	v_fma_f32 v45, v89, v89, v45
	v_fma_f32 v52, v94, v94, v52
	v_fma_f32 v53, v95, v95, v53
	v_mul_f32_e32 v26, v102, v26
	v_mul_f32_e32 v27, v103, v27
	v_fma_f32 v8, v82, v82, v8
	v_fma_f32 v9, v83, v83, v9
	v_fma_f32 v54, v100, v100, v54
	v_fma_f32 v55, v101, v101, v55
	v_mov_b32_e32 v58, v52
	v_mov_b32_e32 v59, v44
	v_mov_b32_e32 v44, v53
	v_mul_f32_e32 v26, v26, v56
	v_mul_f32_e32 v27, v27, v57
	v_mov_b32_e32 v56, v8
	v_mov_b32_e32 v57, v54
	v_mov_b32_e32 v54, v9
	v_add_f32_e32 v8, v58, v44
	v_add_f32_e32 v9, v59, v45
	v_add_f32_e32 v44, v56, v54
	v_add_f32_e32 v45, v57, v55
	v_add_f32_e32 v8, v92, v8
	v_add_f32_e32 v9, v93, v9
	v_add_f32_e32 v44, v90, v44
	v_add_f32_e32 v45, v91, v45
	v_add_f32_e32 v8, v84, v8
	v_add_f32_e32 v9, v85, v9
	v_add_f32_e32 v44, v46, v44
	v_add_f32_e32 v45, v47, v45
	ds_bpermute_b32 v47, v10, v9
	ds_bpermute_b32 v46, v10, v8
	ds_bpermute_b32 v53, v10, v45
	ds_bpermute_b32 v52, v10, v44
	v_mul_f32_e32 v114, 0xbfb8aa3b, v24
	v_mul_f32_e32 v115, 0xbfb8aa3b, v25
	s_waitcnt lgkmcnt(2)
	v_add_f32_e32 v8, v8, v46
	v_add_f32_e32 v9, v9, v47
	ds_bpermute_b32 v47, v11, v9
	s_waitcnt lgkmcnt(1)
	v_add_f32_e32 v44, v44, v52
	v_add_f32_e32 v45, v45, v53
	ds_bpermute_b32 v46, v11, v8
	ds_bpermute_b32 v53, v11, v45
	ds_bpermute_b32 v52, v11, v44
	v_mul_f32_e32 v122, 0xbfb8aa3b, v32
	v_mul_f32_e32 v123, 0xbfb8aa3b, v33
	s_waitcnt lgkmcnt(2)
	v_add_f32_e32 v8, v8, v46
	v_add_f32_e32 v9, v9, v47
	ds_bpermute_b32 v47, v12, v9
	s_waitcnt lgkmcnt(1)
	v_add_f32_e32 v44, v44, v52
	v_add_f32_e32 v45, v45, v53
	ds_bpermute_b32 v46, v12, v8
	ds_bpermute_b32 v53, v12, v45
	ds_bpermute_b32 v52, v12, v44
	v_mul_f32_e32 v130, 0xbfb8aa3b, v40
	v_mul_f32_e32 v131, 0xbfb8aa3b, v41
	s_waitcnt lgkmcnt(2)
	v_add_f32_e32 v8, v8, v46
	v_add_f32_e32 v9, v9, v47
	ds_bpermute_b32 v47, v13, v9
	s_waitcnt lgkmcnt(1)
	v_add_f32_e32 v44, v44, v52
	v_add_f32_e32 v45, v45, v53
	ds_bpermute_b32 v46, v13, v8
	ds_bpermute_b32 v53, v13, v45
	ds_bpermute_b32 v52, v13, v44
	v_exp_f32_e32 v114, v114
	v_exp_f32_e32 v115, v115
	s_waitcnt lgkmcnt(2)
	v_add_f32_e32 v8, v8, v46
	v_add_f32_e32 v9, v9, v47
	ds_bpermute_b32 v47, v14, v9
	s_waitcnt lgkmcnt(1)
	v_add_f32_e32 v44, v44, v52
	v_add_f32_e32 v45, v45, v53
	ds_bpermute_b32 v46, v14, v8
	ds_bpermute_b32 v53, v14, v45
	ds_bpermute_b32 v52, v14, v44
	v_exp_f32_e32 v122, v122
	v_exp_f32_e32 v123, v123
	s_waitcnt lgkmcnt(2)
	v_add_f32_e32 v8, v8, v46
	v_add_f32_e32 v9, v9, v47
	ds_bpermute_b32 v47, v15, v9
	s_waitcnt lgkmcnt(1)
	v_add_f32_e32 v44, v44, v52
	v_add_f32_e32 v45, v45, v53
	ds_bpermute_b32 v46, v15, v8
	ds_bpermute_b32 v53, v15, v45
	ds_bpermute_b32 v52, v15, v44
	v_exp_f32_e32 v130, v130
	v_exp_f32_e32 v131, v131
	s_waitcnt lgkmcnt(2)
	v_add_f32_e32 v8, v8, v46
	v_add_f32_e32 v9, v9, v47
	v_add_f32_e32 v106, 1.0, v114
	s_waitcnt lgkmcnt(0)
	v_add_f32_e32 v44, v44, v52
	v_add_f32_e32 v45, v45, v53
	v_fma_f32 v8, v8, s18, v2
	v_fma_f32 v9, v9, s18, v2
	v_fma_f32 v44, v44, s18, v2
	v_fma_f32 v45, v45, s18, v2
	v_mul_f32_e32 v46, 0x4b800000, v9
	v_cmp_gt_f32_e64 s[4:5], s20, v9
	v_add_f32_e32 v107, 1.0, v115
	v_mul_f32_e32 v47, 0x4b800000, v8
	v_cmp_gt_f32_e32 vcc, s20, v8
	v_mul_f32_e32 v52, 0x4b800000, v45
	v_mul_f32_e32 v53, 0x4b800000, v44
	v_cmp_gt_f32_e64 s[6:7], s20, v44
	v_cndmask_b32_e64 v9, v9, v46, s[4:5]
	v_cmp_gt_f32_e64 s[10:11], s20, v45
	v_add_f32_e32 v114, 1.0, v122
	v_add_f32_e32 v115, 1.0, v123
	v_add_f32_e32 v122, 1.0, v130
	v_add_f32_e32 v123, 1.0, v131
	v_rcp_f32_e32 v106, v106
	v_rcp_f32_e32 v107, v107
	v_cndmask_b32_e32 v8, v8, v47, vcc
	v_cndmask_b32_e64 v45, v45, v52, s[10:11]
	v_cndmask_b32_e64 v44, v44, v53, s[6:7]
	v_rsq_f32_e32 v9, v9
	v_rcp_f32_e32 v114, v114
	v_rcp_f32_e32 v115, v115
	v_rcp_f32_e32 v122, v122
	v_rcp_f32_e32 v123, v123
	v_rsq_f32_e32 v46, v8
	v_rsq_f32_e32 v45, v45
	v_rsq_f32_e32 v47, v44
	v_mul_f32_e32 v24, v106, v24
	v_mul_f32_e32 v25, v107, v25
	v_mul_f32_e32 v8, 0x45800000, v9
	v_mul_f32_e32 v32, v114, v32
	v_mul_f32_e32 v33, v115, v33
	v_mul_f32_e32 v40, v122, v40
	v_mul_f32_e32 v41, v123, v41
	v_mul_f32_e32 v24, v24, v62
	v_mul_f32_e32 v25, v25, v63
	v_mul_f32_e32 v44, 0x45800000, v46
	v_mul_f32_e32 v52, 0x45800000, v45
	v_mul_f32_e32 v53, 0x45800000, v47
	v_cndmask_b32_e64 v8, v9, v8, s[4:5]
	v_mul_f32_e32 v32, v32, v70
	v_mul_f32_e32 v33, v33, v71
	v_mul_f32_e32 v40, v40, v78
	v_mul_f32_e32 v41, v41, v79
	v_cndmask_b32_e32 v44, v46, v44, vcc
	v_cndmask_b32_e64 v46, v45, v52, s[10:11]
	v_cndmask_b32_e64 v52, v47, v53, s[6:7]
	v_mul_f32_e32 v24, v24, v8
	v_mul_f32_e32 v25, v25, v8
	v_mul_f32_e32 v48, v48, v8
	v_mul_f32_e32 v49, v49, v8
	v_mul_f32_e32 v26, v26, v8
	v_mul_f32_e32 v27, v27, v8
	v_mul_f32_e32 v9, v23, v8
	v_mul_f32_e32 v8, v22, v8
	v_mul_f32_e32 v22, v32, v44
	v_mul_f32_e32 v23, v33, v44
	v_mul_f32_e32 v32, v34, v44
	v_mul_f32_e32 v33, v35, v44
	v_mul_f32_e32 v28, v28, v44
	v_mul_f32_e32 v29, v29, v44
	v_mul_f32_e32 v30, v30, v44
	v_mul_f32_e32 v31, v31, v44
	v_mul_f32_e32 v34, v40, v46
	v_mul_f32_e32 v35, v41, v46
	v_mul_f32_e32 v40, v42, v46
	v_mul_f32_e32 v41, v43, v46
	v_mul_f32_e32 v36, v36, v46
	v_mul_f32_e32 v37, v37, v46
	v_mul_f32_e32 v38, v38, v46
	v_mul_f32_e32 v39, v39, v46
	v_mul_f32_e32 v42, v16, v52
	v_mul_f32_e32 v43, v17, v52
	v_mul_f32_e32 v44, v50, v52
	v_mul_f32_e32 v45, v51, v52
	v_mul_f32_e32 v46, v18, v52
	v_mul_f32_e32 v47, v19, v52
	v_mul_f32_e32 v50, v20, v52
	v_mul_f32_e32 v51, v21, v52
	v_cvt_pk_bf16_f32 v16, v24, v25
	v_cvt_pk_bf16_f32 v17, v48, v49
	v_cvt_pk_bf16_f32 v18, v26, v27
	v_cvt_pk_bf16_f32 v19, v8, v9
	v_cvt_pk_bf16_f32 v20, v22, v23
	v_cvt_pk_bf16_f32 v21, v32, v33
	v_cvt_pk_bf16_f32 v22, v28, v29
	v_cvt_pk_bf16_f32 v23, v30, v31
	v_cvt_pk_bf16_f32 v24, v34, v35
	v_cvt_pk_bf16_f32 v25, v40, v41
	v_cvt_pk_bf16_f32 v26, v36, v37
	v_cvt_pk_bf16_f32 v27, v38, v39
	v_cvt_pk_bf16_f32 v28, v42, v43
	v_cvt_pk_bf16_f32 v29, v44, v45
	v_cvt_pk_bf16_f32 v30, v46, v47
	v_cvt_pk_bf16_f32 v31, v50, v51
	global_store_dwordx4 v[4:5], v[16:19], off offset:2048 nt
	global_store_dwordx4 v[4:5], v[20:23], off offset:3072 nt
	global_store_dwordx4 v[6:7], v[24:27], off nt
	global_store_dwordx4 v[4:5], v[28:31], off offset:1024 nt
	s_cbranch_scc1 .LBB0_377

.LBB0_395:
	s_and_b32 s6, s0, 0xffffe000
	s_and_b32 s7, s21, 0xfff
	s_or_b32 s6, s6, s7
	s_mul_hi_i32 s7, s6, 0x3000
	s_mulk_i32 s6, 0x3000
	s_add_u32 s6, s62, s6
	s_addc_u32 s7, s63, s7
	v_lshl_add_u64 v[6:7], v[0:1], 1, s[6:7]
	v_lshl_add_u64 v[8:9], v[6:7], 0, s[14:15]
	v_lshl_add_u64 v[4:5], v[6:7], 0, s[16:17]
	v_add_co_u32_e32 v6, vcc, s19, v6
	global_load_dwordx4 v[16:19], v[8:9], off offset:1024 nt
	global_load_dwordx4 v[20:23], v[4:5], off offset:1024 nt
	global_load_dwordx4 v[24:27], v[8:9], off offset:2048 nt
	global_load_dwordx4 v[28:31], v[4:5], off offset:2048 nt
	global_load_dwordx4 v[32:35], v[8:9], off offset:3072 nt
	global_load_dwordx4 v[36:39], v[4:5], off offset:3072 nt
	v_addc_co_u32_e32 v7, vcc, 0, v7, vcc
	global_load_dwordx4 v[40:43], v[6:7], off offset:-4096 nt
	global_load_dwordx4 v[44:47], v[6:7], off nt
	s_add_i32 s21, s21, s82
	s_add_i32 s0, s0, s1
	s_cmpk_lt_i32 s21, 0x4000
	s_waitcnt vmcnt(7)
	v_lshlrev_b32_e32 v48, 16, v19
	v_and_b32_e32 v49, 0xffff0000, v19
	v_lshlrev_b32_e32 v50, 16, v18
	v_and_b32_e32 v51, 0xffff0000, v18
	s_waitcnt vmcnt(6)
	v_lshlrev_b32_e32 v18, 16, v22
	v_and_b32_e32 v19, 0xffff0000, v22
	v_lshlrev_b32_e32 v8, 16, v17
	v_and_b32_e32 v9, 0xffff0000, v17
	v_lshlrev_b32_e32 v52, 16, v21
	v_and_b32_e32 v53, 0xffff0000, v21
	v_lshlrev_b32_e32 v54, 16, v16
	v_and_b32_e32 v55, 0xffff0000, v16
	v_lshlrev_b32_e32 v16, 16, v20
	v_and_b32_e32 v17, 0xffff0000, v20
	v_lshlrev_b32_e32 v20, 16, v23
	v_and_b32_e32 v21, 0xffff0000, v23
	s_waitcnt vmcnt(5)
	v_lshlrev_b32_e32 v22, 16, v27
	v_and_b32_e32 v23, 0xffff0000, v27
	v_lshlrev_b32_e32 v56, 16, v26
	v_and_b32_e32 v57, 0xffff0000, v26
	s_waitcnt vmcnt(4)
	v_lshlrev_b32_e32 v26, 16, v30
	v_and_b32_e32 v27, 0xffff0000, v30
	v_lshlrev_b32_e32 v58, 16, v25
	v_and_b32_e32 v59, 0xffff0000, v25
	v_lshlrev_b32_e32 v60, 16, v29
	v_and_b32_e32 v61, 0xffff0000, v29
	v_lshlrev_b32_e32 v62, 16, v24
	v_and_b32_e32 v63, 0xffff0000, v24
	v_lshlrev_b32_e32 v24, 16, v28
	v_and_b32_e32 v25, 0xffff0000, v28
	v_lshlrev_b32_e32 v28, 16, v31
	v_and_b32_e32 v29, 0xffff0000, v31
	s_waitcnt vmcnt(3)
	v_lshlrev_b32_e32 v30, 16, v35
	v_and_b32_e32 v31, 0xffff0000, v35
	v_lshlrev_b32_e32 v64, 16, v34
	v_and_b32_e32 v65, 0xffff0000, v34
	s_waitcnt vmcnt(2)
	v_lshlrev_b32_e32 v34, 16, v38
	v_and_b32_e32 v35, 0xffff0000, v38
	v_lshlrev_b32_e32 v68, 16, v37
	v_and_b32_e32 v69, 0xffff0000, v37
	v_lshlrev_b32_e32 v66, 16, v33
	v_and_b32_e32 v67, 0xffff0000, v33
	v_lshlrev_b32_e32 v70, 16, v32
	v_and_b32_e32 v71, 0xffff0000, v32
	v_lshlrev_b32_e32 v32, 16, v36
	v_and_b32_e32 v33, 0xffff0000, v36
	v_lshlrev_b32_e32 v36, 16, v39
	v_and_b32_e32 v37, 0xffff0000, v39
	s_waitcnt vmcnt(1)
	v_lshlrev_b32_e32 v38, 16, v43
	v_and_b32_e32 v39, 0xffff0000, v43
	v_lshlrev_b32_e32 v72, 16, v42
	v_and_b32_e32 v73, 0xffff0000, v42
	s_waitcnt vmcnt(0)
	v_lshlrev_b32_e32 v42, 16, v46
	v_and_b32_e32 v43, 0xffff0000, v46
	v_lshlrev_b32_e32 v74, 16, v41
	v_and_b32_e32 v75, 0xffff0000, v41
	v_lshlrev_b32_e32 v76, 16, v45
	v_and_b32_e32 v77, 0xffff0000, v45
	v_lshlrev_b32_e32 v78, 16, v40
	v_and_b32_e32 v79, 0xffff0000, v40
	v_lshlrev_b32_e32 v40, 16, v44
	v_and_b32_e32 v41, 0xffff0000, v44
	v_lshlrev_b32_e32 v44, 16, v47
	v_and_b32_e32 v45, 0xffff0000, v47
	v_mul_f32_e32 v102, 0xbfb8aa3b, v18
	v_mul_f32_e32 v103, 0xbfb8aa3b, v19
	v_mul_f32_e32 v104, 0xbfb8aa3b, v52
	v_mul_f32_e32 v105, 0xbfb8aa3b, v53
	v_mul_f32_e32 v108, 0xbfb8aa3b, v20
	v_mul_f32_e32 v109, 0xbfb8aa3b, v21
	v_mul_f32_e32 v110, 0xbfb8aa3b, v26
	v_mul_f32_e32 v111, 0xbfb8aa3b, v27
	v_mul_f32_e32 v112, 0xbfb8aa3b, v60
	v_mul_f32_e32 v113, 0xbfb8aa3b, v61
	v_mul_f32_e32 v116, 0xbfb8aa3b, v28
	v_mul_f32_e32 v117, 0xbfb8aa3b, v29
	v_mul_f32_e32 v118, 0xbfb8aa3b, v34
	v_mul_f32_e32 v119, 0xbfb8aa3b, v35
	v_mul_f32_e32 v120, 0xbfb8aa3b, v68
	v_mul_f32_e32 v121, 0xbfb8aa3b, v69
	v_mul_f32_e32 v124, 0xbfb8aa3b, v36
	v_mul_f32_e32 v125, 0xbfb8aa3b, v37
	v_mul_f32_e32 v126, 0xbfb8aa3b, v42
	v_mul_f32_e32 v127, 0xbfb8aa3b, v43
	v_mul_f32_e32 v128, 0xbfb8aa3b, v76
	v_mul_f32_e32 v129, 0xbfb8aa3b, v77
	v_mul_f32_e32 v132, 0xbfb8aa3b, v44
	v_mul_f32_e32 v133, 0xbfb8aa3b, v45
	v_exp_f32_e32 v102, v102
	v_exp_f32_e32 v103, v103
	v_exp_f32_e32 v104, v104
	v_exp_f32_e32 v105, v105
	v_exp_f32_e32 v108, v108
	v_exp_f32_e32 v109, v109
	v_exp_f32_e32 v110, v110
	v_exp_f32_e32 v111, v111
	v_exp_f32_e32 v112, v112
	v_exp_f32_e32 v113, v113
	v_exp_f32_e32 v116, v116
	v_exp_f32_e32 v117, v117
	v_exp_f32_e32 v118, v118
	v_exp_f32_e32 v119, v119
	v_exp_f32_e32 v120, v120
	v_exp_f32_e32 v121, v121
	v_mov_b32_e32 v80, v49
	v_mov_b32_e32 v81, v51
	v_mul_f32_e32 v106, 0xbfb8aa3b, v16
	v_mul_f32_e32 v107, 0xbfb8aa3b, v17
	v_mov_b32_e32 v86, v23
	v_mov_b32_e32 v87, v57
	v_mov_b32_e32 v92, v31
	v_mov_b32_e32 v93, v65
	v_mov_b32_e32 v98, v39
	v_mov_b32_e32 v99, v73
	v_exp_f32_e32 v124, v124
	v_exp_f32_e32 v125, v125
	v_exp_f32_e32 v126, v126
	v_exp_f32_e32 v127, v127
	v_exp_f32_e32 v128, v128
	v_exp_f32_e32 v129, v129
	v_exp_f32_e32 v132, v132
	v_exp_f32_e32 v133, v133
	v_mov_b32_e32 v46, v48
	v_mov_b32_e32 v47, v50
	v_mov_b32_e32 v84, v22
	v_mov_b32_e32 v85, v56
	v_mov_b32_e32 v90, v30
	v_mov_b32_e32 v91, v64
	v_mov_b32_e32 v96, v38
	v_mov_b32_e32 v97, v72
	v_mul_f32_e32 v80, v80, v80
	v_mul_f32_e32 v81, v81, v81
	v_exp_f32_e32 v106, v106
	v_exp_f32_e32 v107, v107
	v_mul_f32_e32 v86, v86, v86
	v_mul_f32_e32 v87, v87, v87
	v_mul_f32_e32 v92, v92, v92
	v_mul_f32_e32 v93, v93, v93
	v_mul_f32_e32 v98, v98, v98
	v_mul_f32_e32 v99, v99, v99
	v_fma_f32 v46, v46, v46, v80
	v_fma_f32 v47, v47, v47, v81
	v_fma_f32 v80, v84, v84, v86
	v_fma_f32 v81, v85, v85, v87
	v_fma_f32 v84, v90, v90, v92
	v_fma_f32 v85, v91, v91, v93
	v_fma_f32 v86, v96, v96, v98
	v_fma_f32 v87, v97, v97, v99
	v_mov_b32_e32 v90, v47
	v_mov_b32_e32 v92, v85
	v_mov_b32_e32 v93, v81
	v_mov_b32_e32 v85, v80
	v_mov_b32_e32 v91, v87
	v_mov_b32_e32 v47, v86
	v_add_f32_e32 v80, 1.0, v102
	v_add_f32_e32 v81, 1.0, v103
	v_add_f32_e32 v86, 1.0, v104
	v_add_f32_e32 v87, 1.0, v105
	v_add_f32_e32 v98, 1.0, v108
	v_add_f32_e32 v99, 1.0, v109
	v_add_f32_e32 v102, 1.0, v110
	v_add_f32_e32 v103, 1.0, v111
	v_add_f32_e32 v104, 1.0, v112
	v_add_f32_e32 v105, 1.0, v113
	v_add_f32_e32 v108, 1.0, v116
	v_add_f32_e32 v109, 1.0, v117
	v_add_f32_e32 v110, 1.0, v118
	v_add_f32_e32 v111, 1.0, v119
	v_add_f32_e32 v112, 1.0, v120
	v_add_f32_e32 v113, 1.0, v121
	v_add_f32_e32 v116, 1.0, v124
	v_add_f32_e32 v117, 1.0, v125
	v_add_f32_e32 v118, 1.0, v126
	v_add_f32_e32 v119, 1.0, v127
	v_add_f32_e32 v120, 1.0, v128
	v_add_f32_e32 v121, 1.0, v129
	v_add_f32_e32 v124, 1.0, v132
	v_add_f32_e32 v125, 1.0, v133
	v_rcp_f32_e32 v98, v98
	v_rcp_f32_e32 v99, v99
	v_rcp_f32_e32 v104, v104
	v_rcp_f32_e32 v105, v105
	v_rcp_f32_e32 v108, v108
	v_rcp_f32_e32 v109, v109
	v_rcp_f32_e32 v110, v110
	v_rcp_f32_e32 v111, v111
	v_rcp_f32_e32 v112, v112
	v_rcp_f32_e32 v113, v113
	v_add_f32_e32 v96, 1.0, v106
	v_add_f32_e32 v97, 1.0, v107
	v_rcp_f32_e32 v80, v80
	v_rcp_f32_e32 v81, v81
	v_rcp_f32_e32 v86, v86
	v_rcp_f32_e32 v87, v87
	v_rcp_f32_e32 v116, v116
	v_rcp_f32_e32 v117, v117
	v_rcp_f32_e32 v118, v118
	v_rcp_f32_e32 v119, v119
	v_rcp_f32_e32 v120, v120
	v_rcp_f32_e32 v121, v121
	v_rcp_f32_e32 v124, v124
	v_rcp_f32_e32 v125, v125
	v_rcp_f32_e32 v96, v96
	v_rcp_f32_e32 v97, v97
	v_rcp_f32_e32 v102, v102
	v_rcp_f32_e32 v103, v103
	v_mul_f32_e32 v20, v98, v20
	v_mul_f32_e32 v21, v99, v21
	v_mul_f32_e32 v60, v104, v60
	v_mul_f32_e32 v61, v105, v61
	v_mul_f32_e32 v28, v108, v28
	v_mul_f32_e32 v29, v109, v29
	v_mul_f32_e32 v34, v110, v34
	v_mul_f32_e32 v35, v111, v35
	v_mul_f32_e32 v68, v112, v68
	v_mul_f32_e32 v69, v113, v69
	v_mov_b32_e32 v89, v58
	v_mov_b32_e32 v95, v66
	v_mul_f32_e32 v18, v80, v18
	v_mul_f32_e32 v19, v81, v19
	v_mul_f32_e32 v52, v86, v52
	v_mul_f32_e32 v53, v87, v53
	v_mul_f32_e32 v36, v116, v36
	v_mul_f32_e32 v37, v117, v37
	v_mul_f32_e32 v42, v118, v42
	v_mul_f32_e32 v43, v119, v43
	v_mul_f32_e32 v76, v120, v76
	v_mul_f32_e32 v77, v121, v77
	v_mul_f32_e32 v44, v124, v44
	v_mul_f32_e32 v45, v125, v45
	v_mul_f32_e32 v20, v20, v48
	v_mul_f32_e32 v21, v21, v49
	v_mul_f32_e32 v48, v60, v58
	v_mul_f32_e32 v49, v61, v59
	v_mov_b32_e32 v58, v63
	v_mul_f32_e32 v22, v28, v22
	v_mul_f32_e32 v23, v29, v23
	v_mul_f32_e32 v28, v34, v64
	v_mul_f32_e32 v29, v35, v65
	v_mul_f32_e32 v34, v68, v66
	v_mul_f32_e32 v35, v69, v67
	v_mov_b32_e32 v66, v71
	v_mov_b32_e32 v83, v8
	v_mov_b32_e32 v88, v62
	v_mov_b32_e32 v94, v70
	v_mov_b32_e32 v101, v74
	v_mul_f32_e32 v16, v96, v16
	v_mul_f32_e32 v17, v97, v17
	v_mul_f32_e32 v18, v18, v50
	v_mul_f32_e32 v19, v19, v51
	v_mul_f32_e32 v50, v52, v8
	v_mul_f32_e32 v51, v53, v9
	v_mov_b32_e32 v8, v55
	v_mul_f32_e32 v30, v36, v30
	v_mul_f32_e32 v31, v37, v31
	v_mul_f32_e32 v36, v42, v72
	v_mul_f32_e32 v37, v43, v73
	v_mul_f32_e32 v42, v76, v74
	v_mul_f32_e32 v43, v77, v75
	v_mov_b32_e32 v74, v79
	v_mul_f32_e32 v38, v44, v38
	v_mul_f32_e32 v39, v45, v39
	v_mul_f32_e32 v44, v58, v58
	v_mul_f32_e32 v45, v59, v59
	v_mul_f32_e32 v52, v66, v66
	v_mul_f32_e32 v53, v67, v67
	v_mov_b32_e32 v82, v54
	v_mov_b32_e32 v100, v78
	v_mul_f32_e32 v16, v16, v54
	v_mul_f32_e32 v17, v17, v55
	v_mul_f32_e32 v8, v8, v8
	v_mul_f32_e32 v9, v9, v9
	v_mul_f32_e32 v54, v74, v74
	v_mul_f32_e32 v55, v75, v75
	v_fma_f32 v44, v88, v88, v44
	v_fma_f32 v45, v89, v89, v45
	v_fma_f32 v52, v94, v94, v52
	v_fma_f32 v53, v95, v95, v53
	v_mul_f32_e32 v26, v102, v26
	v_mul_f32_e32 v27, v103, v27
	v_fma_f32 v8, v82, v82, v8
	v_fma_f32 v9, v83, v83, v9
	v_fma_f32 v54, v100, v100, v54
	v_fma_f32 v55, v101, v101, v55
	v_mov_b32_e32 v58, v52
	v_mov_b32_e32 v59, v44
	v_mov_b32_e32 v44, v53
	v_mul_f32_e32 v26, v26, v56
	v_mul_f32_e32 v27, v27, v57
	v_mov_b32_e32 v56, v8
	v_mov_b32_e32 v57, v54
	v_mov_b32_e32 v54, v9
	v_add_f32_e32 v8, v58, v44
	v_add_f32_e32 v9, v59, v45
	v_add_f32_e32 v44, v56, v54
	v_add_f32_e32 v45, v57, v55
	v_add_f32_e32 v8, v92, v8
	v_add_f32_e32 v9, v93, v9
	v_add_f32_e32 v44, v90, v44
	v_add_f32_e32 v45, v91, v45
	v_add_f32_e32 v8, v84, v8
	v_add_f32_e32 v9, v85, v9
	v_add_f32_e32 v44, v46, v44
	v_add_f32_e32 v45, v47, v45
	ds_bpermute_b32 v47, v10, v9
	ds_bpermute_b32 v46, v10, v8
	ds_bpermute_b32 v53, v10, v45
	ds_bpermute_b32 v52, v10, v44
	v_mul_f32_e32 v114, 0xbfb8aa3b, v24
	v_mul_f32_e32 v115, 0xbfb8aa3b, v25
	s_waitcnt lgkmcnt(2)
	v_add_f32_e32 v8, v8, v46
	v_add_f32_e32 v9, v9, v47
	ds_bpermute_b32 v47, v11, v9
	s_waitcnt lgkmcnt(1)
	v_add_f32_e32 v44, v44, v52
	v_add_f32_e32 v45, v45, v53
	ds_bpermute_b32 v46, v11, v8
	ds_bpermute_b32 v53, v11, v45
	ds_bpermute_b32 v52, v11, v44
	v_mul_f32_e32 v122, 0xbfb8aa3b, v32
	v_mul_f32_e32 v123, 0xbfb8aa3b, v33
	s_waitcnt lgkmcnt(2)
	v_add_f32_e32 v8, v8, v46
	v_add_f32_e32 v9, v9, v47
	ds_bpermute_b32 v47, v12, v9
	s_waitcnt lgkmcnt(1)
	v_add_f32_e32 v44, v44, v52
	v_add_f32_e32 v45, v45, v53
	ds_bpermute_b32 v46, v12, v8
	ds_bpermute_b32 v53, v12, v45
	ds_bpermute_b32 v52, v12, v44
	v_mul_f32_e32 v130, 0xbfb8aa3b, v40
	v_mul_f32_e32 v131, 0xbfb8aa3b, v41
	s_waitcnt lgkmcnt(2)
	v_add_f32_e32 v8, v8, v46
	v_add_f32_e32 v9, v9, v47
	ds_bpermute_b32 v47, v13, v9
	s_waitcnt lgkmcnt(1)
	v_add_f32_e32 v44, v44, v52
	v_add_f32_e32 v45, v45, v53
	ds_bpermute_b32 v46, v13, v8
	ds_bpermute_b32 v53, v13, v45
	ds_bpermute_b32 v52, v13, v44
	v_exp_f32_e32 v114, v114
	v_exp_f32_e32 v115, v115
	s_waitcnt lgkmcnt(2)
	v_add_f32_e32 v8, v8, v46
	v_add_f32_e32 v9, v9, v47
	ds_bpermute_b32 v47, v14, v9
	s_waitcnt lgkmcnt(1)
	v_add_f32_e32 v44, v44, v52
	v_add_f32_e32 v45, v45, v53
	ds_bpermute_b32 v46, v14, v8
	ds_bpermute_b32 v53, v14, v45
	ds_bpermute_b32 v52, v14, v44
	v_exp_f32_e32 v122, v122
	v_exp_f32_e32 v123, v123
	s_waitcnt lgkmcnt(2)
	v_add_f32_e32 v8, v8, v46
	v_add_f32_e32 v9, v9, v47
	ds_bpermute_b32 v47, v15, v9
	s_waitcnt lgkmcnt(1)
	v_add_f32_e32 v44, v44, v52
	v_add_f32_e32 v45, v45, v53
	ds_bpermute_b32 v46, v15, v8
	ds_bpermute_b32 v53, v15, v45
	ds_bpermute_b32 v52, v15, v44
	v_exp_f32_e32 v130, v130
	v_exp_f32_e32 v131, v131
	s_waitcnt lgkmcnt(2)
	v_add_f32_e32 v8, v8, v46
	v_add_f32_e32 v9, v9, v47
	v_add_f32_e32 v106, 1.0, v114
	s_waitcnt lgkmcnt(0)
	v_add_f32_e32 v44, v44, v52
	v_add_f32_e32 v45, v45, v53
	v_fma_f32 v8, v8, s18, v2
	v_fma_f32 v9, v9, s18, v2
	v_fma_f32 v44, v44, s18, v2
	v_fma_f32 v45, v45, s18, v2
	v_mul_f32_e32 v46, 0x4b800000, v9
	v_cmp_gt_f32_e64 s[6:7], s20, v9
	v_add_f32_e32 v107, 1.0, v115
	v_mul_f32_e32 v47, 0x4b800000, v8
	v_cmp_gt_f32_e32 vcc, s20, v8
	v_mul_f32_e32 v52, 0x4b800000, v45
	v_mul_f32_e32 v53, 0x4b800000, v44
	v_cmp_gt_f32_e64 s[10:11], s20, v44
	v_cndmask_b32_e64 v9, v9, v46, s[6:7]
	v_cmp_gt_f32_e64 s[12:13], s20, v45
	v_add_f32_e32 v114, 1.0, v122
	v_add_f32_e32 v115, 1.0, v123
	v_add_f32_e32 v122, 1.0, v130
	v_add_f32_e32 v123, 1.0, v131
	v_rcp_f32_e32 v106, v106
	v_rcp_f32_e32 v107, v107
	v_cndmask_b32_e32 v8, v8, v47, vcc
	v_cndmask_b32_e64 v45, v45, v52, s[12:13]
	v_cndmask_b32_e64 v44, v44, v53, s[10:11]
	v_rsq_f32_e32 v9, v9
	v_rcp_f32_e32 v114, v114
	v_rcp_f32_e32 v115, v115
	v_rcp_f32_e32 v122, v122
	v_rcp_f32_e32 v123, v123
	v_rsq_f32_e32 v46, v8
	v_rsq_f32_e32 v45, v45
	v_rsq_f32_e32 v47, v44
	v_mul_f32_e32 v24, v106, v24
	v_mul_f32_e32 v25, v107, v25
	v_mul_f32_e32 v8, 0x45800000, v9
	v_mul_f32_e32 v32, v114, v32
	v_mul_f32_e32 v33, v115, v33
	v_mul_f32_e32 v40, v122, v40
	v_mul_f32_e32 v41, v123, v41
	v_mul_f32_e32 v24, v24, v62
	v_mul_f32_e32 v25, v25, v63
	v_mul_f32_e32 v44, 0x45800000, v46
	v_mul_f32_e32 v52, 0x45800000, v45
	v_mul_f32_e32 v53, 0x45800000, v47
	v_cndmask_b32_e64 v8, v9, v8, s[6:7]
	v_mul_f32_e32 v32, v32, v70
	v_mul_f32_e32 v33, v33, v71
	v_mul_f32_e32 v40, v40, v78
	v_mul_f32_e32 v41, v41, v79
	v_cndmask_b32_e32 v44, v46, v44, vcc
	v_cndmask_b32_e64 v46, v45, v52, s[12:13]
	v_cndmask_b32_e64 v52, v47, v53, s[10:11]
	v_mul_f32_e32 v24, v24, v8
	v_mul_f32_e32 v25, v25, v8
	v_mul_f32_e32 v48, v48, v8
	v_mul_f32_e32 v49, v49, v8
	v_mul_f32_e32 v26, v26, v8
	v_mul_f32_e32 v27, v27, v8
	v_mul_f32_e32 v9, v23, v8
	v_mul_f32_e32 v8, v22, v8
	v_mul_f32_e32 v22, v32, v44
	v_mul_f32_e32 v23, v33, v44
	v_mul_f32_e32 v32, v34, v44
	v_mul_f32_e32 v33, v35, v44
	v_mul_f32_e32 v28, v28, v44
	v_mul_f32_e32 v29, v29, v44
	v_mul_f32_e32 v30, v30, v44
	v_mul_f32_e32 v31, v31, v44
	v_mul_f32_e32 v34, v40, v46
	v_mul_f32_e32 v35, v41, v46
	v_mul_f32_e32 v40, v42, v46
	v_mul_f32_e32 v41, v43, v46
	v_mul_f32_e32 v36, v36, v46
	v_mul_f32_e32 v37, v37, v46
	v_mul_f32_e32 v38, v38, v46
	v_mul_f32_e32 v39, v39, v46
	v_mul_f32_e32 v42, v16, v52
	v_mul_f32_e32 v43, v17, v52
	v_mul_f32_e32 v44, v50, v52
	v_mul_f32_e32 v45, v51, v52
	v_mul_f32_e32 v46, v18, v52
	v_mul_f32_e32 v47, v19, v52
	v_mul_f32_e32 v50, v20, v52
	v_mul_f32_e32 v51, v21, v52
	v_cvt_pk_bf16_f32 v16, v24, v25
	v_cvt_pk_bf16_f32 v17, v48, v49
	v_cvt_pk_bf16_f32 v18, v26, v27
	v_cvt_pk_bf16_f32 v19, v8, v9
	v_cvt_pk_bf16_f32 v20, v22, v23
	v_cvt_pk_bf16_f32 v21, v32, v33
	v_cvt_pk_bf16_f32 v22, v28, v29
	v_cvt_pk_bf16_f32 v23, v30, v31
	v_cvt_pk_bf16_f32 v24, v34, v35
	v_cvt_pk_bf16_f32 v25, v40, v41
	v_cvt_pk_bf16_f32 v26, v36, v37
	v_cvt_pk_bf16_f32 v27, v38, v39
	v_cvt_pk_bf16_f32 v28, v42, v43
	v_cvt_pk_bf16_f32 v29, v44, v45
	v_cvt_pk_bf16_f32 v30, v46, v47
	v_cvt_pk_bf16_f32 v31, v50, v51
	global_store_dwordx4 v[4:5], v[16:19], off offset:2048 nt
	global_store_dwordx4 v[4:5], v[20:23], off offset:3072 nt
	global_store_dwordx4 v[6:7], v[24:27], off nt
	global_store_dwordx4 v[4:5], v[28:31], off offset:1024 nt
	s_cbranch_scc1 .LBB0_395

.LBB0_406:
	s_and_b32 s6, s19, 0xffffe000
	s_and_b32 s7, s23, 0xfff
	s_or_b32 s6, s7, s6
	s_bitset1_b32 s6, 12
	s_mul_hi_i32 s7, s6, 0x3000
	s_mulk_i32 s6, 0x3000
	s_add_u32 s6, s62, s6
	s_addc_u32 s7, s63, s7
	v_lshl_add_u64 v[0:1], s[6:7], 0, v[32:33]
	v_add_co_u32_e32 v38, vcc, s21, v0
	v_lshl_add_u64 v[12:13], v[0:1], 0, s[14:15]
	s_nop 0
	v_addc_co_u32_e32 v39, vcc, 0, v1, vcc
	s_cmpk_lt_i32 s23, 0x2000
	v_lshl_add_u64 v[36:37], v[0:1], 0, s[16:17]
	global_load_dwordx4 v[0:3], v[38:39], off offset:-4096 nt
	global_load_dwordx4 v[4:7], v[12:13], off offset:1024 nt
	global_load_dwordx4 v[8:11], v[12:13], off offset:2048 nt
	global_load_dwordx4 v[28:31], v[12:13], off offset:3072 nt
	global_load_dwordx4 v[24:27], v[38:39], off nt
	global_load_dwordx4 v[20:23], v[36:37], off offset:1024 nt
	global_load_dwordx4 v[16:19], v[36:37], off offset:2048 nt
	s_nop 0
	global_load_dwordx4 v[12:15], v[36:37], off offset:3072 nt
	s_cselect_b32 s7, s61, s44
	s_cselect_b32 s6, s60, s27
	s_and_b32 s10, s0, 0x1fff000
	s_add_u32 s6, s6, s10
	s_addc_u32 s7, s7, 0
	v_lshl_add_u64 v[40:41], s[6:7], 0, v[32:33]
	global_load_dwordx4 v[48:51], v[40:41], off nt
	global_load_dwordx4 v[52:55], v[40:41], off offset:1024 nt
	global_load_dwordx4 v[56:59], v[40:41], off offset:2048 nt
	global_load_dwordx4 v[60:63], v[40:41], off offset:3072 nt
	s_add_i32 s19, s19, s20
	s_add_i32 s23, s23, s82
	s_add_i32 s0, s0, s1
	s_cmpk_lt_i32 s23, 0x4000
	s_waitcnt vmcnt(11)
	v_lshlrev_b32_e32 v68, 16, v2
	v_and_b32_e32 v69, 0xffff0000, v2
	v_lshlrev_b32_e32 v70, 16, v3
	v_and_b32_e32 v71, 0xffff0000, v3
	s_waitcnt vmcnt(9)
	v_lshlrev_b32_e32 v84, 16, v10
	v_and_b32_e32 v85, 0xffff0000, v10
	v_lshlrev_b32_e32 v86, 16, v11
	v_and_b32_e32 v87, 0xffff0000, v11
	s_waitcnt vmcnt(7)
	v_lshlrev_b32_e32 v2, 16, v25
	v_and_b32_e32 v3, 0xffff0000, v25
	s_waitcnt vmcnt(6)
	v_lshlrev_b32_e32 v10, 16, v21
	v_and_b32_e32 v11, 0xffff0000, v21
	v_lshlrev_b32_e32 v64, 16, v0
	v_and_b32_e32 v65, 0xffff0000, v0
	v_lshlrev_b32_e32 v66, 16, v1
	v_and_b32_e32 v67, 0xffff0000, v1
	v_lshlrev_b32_e32 v72, 16, v4
	v_and_b32_e32 v73, 0xffff0000, v4
	v_lshlrev_b32_e32 v74, 16, v5
	v_and_b32_e32 v75, 0xffff0000, v5
	v_lshlrev_b32_e32 v76, 16, v6
	v_and_b32_e32 v77, 0xffff0000, v6
	v_lshlrev_b32_e32 v78, 16, v7
	v_and_b32_e32 v79, 0xffff0000, v7
	v_lshlrev_b32_e32 v80, 16, v8
	v_and_b32_e32 v81, 0xffff0000, v8
	v_lshlrev_b32_e32 v82, 16, v9
	v_and_b32_e32 v83, 0xffff0000, v9
	v_lshlrev_b32_e32 v88, 16, v28
	v_and_b32_e32 v89, 0xffff0000, v28
	v_lshlrev_b32_e32 v90, 16, v29
	v_and_b32_e32 v91, 0xffff0000, v29
	v_lshlrev_b32_e32 v92, 16, v30
	v_and_b32_e32 v93, 0xffff0000, v30
	v_lshlrev_b32_e32 v94, 16, v31
	v_and_b32_e32 v95, 0xffff0000, v31
	v_lshlrev_b32_e32 v0, 16, v26
	v_and_b32_e32 v1, 0xffff0000, v26
	v_lshlrev_b32_e32 v4, 16, v24
	v_and_b32_e32 v5, 0xffff0000, v24
	v_lshlrev_b32_e32 v6, 16, v27
	v_and_b32_e32 v7, 0xffff0000, v27
	v_lshlrev_b32_e32 v8, 16, v22
	v_and_b32_e32 v9, 0xffff0000, v22
	v_lshlrev_b32_e32 v24, 16, v20
	v_and_b32_e32 v25, 0xffff0000, v20
	v_lshlrev_b32_e32 v20, 16, v23
	v_and_b32_e32 v21, 0xffff0000, v23
	s_waitcnt vmcnt(5)
	v_lshlrev_b32_e32 v22, 16, v18
	v_and_b32_e32 v23, 0xffff0000, v18
	v_lshlrev_b32_e32 v26, 16, v17
	v_and_b32_e32 v27, 0xffff0000, v17
	v_lshlrev_b32_e32 v28, 16, v16
	v_and_b32_e32 v29, 0xffff0000, v16
	v_lshlrev_b32_e32 v16, 16, v19
	v_and_b32_e32 v17, 0xffff0000, v19
	s_waitcnt vmcnt(4)
	v_lshlrev_b32_e32 v18, 16, v14
	v_and_b32_e32 v19, 0xffff0000, v14
	v_lshlrev_b32_e32 v30, 16, v13
	v_and_b32_e32 v31, 0xffff0000, v13
	v_lshlrev_b32_e32 v40, 16, v12
	v_and_b32_e32 v41, 0xffff0000, v12
	v_mul_f32_e32 v96, 0xbfb8aa3b, v2
	v_mul_f32_e32 v97, 0xbfb8aa3b, v3
	v_mul_f32_e32 v104, 0xbfb8aa3b, v10
	v_mul_f32_e32 v105, 0xbfb8aa3b, v11
	v_lshlrev_b32_e32 v12, 16, v15
	v_and_b32_e32 v13, 0xffff0000, v15
	v_mul_f32_e32 v14, 0xbfb8aa3b, v0
	v_mul_f32_e32 v15, 0xbfb8aa3b, v1
	v_mul_f32_e32 v98, 0xbfb8aa3b, v4
	v_mul_f32_e32 v99, 0xbfb8aa3b, v5
	v_mul_f32_e32 v100, 0xbfb8aa3b, v6
	v_mul_f32_e32 v101, 0xbfb8aa3b, v7
	v_mul_f32_e32 v102, 0xbfb8aa3b, v8
	v_mul_f32_e32 v103, 0xbfb8aa3b, v9
	v_mul_f32_e32 v106, 0xbfb8aa3b, v24
	v_mul_f32_e32 v107, 0xbfb8aa3b, v25
	v_mul_f32_e32 v112, 0xbfb8aa3b, v26
	v_mul_f32_e32 v113, 0xbfb8aa3b, v27
	v_mul_f32_e32 v114, 0xbfb8aa3b, v28
	v_mul_f32_e32 v115, 0xbfb8aa3b, v29
	v_mul_f32_e32 v118, 0xbfb8aa3b, v18
	v_mul_f32_e32 v119, 0xbfb8aa3b, v19
	v_mul_f32_e32 v120, 0xbfb8aa3b, v30
	v_mul_f32_e32 v121, 0xbfb8aa3b, v31
	v_mul_f32_e32 v122, 0xbfb8aa3b, v40
	v_mul_f32_e32 v123, 0xbfb8aa3b, v41
	v_exp_f32_e32 v128, v96
	v_exp_f32_e32 v129, v97
	v_exp_f32_e32 v136, v104
	v_exp_f32_e32 v137, v105
	v_mul_f32_e32 v116, 0xbfb8aa3b, v16
	v_mul_f32_e32 v117, 0xbfb8aa3b, v17
	v_mul_f32_e32 v124, 0xbfb8aa3b, v12
	v_mul_f32_e32 v125, 0xbfb8aa3b, v13
	v_exp_f32_e32 v126, v14
	v_exp_f32_e32 v127, v15
	v_exp_f32_e32 v130, v98
	v_exp_f32_e32 v131, v99
	v_exp_f32_e32 v132, v100
	v_exp_f32_e32 v133, v101
	v_exp_f32_e32 v134, v102
	v_exp_f32_e32 v135, v103
	v_exp_f32_e32 v138, v106
	v_exp_f32_e32 v139, v107
	v_exp_f32_e32 v112, v112
	v_exp_f32_e32 v113, v113
	v_exp_f32_e32 v114, v114
	v_exp_f32_e32 v115, v115
	v_exp_f32_e32 v118, v118
	v_exp_f32_e32 v119, v119
	v_exp_f32_e32 v120, v120
	v_exp_f32_e32 v121, v121
	v_exp_f32_e32 v122, v122
	v_exp_f32_e32 v123, v123
	v_exp_f32_e32 v116, v116
	v_exp_f32_e32 v117, v117
	v_exp_f32_e32 v124, v124
	v_exp_f32_e32 v125, v125
	s_waitcnt vmcnt(3)
	v_lshlrev_b32_e32 v14, 16, v48
	v_and_b32_e32 v15, 0xffff0000, v48
	v_lshlrev_b32_e32 v48, 16, v49
	v_and_b32_e32 v49, 0xffff0000, v49
	s_waitcnt vmcnt(2)
	v_lshlrev_b32_e32 v98, 16, v52
	v_and_b32_e32 v99, 0xffff0000, v52
	s_waitcnt vmcnt(1)
	v_lshlrev_b32_e32 v104, 16, v58
	v_and_b32_e32 v105, 0xffff0000, v58
	v_lshlrev_b32_e32 v96, 16, v50
	v_and_b32_e32 v97, 0xffff0000, v50
	v_lshlrev_b32_e32 v50, 16, v51
	v_and_b32_e32 v51, 0xffff0000, v51
	v_lshlrev_b32_e32 v52, 16, v53
	v_and_b32_e32 v53, 0xffff0000, v53
	v_lshlrev_b32_e32 v102, 16, v56
	v_and_b32_e32 v103, 0xffff0000, v56
	v_lshlrev_b32_e32 v56, 16, v57
	v_and_b32_e32 v57, 0xffff0000, v57
	s_waitcnt vmcnt(0)
	v_lshlrev_b32_e32 v106, 16, v60
	v_and_b32_e32 v107, 0xffff0000, v60
	v_lshlrev_b32_e32 v60, 16, v61
	v_and_b32_e32 v61, 0xffff0000, v61
	v_add_f32_e32 v48, v66, v48
	v_add_f32_e32 v49, v67, v49
	v_add_f32_e32 v66, v72, v98
	v_add_f32_e32 v67, v73, v99
	v_add_f32_e32 v72, v84, v104
	v_add_f32_e32 v73, v85, v105
	v_add_f32_e32 v84, 1.0, v128
	v_add_f32_e32 v85, 1.0, v129
	v_add_f32_e32 v98, 1.0, v136
	v_add_f32_e32 v99, 1.0, v137
	v_add_f32_e32 v14, v64, v14
	v_add_f32_e32 v15, v65, v15
	v_add_f32_e32 v64, v68, v96
	v_add_f32_e32 v65, v69, v97
	v_add_f32_e32 v50, v70, v50
	v_add_f32_e32 v51, v71, v51
	v_add_f32_e32 v52, v74, v52
	v_add_f32_e32 v53, v75, v53
	v_add_f32_e32 v70, v80, v102
	v_add_f32_e32 v71, v81, v103
	v_add_f32_e32 v56, v82, v56
	v_add_f32_e32 v57, v83, v57
	v_add_f32_e32 v74, v88, v106
	v_add_f32_e32 v75, v89, v107
	v_add_f32_e32 v60, v90, v60
	v_add_f32_e32 v61, v91, v61
	v_add_f32_e32 v82, 1.0, v126
	v_add_f32_e32 v83, 1.0, v127
	v_add_f32_e32 v88, 1.0, v130
	v_add_f32_e32 v89, 1.0, v131
	v_add_f32_e32 v90, 1.0, v132
	v_add_f32_e32 v91, 1.0, v133
	v_add_f32_e32 v96, 1.0, v134
	v_add_f32_e32 v97, 1.0, v135
	v_add_f32_e32 v102, 1.0, v138
	v_add_f32_e32 v103, 1.0, v139
	v_add_f32_e32 v112, 1.0, v112
	v_add_f32_e32 v113, 1.0, v113
	v_add_f32_e32 v126, 1.0, v114
	v_add_f32_e32 v127, 1.0, v115
	v_add_f32_e32 v130, 1.0, v118
	v_add_f32_e32 v131, 1.0, v119
	v_add_f32_e32 v132, 1.0, v120
	v_add_f32_e32 v133, 1.0, v121
	v_add_f32_e32 v134, 1.0, v122
	v_add_f32_e32 v135, 1.0, v123
	v_rcp_f32_e32 v84, v84
	v_rcp_f32_e32 v85, v85
	v_rcp_f32_e32 v98, v98
	v_rcp_f32_e32 v99, v99
	v_add_f32_e32 v128, 1.0, v116
	v_add_f32_e32 v129, 1.0, v117
	v_add_f32_e32 v136, 1.0, v124
	v_add_f32_e32 v137, 1.0, v125
	v_rcp_f32_e32 v88, v88
	v_rcp_f32_e32 v89, v89
	v_rcp_f32_e32 v102, v102
	v_rcp_f32_e32 v103, v103
	v_rcp_f32_e32 v112, v112
	v_rcp_f32_e32 v113, v113
	v_rcp_f32_e32 v116, v126
	v_rcp_f32_e32 v117, v127
	v_rcp_f32_e32 v124, v130
	v_rcp_f32_e32 v125, v131
	v_rcp_f32_e32 v126, v132
	v_rcp_f32_e32 v127, v133
	v_rcp_f32_e32 v130, v134
	v_rcp_f32_e32 v131, v135
	v_mul_f32_e32 v108, 0xbfb8aa3b, v20
	v_mul_f32_e32 v109, 0xbfb8aa3b, v21
	v_lshlrev_b32_e32 v100, 16, v54
	v_and_b32_e32 v101, 0xffff0000, v54
	v_lshlrev_b32_e32 v54, 16, v55
	v_and_b32_e32 v55, 0xffff0000, v55
	v_lshlrev_b32_e32 v58, 16, v59
	v_and_b32_e32 v59, 0xffff0000, v59
	v_rcp_f32_e32 v82, v82
	v_rcp_f32_e32 v83, v83
	v_rcp_f32_e32 v90, v90
	v_rcp_f32_e32 v91, v91
	v_exp_f32_e32 v140, v108
	v_exp_f32_e32 v141, v109
	v_lshlrev_b32_e32 v108, 16, v62
	v_and_b32_e32 v109, 0xffff0000, v62
	v_lshlrev_b32_e32 v62, 16, v63
	v_and_b32_e32 v63, 0xffff0000, v63
	v_add_f32_e32 v68, v76, v100
	v_add_f32_e32 v69, v77, v101
	v_add_f32_e32 v54, v78, v54
	v_add_f32_e32 v55, v79, v55
	v_add_f32_e32 v58, v86, v58
	v_add_f32_e32 v59, v87, v59
	v_cvt_pk_bf16_f32 v15, v14, v15
	v_cvt_pk_bf16_f32 v49, v48, v49
	v_cvt_pk_bf16_f32 v66, v66, v67
	v_cvt_pk_bf16_f32 v67, v52, v53
	v_add_f32_e32 v76, v92, v108
	v_add_f32_e32 v77, v93, v109
	v_add_f32_e32 v62, v94, v62
	v_add_f32_e32 v63, v95, v63
	v_cvt_pk_bf16_f32 v64, v64, v65
	v_cvt_pk_bf16_f32 v65, v50, v51
	v_cvt_pk_bf16_f32 v68, v68, v69
	v_cvt_pk_bf16_f32 v69, v54, v55
	v_cvt_pk_bf16_f32 v70, v70, v71
	v_cvt_pk_bf16_f32 v71, v56, v57
	v_cvt_pk_bf16_f32 v72, v72, v73
	v_cvt_pk_bf16_f32 v73, v58, v59
	v_cvt_pk_bf16_f32 v74, v74, v75
	v_cvt_pk_bf16_f32 v75, v60, v61
	v_lshlrev_b32_e32 v14, 16, v15
	v_and_b32_e32 v15, 0xffff0000, v15
	v_lshlrev_b32_e32 v48, 16, v49
	v_and_b32_e32 v49, 0xffff0000, v49
	v_and_b32_e32 v55, 0xffff0000, v66
	v_lshlrev_b32_e32 v56, 16, v67
	v_and_b32_e32 v57, 0xffff0000, v67
	v_mul_f32_e32 v2, v84, v2
	v_mul_f32_e32 v3, v85, v3
	v_mul_f32_e32 v10, v98, v10
	v_mul_f32_e32 v11, v99, v11
	v_cvt_pk_bf16_f32 v76, v76, v77
	v_cvt_pk_bf16_f32 v77, v62, v63
	v_lshlrev_b32_e32 v50, 16, v64
	v_and_b32_e32 v51, 0xffff0000, v64
	v_lshlrev_b32_e32 v52, 16, v65
	v_and_b32_e32 v53, 0xffff0000, v65
	v_lshlrev_b32_e32 v54, 16, v66
	v_lshlrev_b32_e32 v58, 16, v68
	v_and_b32_e32 v59, 0xffff0000, v68
	v_lshlrev_b32_e32 v60, 16, v69
	v_and_b32_e32 v61, 0xffff0000, v69
	v_lshlrev_b32_e32 v62, 16, v70
	v_and_b32_e32 v63, 0xffff0000, v70
	v_lshlrev_b32_e32 v64, 16, v71
	v_and_b32_e32 v65, 0xffff0000, v71
	v_lshlrev_b32_e32 v66, 16, v72
	v_and_b32_e32 v67, 0xffff0000, v72
	v_lshlrev_b32_e32 v68, 16, v73
	v_and_b32_e32 v69, 0xffff0000, v73
	v_lshlrev_b32_e32 v70, 16, v74
	v_and_b32_e32 v71, 0xffff0000, v74
	v_lshlrev_b32_e32 v72, 16, v75
	v_and_b32_e32 v73, 0xffff0000, v75
	v_mov_b32_e32 v87, v48
	v_mov_b32_e32 v101, v56
	v_mul_f32_e32 v4, v88, v4
	v_mul_f32_e32 v5, v89, v5
	v_mul_f32_e32 v24, v102, v24
	v_mul_f32_e32 v25, v103, v25
	v_mul_f32_e32 v26, v112, v26
	v_mul_f32_e32 v27, v113, v27
	v_mul_f32_e32 v28, v116, v28
	v_mul_f32_e32 v29, v117, v29
	v_mul_f32_e32 v30, v126, v30
	v_mul_f32_e32 v31, v127, v31
	v_mul_f32_e32 v40, v130, v40
	v_mul_f32_e32 v41, v131, v41
	v_mul_f32_e32 v2, v2, v48
	v_mul_f32_e32 v3, v3, v49
	v_mov_b32_e32 v48, v15
	v_mul_f32_e32 v10, v10, v56
	v_mul_f32_e32 v11, v11, v57
	v_mov_b32_e32 v56, v55
	v_lshlrev_b32_e32 v74, 16, v76
	v_and_b32_e32 v75, 0xffff0000, v76
	v_lshlrev_b32_e32 v76, 16, v77
	v_and_b32_e32 v77, 0xffff0000, v77
	v_mov_b32_e32 v80, v53
	v_mov_b32_e32 v81, v51
	v_mov_b32_e32 v86, v14
	v_mov_b32_e32 v94, v61
	v_mov_b32_e32 v95, v59
	v_mov_b32_e32 v100, v54
	v_mov_b32_e32 v115, v64
	v_rcp_f32_e32 v119, v129
	v_mov_b32_e32 v129, v72
	v_mul_f32_e32 v0, v82, v0
	v_mul_f32_e32 v1, v83, v1
	v_mul_f32_e32 v6, v90, v6
	v_mul_f32_e32 v7, v91, v7
	v_mul_f32_e32 v4, v4, v14
	v_mul_f32_e32 v5, v5, v15
	v_mul_f32_e32 v14, v24, v54
	v_mul_f32_e32 v15, v25, v55
	v_mul_f32_e32 v24, v26, v64
	v_mul_f32_e32 v25, v27, v65
	v_mov_b32_e32 v64, v63
	v_mul_f32_e32 v26, v28, v62
	v_mul_f32_e32 v27, v29, v63
	v_mul_f32_e32 v28, v30, v72
	v_mul_f32_e32 v29, v31, v73
	v_mov_b32_e32 v72, v71
	v_mul_f32_e32 v30, v40, v70
	v_mul_f32_e32 v31, v41, v71
	v_mul_f32_e32 v40, v48, v48
	v_mul_f32_e32 v41, v49, v49
	v_mul_f32_e32 v48, v56, v56
	v_mul_f32_e32 v49, v57, v57
	v_mov_b32_e32 v78, v52
	v_mov_b32_e32 v79, v50
	v_mov_b32_e32 v92, v60
	v_mov_b32_e32 v93, v58
	v_mov_b32_e32 v108, v69
	v_mov_b32_e32 v109, v67
	v_mov_b32_e32 v114, v62
	v_rcp_f32_e32 v118, v128
	v_mov_b32_e32 v122, v77
	v_mov_b32_e32 v123, v75
	v_mov_b32_e32 v128, v70
	v_mul_f32_e32 v80, v80, v80
	v_mul_f32_e32 v81, v81, v81
	v_mul_f32_e32 v94, v94, v94
	v_mul_f32_e32 v95, v95, v95
	v_mul_f32_e32 v0, v0, v50
	v_mul_f32_e32 v1, v1, v51
	v_mul_f32_e32 v6, v6, v52
	v_mul_f32_e32 v7, v7, v53
	v_mul_f32_e32 v50, v64, v64
	v_mul_f32_e32 v51, v65, v65
	v_mul_f32_e32 v52, v72, v72
	v_mul_f32_e32 v53, v73, v73
	v_fma_f32 v40, v86, v86, v40
	v_fma_f32 v41, v87, v87, v41
	v_fma_f32 v48, v100, v100, v48
	v_fma_f32 v49, v101, v101, v49
	v_mov_b32_e32 v106, v68
	v_mov_b32_e32 v107, v66
	v_mov_b32_e32 v120, v76
	v_mov_b32_e32 v121, v74
	v_mul_f32_e32 v108, v108, v108
	v_mul_f32_e32 v109, v109, v109
	v_mul_f32_e32 v122, v122, v122
	v_mul_f32_e32 v123, v123, v123
	v_fma_f32 v78, v78, v78, v80
	v_fma_f32 v79, v79, v79, v81
	v_fma_f32 v80, v92, v92, v94
	v_fma_f32 v81, v93, v93, v95
	v_fma_f32 v50, v114, v114, v50
	v_fma_f32 v51, v115, v115, v51
	v_fma_f32 v52, v128, v128, v52
	v_fma_f32 v53, v129, v129, v53
	v_mov_b32_e32 v54, v48
	v_mov_b32_e32 v55, v40
	v_mov_b32_e32 v40, v49
	v_fma_f32 v92, v106, v106, v108
	v_fma_f32 v93, v107, v107, v109
	v_fma_f32 v94, v120, v120, v122
	v_fma_f32 v95, v121, v121, v123
	v_mov_b32_e32 v106, v81
	v_mov_b32_e32 v107, v79
	v_mov_b32_e32 v48, v52
	v_mov_b32_e32 v49, v50
	v_mov_b32_e32 v50, v53
	v_add_f32_e32 v40, v54, v40
	v_add_f32_e32 v41, v55, v41
	v_mov_b32_e32 v81, v78
	v_mov_b32_e32 v78, v95
	v_mov_b32_e32 v79, v93
	v_add_f32_e32 v48, v48, v50
	v_add_f32_e32 v49, v49, v51
	v_add_f32_e32 v40, v106, v40
	v_add_f32_e32 v41, v107, v41
	v_mov_b32_e32 v95, v92
	v_add_f32_e32 v48, v78, v48
	v_add_f32_e32 v49, v79, v49
	v_add_f32_e32 v40, v80, v40
	v_add_f32_e32 v41, v81, v41
	v_add_f32_e32 v48, v94, v48
	v_add_f32_e32 v49, v95, v49
	ds_bpermute_b32 v51, v42, v41
	ds_bpermute_b32 v50, v42, v40
	ds_bpermute_b32 v53, v42, v49
	ds_bpermute_b32 v52, v42, v48
	v_mul_f32_e32 v110, 0xbfb8aa3b, v22
	v_mul_f32_e32 v111, 0xbfb8aa3b, v23
	s_waitcnt lgkmcnt(2)
	v_add_f32_e32 v40, v40, v50
	v_add_f32_e32 v41, v41, v51
	ds_bpermute_b32 v51, v43, v41
	s_waitcnt lgkmcnt(1)
	v_add_f32_e32 v48, v48, v52
	v_add_f32_e32 v49, v49, v53
	ds_bpermute_b32 v50, v43, v40
	ds_bpermute_b32 v53, v43, v49
	ds_bpermute_b32 v52, v43, v48
	v_exp_f32_e32 v110, v110
	v_exp_f32_e32 v111, v111
	s_waitcnt lgkmcnt(2)
	v_add_f32_e32 v40, v40, v50
	v_add_f32_e32 v41, v41, v51
	ds_bpermute_b32 v51, v44, v41
	s_waitcnt lgkmcnt(1)
	v_add_f32_e32 v48, v48, v52
	v_add_f32_e32 v49, v49, v53
	ds_bpermute_b32 v50, v44, v40
	ds_bpermute_b32 v53, v44, v49
	ds_bpermute_b32 v52, v44, v48
	v_add_f32_e32 v104, 1.0, v140
	v_add_f32_e32 v105, 1.0, v141
	s_waitcnt lgkmcnt(2)
	v_add_f32_e32 v40, v40, v50
	v_add_f32_e32 v41, v41, v51
	ds_bpermute_b32 v51, v45, v41
	s_waitcnt lgkmcnt(1)
	v_add_f32_e32 v48, v48, v52
	v_add_f32_e32 v49, v49, v53
	ds_bpermute_b32 v50, v45, v40
	ds_bpermute_b32 v53, v45, v49
	ds_bpermute_b32 v52, v45, v48
	v_add_f32_e32 v110, 1.0, v110
	v_add_f32_e32 v111, 1.0, v111
	s_waitcnt lgkmcnt(2)
	v_add_f32_e32 v40, v40, v50
	v_add_f32_e32 v41, v41, v51
	ds_bpermute_b32 v51, v46, v41
	s_waitcnt lgkmcnt(1)
	v_add_f32_e32 v48, v48, v52
	v_add_f32_e32 v49, v49, v53
	ds_bpermute_b32 v50, v46, v40
	ds_bpermute_b32 v53, v46, v49
	ds_bpermute_b32 v52, v46, v48
	v_rcp_f32_e32 v96, v96
	v_rcp_f32_e32 v97, v97
	s_waitcnt lgkmcnt(2)
	v_add_f32_e32 v40, v40, v50
	v_add_f32_e32 v41, v41, v51
	ds_bpermute_b32 v51, v47, v41
	s_waitcnt lgkmcnt(1)
	v_add_f32_e32 v48, v48, v52
	v_add_f32_e32 v49, v49, v53
	ds_bpermute_b32 v50, v47, v40
	ds_bpermute_b32 v53, v47, v49
	ds_bpermute_b32 v52, v47, v48
	v_rcp_f32_e32 v104, v104
	v_rcp_f32_e32 v105, v105
	s_waitcnt lgkmcnt(2)
	v_add_f32_e32 v40, v40, v50
	v_add_f32_e32 v41, v41, v51
	v_rcp_f32_e32 v110, v110
	s_waitcnt lgkmcnt(0)
	v_add_f32_e32 v48, v48, v52
	v_add_f32_e32 v49, v49, v53
	v_fma_f32 v40, v40, s18, v34
	v_fma_f32 v41, v41, s18, v34
	v_fma_f32 v48, v48, s18, v34
	v_fma_f32 v49, v49, s18, v34
	v_mul_f32_e32 v50, 0x4b800000, v41
	v_cmp_gt_f32_e64 s[12:13], s22, v41
	v_mul_f32_e32 v51, 0x4b800000, v40
	v_cmp_gt_f32_e32 vcc, s22, v40
	v_mul_f32_e32 v52, 0x4b800000, v49
	v_mul_f32_e32 v53, 0x4b800000, v48
	v_cmp_gt_f32_e64 s[6:7], s22, v48
	v_cmp_gt_f32_e64 s[10:11], s22, v49
	v_cndmask_b32_e64 v41, v41, v50, s[12:13]
	v_cndmask_b32_e32 v40, v40, v51, vcc
	v_cndmask_b32_e64 v49, v49, v52, s[10:11]
	v_cndmask_b32_e64 v48, v48, v53, s[6:7]
	v_rsq_f32_e32 v41, v41
	v_rcp_f32_e32 v111, v111
	v_rcp_f32_e32 v132, v136
	v_rcp_f32_e32 v133, v137
	v_rsq_f32_e32 v50, v40
	v_rsq_f32_e32 v49, v49
	v_rsq_f32_e32 v51, v48
	v_mul_f32_e32 v40, 0x45800000, v41
	v_mul_f32_e32 v8, v96, v8
	v_mul_f32_e32 v9, v97, v9
	v_mul_f32_e32 v20, v104, v20
	v_mul_f32_e32 v21, v105, v21
	v_mul_f32_e32 v22, v110, v22
	v_mul_f32_e32 v23, v111, v23
	v_mul_f32_e32 v16, v118, v16
	v_mul_f32_e32 v17, v119, v17
	v_mul_f32_e32 v18, v124, v18
	v_mul_f32_e32 v19, v125, v19
	v_mul_f32_e32 v12, v132, v12
	v_mul_f32_e32 v13, v133, v13
	v_mul_f32_e32 v48, 0x45800000, v50
	v_mul_f32_e32 v52, 0x45800000, v49
	v_mul_f32_e32 v53, 0x45800000, v51
	v_cndmask_b32_e64 v40, v41, v40, s[12:13]
	v_mul_f32_e32 v8, v8, v58
	v_mul_f32_e32 v9, v9, v59
	v_mul_f32_e32 v20, v20, v60
	v_mul_f32_e32 v21, v21, v61
	v_mul_f32_e32 v22, v22, v66
	v_mul_f32_e32 v23, v23, v67
	v_mul_f32_e32 v16, v16, v68
	v_mul_f32_e32 v17, v17, v69
	v_mul_f32_e32 v18, v18, v74
	v_mul_f32_e32 v19, v19, v75
	v_mul_f32_e32 v12, v12, v76
	v_mul_f32_e32 v13, v13, v77
	v_cndmask_b32_e32 v48, v50, v48, vcc
	v_cndmask_b32_e64 v50, v49, v52, s[10:11]
	v_cndmask_b32_e64 v52, v51, v53, s[6:7]
	v_mul_f32_e32 v4, v4, v40
	v_mul_f32_e32 v5, v5, v40
	v_mul_f32_e32 v2, v2, v40
	v_mul_f32_e32 v3, v3, v40
	v_mul_f32_e32 v54, v0, v40
	v_mul_f32_e32 v55, v1, v40
	v_mul_f32_e32 v6, v6, v40
	v_mul_f32_e32 v7, v7, v40
	v_mul_f32_e32 v14, v14, v48
	v_mul_f32_e32 v15, v15, v48
	v_mul_f32_e32 v10, v10, v48
	v_mul_f32_e32 v11, v11, v48
	v_mul_f32_e32 v8, v8, v48
	v_mul_f32_e32 v9, v9, v48
	v_mul_f32_e32 v20, v20, v48
	v_mul_f32_e32 v21, v21, v48
	v_mul_f32_e32 v26, v26, v50
	v_mul_f32_e32 v27, v27, v50
	v_mul_f32_e32 v24, v24, v50
	v_mul_f32_e32 v25, v25, v50
	v_mul_f32_e32 v22, v22, v50
	v_mul_f32_e32 v23, v23, v50
	v_mul_f32_e32 v16, v16, v50
	v_mul_f32_e32 v17, v17, v50
	v_mul_f32_e32 v30, v30, v52
	v_mul_f32_e32 v31, v31, v52
	v_mul_f32_e32 v28, v28, v52
	v_mul_f32_e32 v29, v29, v52
	v_mul_f32_e32 v18, v18, v52
	v_mul_f32_e32 v19, v19, v52
	v_mul_f32_e32 v40, v12, v52
	v_mul_f32_e32 v41, v13, v52
	v_cvt_pk_bf16_f32 v0, v4, v5
	v_cvt_pk_bf16_f32 v1, v2, v3
	v_cvt_pk_bf16_f32 v2, v54, v55
	v_cvt_pk_bf16_f32 v3, v6, v7
	v_cvt_pk_bf16_f32 v4, v14, v15
	v_cvt_pk_bf16_f32 v5, v10, v11
	v_cvt_pk_bf16_f32 v6, v8, v9
	v_cvt_pk_bf16_f32 v7, v20, v21
	v_cvt_pk_bf16_f32 v8, v26, v27
	v_cvt_pk_bf16_f32 v9, v24, v25
	v_cvt_pk_bf16_f32 v10, v22, v23
	v_cvt_pk_bf16_f32 v11, v16, v17
	v_cvt_pk_bf16_f32 v12, v30, v31
	v_cvt_pk_bf16_f32 v13, v28, v29
	v_cvt_pk_bf16_f32 v14, v18, v19
	v_cvt_pk_bf16_f32 v15, v40, v41
	global_store_dwordx4 v[38:39], v[0:3], off nt
	global_store_dwordx4 v[36:37], v[4:7], off offset:1024 nt
	global_store_dwordx4 v[36:37], v[8:11], off offset:2048 nt
	global_store_dwordx4 v[36:37], v[12:15], off offset:3072 nt
	s_cbranch_scc1 .LBB0_406

.LBB0_452:
	global_load_dwordx2 v[0:1], v[26:27], off offset:-1024 nt
	global_load_dwordx2 v[2:3], v[26:27], off offset:-512 nt
	global_load_dwordx2 v[4:5], v[26:27], off nt
	global_load_dwordx2 v[6:7], v[26:27], off offset:512 nt
	s_add_i32 s17, s82, s26
	s_cmp_lt_i32 s17, 0x8000
	s_cselect_b32 s14, s17, s26
	s_ashr_i32 s12, s26, 31
	s_ashr_i32 s15, s14, 31
	s_lshr_b32 s18, s12, 19
	s_lshl_b64 s[12:13], s[14:15], 12
	s_add_i32 s15, s26, s18
	s_ashr_i32 s15, s15, 13
	s_mul_i32 s18, s15, 0xc00
	s_ashr_i32 s19, s18, 31
	s_lshl_b64 s[18:19], s[18:19], 2
	s_add_u32 s18, s34, s18
	s_addc_u32 s19, s35, s19
	v_lshl_add_u64 v[42:43], v[16:17], 2, s[18:19]
	v_add_co_u32_e32 v8, vcc, s1, v42
	v_lshl_add_u64 v[28:29], s[8:9], 0, v[20:21]
	s_nop 0
	v_addc_co_u32_e32 v9, vcc, 0, v43, vcc
	global_load_dwordx4 v[38:41], v[8:9], off
	global_load_dwordx4 v[30:33], v[24:25], off
	global_load_dwordx4 v[34:37], v[28:29], off nt
	v_lshl_add_u64 v[64:65], v[22:23], 0, s[12:13]
	v_lshl_add_u64 v[42:43], v[42:43], 0, s[10:11]
	s_cmpk_gt_i32 s17, 0x7fff
	s_waitcnt vmcnt(6)
	v_and_b32_e32 v45, 0xffff0000, v0
	s_waitcnt vmcnt(5)
	v_and_b32_e32 v57, 0xffff0000, v2
	v_lshlrev_b32_e32 v44, 16, v0
	v_lshlrev_b32_e32 v56, 16, v2
	v_lshlrev_b32_e32 v58, 16, v3
	v_and_b32_e32 v59, 0xffff0000, v3
	s_waitcnt vmcnt(4)
	v_and_b32_e32 v61, 0xffff0000, v4
	s_waitcnt vmcnt(3)
	v_and_b32_e32 v69, 0xffff0000, v6
	v_mov_b32_e32 v2, v45
	v_mov_b32_e32 v3, v57
	v_lshlrev_b32_e32 v54, 16, v1
	s_waitcnt lgkmcnt(0)
	v_and_b32_e32 v55, 0xffff0000, v1
	v_lshlrev_b32_e32 v60, 16, v4
	v_lshlrev_b32_e32 v68, 16, v6
	v_mov_b32_e32 v0, v44
	v_mov_b32_e32 v1, v56
	v_mov_b32_e32 v10, v61
	v_mov_b32_e32 v11, v69
	v_mul_f32_e32 v2, v2, v2
	v_mul_f32_e32 v3, v3, v3
	v_lshlrev_b32_e32 v62, 16, v5
	v_and_b32_e32 v63, 0xffff0000, v5
	v_lshlrev_b32_e32 v70, 16, v7
	v_mov_b32_e32 v4, v54
	v_mov_b32_e32 v5, v58
	v_mov_b32_e32 v8, v60
	v_mov_b32_e32 v9, v68
	v_mul_f32_e32 v10, v10, v10
	v_mul_f32_e32 v11, v11, v11
	v_fma_f32 v0, v0, v0, v2
	v_fma_f32 v1, v1, v1, v3
	v_and_b32_e32 v71, 0xffff0000, v7
	v_mov_b32_e32 v6, v55
	v_mov_b32_e32 v7, v59
	v_mov_b32_e32 v12, v62
	v_mov_b32_e32 v13, v70
	v_fma_f32 v2, v8, v8, v10
	v_fma_f32 v3, v9, v9, v11
	v_fma_f32 v0, v4, v4, v0
	v_fma_f32 v1, v5, v5, v1
	v_mov_b32_e32 v14, v63
	v_mov_b32_e32 v15, v71
	v_fma_f32 v2, v12, v12, v2
	v_fma_f32 v3, v13, v13, v3
	v_fma_f32 v0, v6, v6, v0
	v_fma_f32 v1, v7, v7, v1
	v_fma_f32 v2, v14, v14, v2
	v_fma_f32 v3, v15, v15, v3
	v_add_f32_e32 v0, v0, v1
	v_add_f32_e32 v0, v0, v2
	v_add_f32_e32 v0, v0, v3
	ds_bpermute_b32 v1, v46, v0
	s_waitcnt vmcnt(2)
	v_mul_f32_e32 v38, v38, v44
	v_mul_f32_e32 v39, v39, v45
	v_mul_f32_e32 v40, v40, v54
	v_mul_f32_e32 v41, v41, v55
	s_waitcnt lgkmcnt(0)
	v_add_f32_e32 v0, v0, v1
	ds_bpermute_b32 v1, v47, v0
	s_waitcnt lgkmcnt(0)
	v_add_f32_e32 v0, v0, v1
	ds_bpermute_b32 v1, v48, v0
	s_waitcnt lgkmcnt(0)
	v_add_f32_e32 v2, v0, v1
	ds_bpermute_b32 v3, v49, v2
	v_mad_i64_i32 v[0:1], s[14:15], s14, v52, v[18:19]
	global_load_dwordx2 v[72:73], v[0:1], off nt
	global_load_dwordx2 v[74:75], v[0:1], off offset:512 nt
	global_load_dwordx2 v[76:77], v[0:1], off offset:1024 nt
	global_load_dwordx2 v[78:79], v[0:1], off offset:1536 nt
	s_waitcnt lgkmcnt(0)
	v_add_f32_e32 v2, v2, v3
	ds_bpermute_b32 v3, v50, v2
	s_waitcnt lgkmcnt(0)
	v_add_f32_e32 v66, v2, v3
	ds_bpermute_b32 v67, v51, v66
	global_load_dwordx4 v[12:15], v[64:65], off nt
	global_load_dwordx4 v[8:11], v[64:65], off offset:1024 nt
	global_load_dwordx4 v[4:7], v[64:65], off offset:2048 nt
	global_load_dwordx4 v[0:3], v[64:65], off offset:3072 nt
	s_waitcnt lgkmcnt(0)
	v_add_f32_e32 v64, v66, v67
	v_fmamk_f32 v64, v64, 0x3a800000, v53
	v_mul_f32_e32 v65, 0x4b800000, v64
	v_cmp_gt_f32_e32 vcc, s16, v64
	s_waitcnt vmcnt(7)
	v_and_b32_e32 v45, 0xffff0000, v73
	v_cndmask_b32_e32 v64, v64, v65, vcc
	v_rsq_f32_e32 v64, v64
	s_nop 0
	v_mul_f32_e32 v44, 0x45800000, v64
	v_cndmask_b32_e32 v80, v64, v44, vcc
	v_mul_f32_e32 v38, v80, v38
	v_mul_f32_e32 v39, v80, v39
	v_mul_f32_e32 v40, v80, v40
	v_mul_f32_e32 v41, v80, v41
	v_fma_f32 v30, v30, v38, v34
	v_fma_f32 v31, v31, v39, v35
	v_fma_f32 v32, v32, v40, v36
	v_fma_f32 v33, v33, v41, v37
	global_store_dwordx4 v[28:29], v[30:33], off nt
	global_load_dwordx4 v[30:33], v[42:43], off offset:1024
	s_nop 0
	global_load_dwordx4 v[34:37], v[28:29], off offset:1024 nt
	global_load_dwordx4 v[38:41], v[24:25], off offset:1024
	v_lshlrev_b32_e32 v44, 16, v73
	s_waitcnt vmcnt(2)
	v_mul_f32_e32 v30, v30, v56
	v_mul_f32_e32 v31, v31, v57
	v_mul_f32_e32 v32, v32, v58
	v_mul_f32_e32 v33, v33, v59
	v_mul_f32_e32 v30, v80, v30
	v_mul_f32_e32 v31, v80, v31
	v_mul_f32_e32 v32, v80, v32
	v_mul_f32_e32 v33, v80, v33
	s_waitcnt vmcnt(0)
	v_fma_f32 v30, v38, v30, v34
	v_fma_f32 v31, v39, v31, v35
	v_fma_f32 v32, v40, v32, v36
	v_fma_f32 v33, v41, v33, v37
	global_store_dwordx4 v[28:29], v[30:33], off offset:1024 nt
	global_load_dwordx4 v[30:33], v[42:43], off offset:2048
	s_nop 0
	global_load_dwordx4 v[34:37], v[28:29], off offset:2048 nt
	global_load_dwordx4 v[38:41], v[24:25], off offset:2048
	s_waitcnt vmcnt(2)
	v_mul_f32_e32 v30, v30, v60
	v_mul_f32_e32 v31, v31, v61
	v_mul_f32_e32 v32, v32, v62
	v_mul_f32_e32 v33, v33, v63
	v_mul_f32_e32 v30, v80, v30
	v_mul_f32_e32 v31, v80, v31
	v_mul_f32_e32 v32, v80, v32
	v_mul_f32_e32 v33, v80, v33
	s_waitcnt vmcnt(0)
	v_fma_f32 v30, v38, v30, v34
	v_fma_f32 v31, v39, v31, v35
	v_fma_f32 v32, v40, v32, v36
	v_fma_f32 v33, v41, v33, v37
	global_store_dwordx4 v[28:29], v[30:33], off offset:2048 nt
	global_load_dwordx4 v[56:59], v[42:43], off offset:3072
	global_load_dwordx4 v[60:63], v[28:29], off offset:3072 nt
	global_load_dwordx4 v[64:67], v[24:25], off offset:3072
	v_lshlrev_b32_e32 v42, 16, v72
	v_and_b32_e32 v43, 0xffff0000, v72
	v_lshlrev_b32_e32 v38, 16, v74
	v_and_b32_e32 v39, 0xffff0000, v74
	v_lshlrev_b32_e32 v40, 16, v75
	v_and_b32_e32 v41, 0xffff0000, v75
	v_lshlrev_b32_e32 v34, 16, v76
	v_and_b32_e32 v35, 0xffff0000, v76
	v_mul_f32_e32 v54, v42, v42
	v_mul_f32_e32 v55, v43, v43
	v_mul_f32_e32 v74, v38, v38
	v_mul_f32_e32 v75, v39, v39
	v_lshlrev_b32_e32 v36, 16, v77
	v_and_b32_e32 v37, 0xffff0000, v77
	v_lshlrev_b32_e32 v30, 16, v78
	v_and_b32_e32 v31, 0xffff0000, v78
	v_lshlrev_b32_e32 v32, 16, v79
	v_and_b32_e32 v33, 0xffff0000, v79
	v_mul_f32_e32 v72, v44, v44
	v_mul_f32_e32 v73, v45, v45
	v_mul_f32_e32 v76, v40, v40
	v_mul_f32_e32 v77, v41, v41
	v_mul_f32_e32 v78, v34, v34
	v_mul_f32_e32 v79, v35, v35
	v_add_f32_e32 v74, v74, v75
	v_add_f32_e32 v54, v54, v55
	v_mul_f32_e32 v82, v36, v36
	v_mul_f32_e32 v83, v37, v37
	v_mul_f32_e32 v84, v30, v30
	v_mul_f32_e32 v85, v31, v31
	v_add_f32_e32 v55, v78, v79
	v_add_f32_e32 v74, v76, v74
	v_add_f32_e32 v54, v72, v54
	v_mul_f32_e32 v86, v32, v32
	v_mul_f32_e32 v87, v33, v33
	v_add_f32_e32 v75, v84, v85
	v_add_f32_e32 v55, v82, v55
	v_add_f32_e32 v74, v77, v74
	v_add_f32_e32 v54, v73, v54
	v_add_f32_e32 v72, v86, v75
	v_add_f32_e32 v55, v83, v55
	v_add_f32_e32 v54, v54, v74
	v_add_f32_e32 v72, v87, v72
	v_add_f32_e32 v54, v54, v55
	v_add_f32_e32 v54, v54, v72
	ds_bpermute_b32 v55, v46, v54
	s_waitcnt lgkmcnt(0)
	v_add_f32_e32 v54, v54, v55
	ds_bpermute_b32 v55, v47, v54
	s_waitcnt lgkmcnt(0)
	v_add_f32_e32 v54, v54, v55
	ds_bpermute_b32 v55, v48, v54
	s_waitcnt lgkmcnt(0)
	v_add_f32_e32 v54, v54, v55
	ds_bpermute_b32 v55, v49, v54
	s_waitcnt lgkmcnt(0)
	v_add_f32_e32 v54, v54, v55
	ds_bpermute_b32 v55, v50, v54
	s_waitcnt lgkmcnt(0)
	v_add_f32_e32 v54, v54, v55
	ds_bpermute_b32 v55, v51, v54
	s_waitcnt vmcnt(2)
	v_mul_f32_e32 v56, v56, v68
	v_mul_f32_e32 v57, v57, v69
	v_mul_f32_e32 v58, v58, v70
	v_mul_f32_e32 v59, v59, v71
	v_mul_f32_e32 v56, v80, v56
	v_mul_f32_e32 v57, v80, v57
	v_mul_f32_e32 v58, v80, v58
	v_mul_f32_e32 v59, v80, v59
	s_waitcnt vmcnt(0)
	v_fma_f32 v56, v64, v56, v60
	v_fma_f32 v57, v65, v57, v61
	v_fma_f32 v58, v66, v58, v62
	v_fma_f32 v59, v67, v59, v63
	global_store_dwordx4 v[28:29], v[56:59], off offset:3072 nt
	s_cbranch_scc1 .LBB0_451
	s_ashr_i32 s12, s17, 31
	s_lshr_b32 s12, s12, 19
	s_add_i32 s17, s17, s12
	s_ashr_i32 s12, s17, 13
	s_mulk_i32 s12, 0xc00
	s_ashr_i32 s13, s12, 31
	s_lshl_b64 s[12:13], s[12:13], 2
	s_add_u32 s12, s34, s12
	s_addc_u32 s13, s35, s13
	v_lshl_add_u64 v[28:29], v[16:17], 2, s[12:13]
	v_add_co_u32_e32 v64, vcc, s1, v28
	s_waitcnt lgkmcnt(0)
	v_add_f32_e32 v54, v54, v55
	v_addc_co_u32_e32 v65, vcc, 0, v29, vcc
	global_load_dwordx4 v[56:59], v[64:65], off
	global_load_dwordx4 v[60:63], v[24:25], off
	v_fmamk_f32 v54, v54, 0x3a800000, v53
	v_mul_f32_e32 v55, 0x4b800000, v54
	v_cmp_gt_f32_e32 vcc, s16, v54
	v_lshl_add_u64 v[28:29], v[28:29], 0, s[10:11]
	s_waitcnt vmcnt(1)
	v_mul_f32_e32 v42, v56, v42
	v_mul_f32_e32 v43, v57, v43
	v_cndmask_b32_e32 v54, v54, v55, vcc
	v_rsq_f32_e32 v64, v54
	v_mul_f32_e32 v44, v58, v44
	v_mul_f32_e32 v45, v59, v45
	v_lshl_add_u64 v[54:55], s[4:5], 0, v[20:21]
	v_mul_f32_e32 v65, 0x45800000, v64
	v_cndmask_b32_e32 v64, v64, v65, vcc
	v_mul_f32_e32 v44, v64, v44
	v_mul_f32_e32 v45, v64, v45
	v_mul_f32_e32 v42, v64, v42
	v_mul_f32_e32 v43, v64, v43
	s_waitcnt vmcnt(0)
	v_fma_f32 v14, v62, v44, v14
	v_fma_f32 v15, v63, v45, v15
	v_fma_f32 v12, v60, v42, v12
	v_fma_f32 v13, v61, v43, v13
	global_store_dwordx4 v[54:55], v[12:15], off nt
	global_load_dwordx4 v[12:15], v[28:29], off offset:1024
	s_nop 0
	global_load_dwordx4 v[42:45], v[24:25], off offset:1024
	s_waitcnt vmcnt(1)
	v_mul_f32_e32 v12, v12, v38
	v_mul_f32_e32 v13, v13, v39
	v_mul_f32_e32 v14, v14, v40
	v_mul_f32_e32 v15, v15, v41
	v_mul_f32_e32 v12, v64, v12
	v_mul_f32_e32 v13, v64, v13
	v_mul_f32_e32 v14, v64, v14
	v_mul_f32_e32 v15, v64, v15
	s_waitcnt vmcnt(0)
	v_fma_f32 v8, v42, v12, v8
	v_fma_f32 v9, v43, v13, v9
	v_fma_f32 v10, v44, v14, v10
	v_fma_f32 v11, v45, v15, v11
	global_store_dwordx4 v[54:55], v[8:11], off offset:1024 nt
	global_load_dwordx4 v[8:11], v[28:29], off offset:2048
	s_nop 0
	global_load_dwordx4 v[12:15], v[24:25], off offset:2048
	s_waitcnt vmcnt(1)
	v_mul_f32_e32 v8, v8, v34
	v_mul_f32_e32 v9, v9, v35
	v_mul_f32_e32 v10, v10, v36
	v_mul_f32_e32 v11, v11, v37
	v_mul_f32_e32 v8, v64, v8
	v_mul_f32_e32 v9, v64, v9
	v_mul_f32_e32 v10, v64, v10
	v_mul_f32_e32 v11, v64, v11
	s_waitcnt vmcnt(0)
	v_fma_f32 v4, v12, v8, v4
	v_fma_f32 v5, v13, v9, v5
	v_fma_f32 v6, v14, v10, v6
	v_fma_f32 v7, v15, v11, v7
	global_store_dwordx4 v[54:55], v[4:7], off offset:2048 nt
	global_load_dwordx4 v[4:7], v[28:29], off offset:3072
	s_nop 0
	global_load_dwordx4 v[8:11], v[24:25], off offset:3072
	s_waitcnt vmcnt(1)
	v_mul_f32_e32 v4, v4, v30
	v_mul_f32_e32 v5, v5, v31
	v_mul_f32_e32 v6, v6, v32
	v_mul_f32_e32 v7, v7, v33
	v_mul_f32_e32 v4, v64, v4
	v_mul_f32_e32 v5, v64, v5
	v_mul_f32_e32 v6, v64, v6
	v_mul_f32_e32 v7, v64, v7
	s_waitcnt vmcnt(0)
	v_fma_f32 v0, v8, v4, v0
	v_fma_f32 v1, v9, v5, v1
	v_fma_f32 v2, v10, v6, v2
	v_fma_f32 v3, v11, v7, v3
	global_store_dwordx4 v[54:55], v[0:3], off offset:3072 nt
	s_branch .LBB0_451
